# K-loops: one static priority raise for waves 4-7 at entry, per-phase priority flips deleted
# baseline (speedup 1.0000x reference)
_ZN2mk8mega_fwdENS_6ParamsE:
	s_load_dword s87, s[0:1], 0x150
	s_mov_b64 s[72:73], s[0:1]
	v_readfirstlane_b32 s54, v0
	s_nop 3
	s_lshr_b32 s33, s54, 6
	s_cmp_ge_u32 s33, 4
	s_cbranch_scc0 .Lprio_done
	s_setprio 1
.Lprio_done:
	s_mov_b32 s44, s2
	v_writelane_b32 v248, s2, 0
	s_waitcnt lgkmcnt(0)
	s_and_b32 s0, s87, 7
	s_cmp_lg_u32 s0, 0
	s_cbranch_scc0 .LBB11_135
	s_movk_i32 s0, 0x80
	v_cmp_gt_u32_e32 vcc, s0, v0
	s_and_saveexec_b64 s[0:1], vcc

.LBB11_221:
	ds_read_b128 v[142:145], v161
	ds_read_b128 v[146:149], v161 offset:1024
	ds_read_b128 v[164:167], v161 offset:2048
	ds_read_b128 v[168:171], v161 offset:3072
	ds_read_b128 v[172:175], v162
	ds_read_b128 v[176:179], v162 offset:1024
	ds_read_b128 v[180:183], v162 offset:2048
	ds_read_b128 v[184:187], v162 offset:3072
	s_add_u32 s22, s20, 0xfffc0080
	s_addc_u32 s23, s21, -1
	s_cmp_eq_u32 s63, 12
	s_cselect_b32 s25, s7, s23
	s_cselect_b32 s24, s26, s22
	s_cselect_b32 s23, s27, s62
	s_cselect_b32 s22, s60, s61
	s_mov_b32 m0, s47
	v_lshl_add_u64 v[196:197], s[20:21], 0, v[138:139]
	ds_read_b128 v[188:191], v163
	ds_read_b128 v[192:195], v163 offset:1024
	ds_read_b128 v[200:203], v163 offset:2048
	ds_read_b128 v[204:207], v163 offset:3072
	ds_read_b128 v[208:211], v163 offset:4096
	ds_read_b128 v[212:215], v163 offset:5120
	ds_read_b128 v[216:219], v163 offset:6144
	ds_read_b128 v[220:223], v163 offset:7168
	global_load_lds_dwordx4 v[196:197], off
	v_lshl_add_u64 v[196:197], s[20:21], 0, v[140:141]
	s_mov_b32 m0, s51
	s_nop 0
	global_load_lds_dwordx4 v[196:197], off
	s_waitcnt vmcnt(8)
	s_waitcnt lgkmcnt(0)
	s_barrier
	v_mfma_f32_16x16x32_bf16 v[124:127], v[142:145], v[188:191], v[124:127]
	v_mfma_f32_16x16x32_bf16 v[120:123], v[164:167], v[188:191], v[120:123]
	v_mfma_f32_16x16x32_bf16 v[108:111], v[142:145], v[200:203], v[108:111]
	v_mfma_f32_16x16x32_bf16 v[104:107], v[164:167], v[200:203], v[104:107]
	v_mfma_f32_16x16x32_bf16 v[92:95], v[142:145], v[208:211], v[92:95]
	v_mfma_f32_16x16x32_bf16 v[88:91], v[164:167], v[208:211], v[88:91]
	v_mfma_f32_16x16x32_bf16 v[76:79], v[142:145], v[216:219], v[76:79]
	v_mfma_f32_16x16x32_bf16 v[72:75], v[164:167], v[216:219], v[72:75]
	v_mfma_f32_16x16x32_bf16 v[124:127], v[146:149], v[192:195], v[124:127]
	v_mfma_f32_16x16x32_bf16 v[120:123], v[168:171], v[192:195], v[120:123]
	v_mfma_f32_16x16x32_bf16 v[108:111], v[146:149], v[204:207], v[108:111]
	v_mfma_f32_16x16x32_bf16 v[104:107], v[168:171], v[204:207], v[104:107]
	v_mfma_f32_16x16x32_bf16 v[92:95], v[146:149], v[212:215], v[92:95]
	v_mfma_f32_16x16x32_bf16 v[88:91], v[168:171], v[212:215], v[88:91]
	v_mfma_f32_16x16x32_bf16 v[76:79], v[146:149], v[220:223], v[76:79]
	v_mfma_f32_16x16x32_bf16 v[72:75], v[168:171], v[220:223], v[72:75]
	v_mfma_f32_16x16x32_bf16 v[116:119], v[172:175], v[188:191], v[116:119]
	v_mfma_f32_16x16x32_bf16 v[112:115], v[180:183], v[188:191], v[112:115]
	v_mfma_f32_16x16x32_bf16 v[100:103], v[172:175], v[200:203], v[100:103]
	v_mfma_f32_16x16x32_bf16 v[96:99], v[180:183], v[200:203], v[96:99]
	v_mfma_f32_16x16x32_bf16 v[84:87], v[172:175], v[208:211], v[84:87]
	v_mfma_f32_16x16x32_bf16 v[80:83], v[180:183], v[208:211], v[80:83]
	v_mfma_f32_16x16x32_bf16 v[68:71], v[172:175], v[216:219], v[68:71]
	v_mfma_f32_16x16x32_bf16 v[64:67], v[180:183], v[216:219], v[64:67]
	v_mfma_f32_16x16x32_bf16 v[116:119], v[176:179], v[192:195], v[116:119]
	v_mfma_f32_16x16x32_bf16 v[112:115], v[184:187], v[192:195], v[112:115]
	v_mfma_f32_16x16x32_bf16 v[100:103], v[176:179], v[204:207], v[100:103]
	v_mfma_f32_16x16x32_bf16 v[96:99], v[184:187], v[204:207], v[96:99]
	v_mfma_f32_16x16x32_bf16 v[84:87], v[176:179], v[212:215], v[84:87]
	v_mfma_f32_16x16x32_bf16 v[80:83], v[184:187], v[212:215], v[80:83]
	v_mfma_f32_16x16x32_bf16 v[68:71], v[176:179], v[220:223], v[68:71]
	v_mfma_f32_16x16x32_bf16 v[64:67], v[184:187], v[220:223], v[64:67]
	s_barrier
	s_mov_b32 m0, s56
	v_lshl_add_u64 v[196:197], s[22:23], 0, v[132:133]
	ds_read_b128 v[188:191], v163 offset:16384
	ds_read_b128 v[192:195], v163 offset:17408
	ds_read_b128 v[200:203], v163 offset:18432
	ds_read_b128 v[204:207], v163 offset:19456
	ds_read_b128 v[208:211], v163 offset:20480
	ds_read_b128 v[212:215], v163 offset:21504
	ds_read_b128 v[216:219], v163 offset:22528
	ds_read_b128 v[220:223], v163 offset:23552
	global_load_lds_dwordx4 v[196:197], off
	s_add_i32 m0, s56, 0x2000
	s_add_u32 s64, s22, 0x40000
	v_lshl_add_u64 v[224:225], s[22:23], 0, v[128:129]
	s_addc_u32 s65, s23, 0
	s_add_i32 s66, s45, s28
	global_load_lds_dwordx4 v[224:225], off
	v_lshl_add_u64 v[226:227], s[64:65], 0, v[132:133]
	s_mov_b32 m0, s66
	v_lshl_add_u64 v[228:229], s[24:25], 0, v[130:131]
	global_load_lds_dwordx4 v[226:227], off
	v_lshl_add_u64 v[226:227], s[64:65], 0, v[128:129]
	s_add_i32 m0, s66, 0x2000
	s_nop 0
	global_load_lds_dwordx4 v[226:227], off
	v_lshl_add_u64 v[226:227], s[24:25], 0, v[134:135]
	s_mov_b32 m0, s38
	s_nop 0
	global_load_lds_dwordx4 v[226:227], off
	s_mov_b32 m0, s39
	s_nop 0
	global_load_lds_dwordx4 v[228:229], off
	s_waitcnt vmcnt(8)
	s_waitcnt lgkmcnt(0)
	s_barrier
	v_mfma_f32_16x16x32_bf16 v[60:63], v[142:145], v[188:191], v[60:63]
	v_mfma_f32_16x16x32_bf16 v[56:59], v[164:167], v[188:191], v[56:59]
	v_mfma_f32_16x16x32_bf16 v[44:47], v[142:145], v[200:203], v[44:47]
	v_mfma_f32_16x16x32_bf16 v[40:43], v[164:167], v[200:203], v[40:43]
	v_mfma_f32_16x16x32_bf16 v[28:31], v[142:145], v[208:211], v[28:31]
	v_mfma_f32_16x16x32_bf16 v[24:27], v[164:167], v[208:211], v[24:27]
	v_mfma_f32_16x16x32_bf16 v[12:15], v[142:145], v[216:219], v[12:15]
	v_mfma_f32_16x16x32_bf16 v[8:11], v[164:167], v[216:219], v[8:11]
	v_mfma_f32_16x16x32_bf16 v[60:63], v[146:149], v[192:195], v[60:63]
	v_mfma_f32_16x16x32_bf16 v[56:59], v[168:171], v[192:195], v[56:59]
	v_mfma_f32_16x16x32_bf16 v[44:47], v[146:149], v[204:207], v[44:47]
	v_mfma_f32_16x16x32_bf16 v[40:43], v[168:171], v[204:207], v[40:43]
	v_mfma_f32_16x16x32_bf16 v[28:31], v[146:149], v[212:215], v[28:31]
	v_mfma_f32_16x16x32_bf16 v[24:27], v[168:171], v[212:215], v[24:27]
	v_mfma_f32_16x16x32_bf16 v[12:15], v[146:149], v[220:223], v[12:15]
	v_mfma_f32_16x16x32_bf16 v[8:11], v[168:171], v[220:223], v[8:11]
	v_mfma_f32_16x16x32_bf16 v[52:55], v[172:175], v[188:191], v[52:55]
	v_mfma_f32_16x16x32_bf16 v[48:51], v[180:183], v[188:191], v[48:51]
	v_mfma_f32_16x16x32_bf16 v[36:39], v[172:175], v[200:203], v[36:39]
	v_mfma_f32_16x16x32_bf16 v[32:35], v[180:183], v[200:203], v[32:35]
	v_mfma_f32_16x16x32_bf16 v[20:23], v[172:175], v[208:211], v[20:23]
	v_mfma_f32_16x16x32_bf16 v[16:19], v[180:183], v[208:211], v[16:19]
	v_mfma_f32_16x16x32_bf16 v[4:7], v[172:175], v[216:219], v[4:7]
	v_mfma_f32_16x16x32_bf16 v[0:3], v[180:183], v[216:219], v[0:3]
	v_mfma_f32_16x16x32_bf16 v[52:55], v[176:179], v[192:195], v[52:55]
	v_mfma_f32_16x16x32_bf16 v[48:51], v[184:187], v[192:195], v[48:51]
	v_mfma_f32_16x16x32_bf16 v[36:39], v[176:179], v[204:207], v[36:39]
	v_mfma_f32_16x16x32_bf16 v[32:35], v[184:187], v[204:207], v[32:35]
	v_mfma_f32_16x16x32_bf16 v[20:23], v[176:179], v[212:215], v[20:23]
	v_mfma_f32_16x16x32_bf16 v[16:19], v[184:187], v[212:215], v[16:19]
	v_mfma_f32_16x16x32_bf16 v[4:7], v[176:179], v[220:223], v[4:7]
	v_mfma_f32_16x16x32_bf16 v[0:3], v[184:187], v[220:223], v[0:3]
	s_barrier
	s_add_i32 s64, 0, 0x18000
	v_add_u32_e32 v136, s64, v159
	s_add_i32 s65, 0, 0x1c000
	ds_read_b128 v[142:145], v136
	ds_read_b128 v[146:149], v136 offset:1024
	ds_read_b128 v[164:167], v136 offset:2048
	ds_read_b128 v[168:171], v136 offset:3072
	v_add_u32_e32 v136, s65, v159
	ds_read_b128 v[172:175], v136
	ds_read_b128 v[176:179], v136 offset:1024
	ds_read_b128 v[180:183], v136 offset:2048
	ds_read_b128 v[184:187], v136 offset:3072
	s_add_u32 s24, s24, 0x40000
	s_addc_u32 s25, s25, 0
	s_mov_b32 m0, s40
	v_lshl_add_u64 v[230:231], s[24:25], 0, v[134:135]
	ds_read_b128 v[188:191], v163 offset:32768
	ds_read_b128 v[192:195], v163 offset:33792
	ds_read_b128 v[200:203], v163 offset:34816
	ds_read_b128 v[204:207], v163 offset:35840
	ds_read_b128 v[208:211], v163 offset:36864
	ds_read_b128 v[212:215], v163 offset:37888
	ds_read_b128 v[216:219], v163 offset:38912
	ds_read_b128 v[220:223], v163 offset:39936
	global_load_lds_dwordx4 v[230:231], off
	v_lshl_add_u64 v[230:231], s[24:25], 0, v[130:131]
	s_mov_b32 m0, s41
	s_nop 0
	global_load_lds_dwordx4 v[230:231], off
	s_waitcnt vmcnt(8)
	s_waitcnt lgkmcnt(0)
	s_barrier
	v_mfma_f32_16x16x32_bf16 v[124:127], v[142:145], v[188:191], v[124:127]
	v_mfma_f32_16x16x32_bf16 v[120:123], v[164:167], v[188:191], v[120:123]
	v_mfma_f32_16x16x32_bf16 v[108:111], v[142:145], v[200:203], v[108:111]
	v_mfma_f32_16x16x32_bf16 v[104:107], v[164:167], v[200:203], v[104:107]
	v_mfma_f32_16x16x32_bf16 v[92:95], v[142:145], v[208:211], v[92:95]
	v_mfma_f32_16x16x32_bf16 v[88:91], v[164:167], v[208:211], v[88:91]
	v_mfma_f32_16x16x32_bf16 v[76:79], v[142:145], v[216:219], v[76:79]
	v_mfma_f32_16x16x32_bf16 v[72:75], v[164:167], v[216:219], v[72:75]
	v_mfma_f32_16x16x32_bf16 v[124:127], v[146:149], v[192:195], v[124:127]
	v_mfma_f32_16x16x32_bf16 v[120:123], v[168:171], v[192:195], v[120:123]
	v_mfma_f32_16x16x32_bf16 v[108:111], v[146:149], v[204:207], v[108:111]
	v_mfma_f32_16x16x32_bf16 v[104:107], v[168:171], v[204:207], v[104:107]
	v_mfma_f32_16x16x32_bf16 v[92:95], v[146:149], v[212:215], v[92:95]
	v_mfma_f32_16x16x32_bf16 v[88:91], v[168:171], v[212:215], v[88:91]
	v_mfma_f32_16x16x32_bf16 v[76:79], v[146:149], v[220:223], v[76:79]
	v_mfma_f32_16x16x32_bf16 v[72:75], v[168:171], v[220:223], v[72:75]
	v_mfma_f32_16x16x32_bf16 v[116:119], v[172:175], v[188:191], v[116:119]
	v_mfma_f32_16x16x32_bf16 v[112:115], v[180:183], v[188:191], v[112:115]
	v_mfma_f32_16x16x32_bf16 v[100:103], v[172:175], v[200:203], v[100:103]
	v_mfma_f32_16x16x32_bf16 v[96:99], v[180:183], v[200:203], v[96:99]
	v_mfma_f32_16x16x32_bf16 v[84:87], v[172:175], v[208:211], v[84:87]
	v_mfma_f32_16x16x32_bf16 v[80:83], v[180:183], v[208:211], v[80:83]
	v_mfma_f32_16x16x32_bf16 v[68:71], v[172:175], v[216:219], v[68:71]
	v_mfma_f32_16x16x32_bf16 v[64:67], v[180:183], v[216:219], v[64:67]
	v_mfma_f32_16x16x32_bf16 v[116:119], v[176:179], v[192:195], v[116:119]
	v_mfma_f32_16x16x32_bf16 v[112:115], v[184:187], v[192:195], v[112:115]
	v_mfma_f32_16x16x32_bf16 v[100:103], v[176:179], v[204:207], v[100:103]
	v_mfma_f32_16x16x32_bf16 v[96:99], v[184:187], v[204:207], v[96:99]
	v_mfma_f32_16x16x32_bf16 v[84:87], v[176:179], v[212:215], v[84:87]
	v_mfma_f32_16x16x32_bf16 v[80:83], v[184:187], v[212:215], v[80:83]
	v_mfma_f32_16x16x32_bf16 v[68:71], v[176:179], v[220:223], v[68:71]
	v_mfma_f32_16x16x32_bf16 v[64:67], v[184:187], v[220:223], v[64:67]
	s_barrier
	s_add_i32 s24, s64, s28
	v_lshl_add_u64 v[196:197], v[196:197], 0, s[8:9]
	s_mov_b32 m0, s24
	ds_read_b128 v[188:191], v163 offset:49152
	ds_read_b128 v[192:195], v163 offset:50176
	ds_read_b128 v[200:203], v163 offset:51200
	ds_read_b128 v[204:207], v163 offset:52224
	ds_read_b128 v[208:211], v163 offset:53248
	ds_read_b128 v[212:215], v163 offset:54272
	ds_read_b128 v[216:219], v163 offset:55296
	ds_read_b128 v[220:223], v163 offset:56320
	global_load_lds_dwordx4 v[196:197], off
	s_add_i32 m0, s24, 0x2000
	s_add_u32 s22, s22, 0x40080
	v_lshl_add_u64 v[196:197], v[224:225], 0, s[8:9]
	s_addc_u32 s23, s23, 0
	s_add_i32 s24, s65, s28
	global_load_lds_dwordx4 v[196:197], off
	v_lshl_add_u64 v[196:197], s[22:23], 0, v[132:133]
	s_mov_b32 m0, s24
	s_nop 0
	global_load_lds_dwordx4 v[196:197], off
	v_lshl_add_u64 v[196:197], s[22:23], 0, v[128:129]
	s_add_i32 m0, s24, 0x2000
	s_nop 0
	global_load_lds_dwordx4 v[196:197], off
	v_lshl_add_u64 v[196:197], v[226:227], 0, s[8:9]
	s_mov_b32 m0, s43
	s_nop 0
	global_load_lds_dwordx4 v[196:197], off
	v_lshl_add_u64 v[196:197], v[228:229], 0, s[8:9]
	s_mov_b32 m0, s44
	s_nop 0
	global_load_lds_dwordx4 v[196:197], off
	s_waitcnt vmcnt(8)
	s_waitcnt lgkmcnt(0)
	s_barrier
	v_mfma_f32_16x16x32_bf16 v[60:63], v[142:145], v[188:191], v[60:63]
	v_mfma_f32_16x16x32_bf16 v[56:59], v[164:167], v[188:191], v[56:59]
	v_mfma_f32_16x16x32_bf16 v[44:47], v[142:145], v[200:203], v[44:47]
	v_mfma_f32_16x16x32_bf16 v[40:43], v[164:167], v[200:203], v[40:43]
	v_mfma_f32_16x16x32_bf16 v[28:31], v[142:145], v[208:211], v[28:31]
	v_mfma_f32_16x16x32_bf16 v[24:27], v[164:167], v[208:211], v[24:27]
	v_mfma_f32_16x16x32_bf16 v[12:15], v[142:145], v[216:219], v[12:15]
	v_mfma_f32_16x16x32_bf16 v[8:11], v[164:167], v[216:219], v[8:11]
	v_mfma_f32_16x16x32_bf16 v[60:63], v[146:149], v[192:195], v[60:63]
	v_mfma_f32_16x16x32_bf16 v[56:59], v[168:171], v[192:195], v[56:59]
	v_mfma_f32_16x16x32_bf16 v[44:47], v[146:149], v[204:207], v[44:47]
	v_mfma_f32_16x16x32_bf16 v[40:43], v[168:171], v[204:207], v[40:43]
	v_mfma_f32_16x16x32_bf16 v[28:31], v[146:149], v[212:215], v[28:31]
	v_mfma_f32_16x16x32_bf16 v[24:27], v[168:171], v[212:215], v[24:27]
	v_mfma_f32_16x16x32_bf16 v[12:15], v[146:149], v[220:223], v[12:15]
	v_mfma_f32_16x16x32_bf16 v[8:11], v[168:171], v[220:223], v[8:11]
	v_mfma_f32_16x16x32_bf16 v[52:55], v[172:175], v[188:191], v[52:55]
	v_mfma_f32_16x16x32_bf16 v[48:51], v[180:183], v[188:191], v[48:51]
	v_mfma_f32_16x16x32_bf16 v[36:39], v[172:175], v[200:203], v[36:39]
	v_mfma_f32_16x16x32_bf16 v[32:35], v[180:183], v[200:203], v[32:35]
	v_mfma_f32_16x16x32_bf16 v[20:23], v[172:175], v[208:211], v[20:23]
	v_mfma_f32_16x16x32_bf16 v[16:19], v[180:183], v[208:211], v[16:19]
	v_mfma_f32_16x16x32_bf16 v[4:7], v[172:175], v[216:219], v[4:7]
	v_mfma_f32_16x16x32_bf16 v[0:3], v[180:183], v[216:219], v[0:3]
	v_mfma_f32_16x16x32_bf16 v[52:55], v[176:179], v[192:195], v[52:55]
	v_mfma_f32_16x16x32_bf16 v[48:51], v[184:187], v[192:195], v[48:51]
	v_mfma_f32_16x16x32_bf16 v[36:39], v[176:179], v[204:207], v[36:39]
	v_mfma_f32_16x16x32_bf16 v[32:35], v[184:187], v[204:207], v[32:35]
	v_mfma_f32_16x16x32_bf16 v[20:23], v[176:179], v[212:215], v[20:23]
	v_mfma_f32_16x16x32_bf16 v[16:19], v[184:187], v[212:215], v[16:19]
	v_mfma_f32_16x16x32_bf16 v[4:7], v[176:179], v[220:223], v[4:7]
	v_mfma_f32_16x16x32_bf16 v[0:3], v[184:187], v[220:223], v[0:3]
	s_barrier
	s_add_i32 s63, s63, 2
	s_add_u32 s20, s20, 0x100
	s_addc_u32 s21, s21, 0
	s_add_u32 s61, s61, 0x100
	s_addc_u32 s62, s62, 0
	s_cmp_gt_u32 s63, 13
	s_cbranch_scc0 .LBB11_221
	s_and_b64 vcc, exec, s[10:11]
	s_cbranch_vccz .LBB11_224
	s_barrier

.LBB11_926:
	s_add_u32 s0, s22, 0xfffc0080
	s_addc_u32 s1, s23, -1
	s_add_i32 s48, 0, 0x10000
	s_cmp_eq_u32 s57, 12
	s_cselect_b32 s27, s8, s1
	s_cselect_b32 s26, s9, s0
	s_cselect_b32 s25, s40, s56
	s_cselect_b32 s24, s46, s47
	s_add_i32 s49, 0, 0x14000
	v_add_u32_e32 v152, s48, v159
	v_add_u32_e32 v156, s49, v159
	ds_read_b128 v[130:133], v152
	ds_read_b128 v[134:137], v152 offset:1024
	ds_read_b128 v[148:151], v152 offset:2048
	ds_read_b128 v[152:155], v152 offset:3072
	ds_read_b128 v[162:165], v156
	ds_read_b128 v[166:169], v156 offset:1024
	ds_read_b128 v[170:173], v156 offset:2048
	ds_read_b128 v[174:177], v156 offset:3072
	v_lshl_add_u64 v[156:157], s[22:23], 0, v[144:145]
	s_add_i32 m0, s35, 0xc000
	ds_read_b128 v[178:181], v161
	ds_read_b128 v[190:193], v161 offset:1024
	ds_read_b128 v[194:197], v161 offset:2048
	ds_read_b128 v[214:217], v161 offset:3072
	ds_read_b128 v[218:221], v161 offset:4096
	ds_read_b128 v[222:225], v161 offset:5120
	ds_read_b128 v[226:229], v161 offset:6144
	ds_read_b128 v[230:233], v161 offset:7168
	global_load_lds_dwordx4 v[156:157], off
	v_lshl_add_u64 v[156:157], s[22:23], 0, v[146:147]
	s_add_i32 m0, s35, 0xe000
	s_nop 0
	global_load_lds_dwordx4 v[156:157], off
	s_waitcnt vmcnt(8)
	s_waitcnt lgkmcnt(0)
	s_barrier
	v_mfma_f32_16x16x32_bf16 v[126:129], v[130:133], v[178:181], v[126:129]
	v_mfma_f32_16x16x32_bf16 v[114:117], v[148:151], v[178:181], v[114:117]
	v_mfma_f32_16x16x32_bf16 v[110:113], v[130:133], v[194:197], v[110:113]
	v_mfma_f32_16x16x32_bf16 v[98:101], v[148:151], v[194:197], v[98:101]
	v_mfma_f32_16x16x32_bf16 v[94:97], v[130:133], v[218:221], v[94:97]
	v_mfma_f32_16x16x32_bf16 v[82:85], v[148:151], v[218:221], v[82:85]
	v_mfma_f32_16x16x32_bf16 v[78:81], v[130:133], v[226:229], v[78:81]
	v_mfma_f32_16x16x32_bf16 v[66:69], v[148:151], v[226:229], v[66:69]
	v_mfma_f32_16x16x32_bf16 v[126:129], v[134:137], v[190:193], v[126:129]
	v_mfma_f32_16x16x32_bf16 v[114:117], v[152:155], v[190:193], v[114:117]
	v_mfma_f32_16x16x32_bf16 v[110:113], v[134:137], v[214:217], v[110:113]
	v_mfma_f32_16x16x32_bf16 v[98:101], v[152:155], v[214:217], v[98:101]
	v_mfma_f32_16x16x32_bf16 v[94:97], v[134:137], v[222:225], v[94:97]
	v_mfma_f32_16x16x32_bf16 v[82:85], v[152:155], v[222:225], v[82:85]
	v_mfma_f32_16x16x32_bf16 v[78:81], v[134:137], v[230:233], v[78:81]
	v_mfma_f32_16x16x32_bf16 v[66:69], v[152:155], v[230:233], v[66:69]
	v_mfma_f32_16x16x32_bf16 v[122:125], v[162:165], v[178:181], v[122:125]
	v_mfma_f32_16x16x32_bf16 v[118:121], v[170:173], v[178:181], v[118:121]
	v_mfma_f32_16x16x32_bf16 v[106:109], v[162:165], v[194:197], v[106:109]
	v_mfma_f32_16x16x32_bf16 v[102:105], v[170:173], v[194:197], v[102:105]
	v_mfma_f32_16x16x32_bf16 v[90:93], v[162:165], v[218:221], v[90:93]
	v_mfma_f32_16x16x32_bf16 v[86:89], v[170:173], v[218:221], v[86:89]
	v_mfma_f32_16x16x32_bf16 v[74:77], v[162:165], v[226:229], v[74:77]
	v_mfma_f32_16x16x32_bf16 v[70:73], v[170:173], v[226:229], v[70:73]
	v_mfma_f32_16x16x32_bf16 v[122:125], v[166:169], v[190:193], v[122:125]
	v_mfma_f32_16x16x32_bf16 v[118:121], v[174:177], v[190:193], v[118:121]
	v_mfma_f32_16x16x32_bf16 v[106:109], v[166:169], v[214:217], v[106:109]
	v_mfma_f32_16x16x32_bf16 v[102:105], v[174:177], v[214:217], v[102:105]
	v_mfma_f32_16x16x32_bf16 v[90:93], v[166:169], v[222:225], v[90:93]
	v_mfma_f32_16x16x32_bf16 v[86:89], v[174:177], v[222:225], v[86:89]
	v_mfma_f32_16x16x32_bf16 v[74:77], v[166:169], v[230:233], v[74:77]
	v_mfma_f32_16x16x32_bf16 v[70:73], v[174:177], v[230:233], v[70:73]
	s_barrier
	s_add_i32 s0, s48, s34
	v_lshl_add_u64 v[156:157], s[24:25], 0, v[0:1]
	s_mov_b32 m0, s0
	ds_read_b128 v[178:181], v161 offset:16384
	ds_read_b128 v[190:193], v161 offset:17408
	ds_read_b128 v[194:197], v161 offset:18432
	ds_read_b128 v[214:217], v161 offset:19456
	ds_read_b128 v[218:221], v161 offset:20480
	ds_read_b128 v[222:225], v161 offset:21504
	ds_read_b128 v[226:229], v161 offset:22528
	ds_read_b128 v[230:233], v161 offset:23552
	global_load_lds_dwordx4 v[156:157], off
	s_add_i32 m0, s0, 0x2000
	s_add_u32 s0, s24, 0x40000
	v_lshl_add_u64 v[182:183], s[24:25], 0, v[138:139]
	s_addc_u32 s1, s25, 0
	s_add_i32 s48, s49, s34
	global_load_lds_dwordx4 v[182:183], off
	v_lshl_add_u64 v[234:235], s[0:1], 0, v[0:1]
	s_mov_b32 m0, s48
	v_lshl_add_u64 v[236:237], s[26:27], 0, v[140:141]
	global_load_lds_dwordx4 v[234:235], off
	v_lshl_add_u64 v[234:235], s[0:1], 0, v[138:139]
	s_add_i32 m0, s48, 0x2000
	s_nop 0
	global_load_lds_dwordx4 v[234:235], off
	v_lshl_add_u64 v[234:235], s[26:27], 0, v[142:143]
	s_mov_b32 m0, s35
	s_nop 0
	global_load_lds_dwordx4 v[234:235], off
	s_mov_b32 m0, s36
	s_nop 0
	global_load_lds_dwordx4 v[236:237], off
	s_waitcnt vmcnt(8)
	s_waitcnt lgkmcnt(0)
	s_barrier
	v_mfma_f32_16x16x32_bf16 v[62:65], v[130:133], v[178:181], v[62:65]
	v_mfma_f32_16x16x32_bf16 v[50:53], v[148:151], v[178:181], v[50:53]
	v_mfma_f32_16x16x32_bf16 v[46:49], v[130:133], v[194:197], v[46:49]
	v_mfma_f32_16x16x32_bf16 v[38:41], v[148:151], v[194:197], v[38:41]
	v_mfma_f32_16x16x32_bf16 v[30:33], v[130:133], v[218:221], v[30:33]
	v_mfma_f32_16x16x32_bf16 v[22:25], v[148:151], v[218:221], v[22:25]
	v_mfma_f32_16x16x32_bf16 v[14:17], v[130:133], v[226:229], v[14:17]
	v_mfma_f32_16x16x32_bf16 v[6:9], v[148:151], v[226:229], v[6:9]
	v_mfma_f32_16x16x32_bf16 v[62:65], v[134:137], v[190:193], v[62:65]
	v_mfma_f32_16x16x32_bf16 v[50:53], v[152:155], v[190:193], v[50:53]
	v_mfma_f32_16x16x32_bf16 v[46:49], v[134:137], v[214:217], v[46:49]
	v_mfma_f32_16x16x32_bf16 v[38:41], v[152:155], v[214:217], v[38:41]
	v_mfma_f32_16x16x32_bf16 v[30:33], v[134:137], v[222:225], v[30:33]
	v_mfma_f32_16x16x32_bf16 v[22:25], v[152:155], v[222:225], v[22:25]
	v_mfma_f32_16x16x32_bf16 v[14:17], v[134:137], v[230:233], v[14:17]
	v_mfma_f32_16x16x32_bf16 v[6:9], v[152:155], v[230:233], v[6:9]
	v_mfma_f32_16x16x32_bf16 v[58:61], v[162:165], v[178:181], v[58:61]
	v_mfma_f32_16x16x32_bf16 v[54:57], v[170:173], v[178:181], v[54:57]
	v_mfma_f32_16x16x32_bf16 v[42:45], v[162:165], v[194:197], v[42:45]
	v_mfma_f32_16x16x32_bf16 v[34:37], v[170:173], v[194:197], v[34:37]
	v_mfma_f32_16x16x32_bf16 v[26:29], v[162:165], v[218:221], v[26:29]
	v_mfma_f32_16x16x32_bf16 v[18:21], v[170:173], v[218:221], v[18:21]
	v_mfma_f32_16x16x32_bf16 v[10:13], v[162:165], v[226:229], v[10:13]
	v_mfma_f32_16x16x32_bf16 v[2:5], v[170:173], v[226:229], v[2:5]
	v_mfma_f32_16x16x32_bf16 v[58:61], v[166:169], v[190:193], v[58:61]
	v_mfma_f32_16x16x32_bf16 v[54:57], v[174:177], v[190:193], v[54:57]
	v_mfma_f32_16x16x32_bf16 v[42:45], v[166:169], v[214:217], v[42:45]
	v_mfma_f32_16x16x32_bf16 v[34:37], v[174:177], v[214:217], v[34:37]
	v_mfma_f32_16x16x32_bf16 v[26:29], v[166:169], v[222:225], v[26:29]
	v_mfma_f32_16x16x32_bf16 v[18:21], v[174:177], v[222:225], v[18:21]
	v_mfma_f32_16x16x32_bf16 v[10:13], v[166:169], v[230:233], v[10:13]
	v_mfma_f32_16x16x32_bf16 v[2:5], v[174:177], v[230:233], v[2:5]
	s_barrier
	s_add_i32 s48, 0, 0x18000
	s_add_i32 s49, 0, 0x1c000
	v_add_u32_e32 v152, s48, v159
	v_add_u32_e32 v174, s49, v159
	ds_read_b128 v[130:133], v152
	ds_read_b128 v[134:137], v152 offset:1024
	ds_read_b128 v[148:151], v152 offset:2048
	ds_read_b128 v[152:155], v152 offset:3072
	ds_read_b128 v[162:165], v174
	ds_read_b128 v[166:169], v174 offset:1024
	ds_read_b128 v[170:173], v174 offset:2048
	ds_read_b128 v[174:177], v174 offset:3072
	s_add_u32 s0, s26, 0x40000
	s_addc_u32 s1, s27, 0
	s_mov_b32 m0, s37
	v_lshl_add_u64 v[238:239], s[0:1], 0, v[142:143]
	ds_read_b128 v[178:181], v161 offset:32768
	ds_read_b128 v[190:193], v161 offset:33792
	ds_read_b128 v[194:197], v161 offset:34816
	ds_read_b128 v[214:217], v161 offset:35840
	ds_read_b128 v[218:221], v161 offset:36864
	ds_read_b128 v[222:225], v161 offset:37888
	ds_read_b128 v[226:229], v161 offset:38912
	ds_read_b128 v[230:233], v161 offset:39936
	global_load_lds_dwordx4 v[238:239], off
	v_lshl_add_u64 v[238:239], s[0:1], 0, v[140:141]
	s_mov_b32 m0, s38
	s_nop 0
	global_load_lds_dwordx4 v[238:239], off
	s_waitcnt vmcnt(8)
	s_waitcnt lgkmcnt(0)
	s_barrier
	v_mfma_f32_16x16x32_bf16 v[126:129], v[130:133], v[178:181], v[126:129]
	v_mfma_f32_16x16x32_bf16 v[114:117], v[148:151], v[178:181], v[114:117]
	v_mfma_f32_16x16x32_bf16 v[110:113], v[130:133], v[194:197], v[110:113]
	v_mfma_f32_16x16x32_bf16 v[98:101], v[148:151], v[194:197], v[98:101]
	v_mfma_f32_16x16x32_bf16 v[94:97], v[130:133], v[218:221], v[94:97]
	v_mfma_f32_16x16x32_bf16 v[82:85], v[148:151], v[218:221], v[82:85]
	v_mfma_f32_16x16x32_bf16 v[78:81], v[130:133], v[226:229], v[78:81]
	v_mfma_f32_16x16x32_bf16 v[66:69], v[148:151], v[226:229], v[66:69]
	v_mfma_f32_16x16x32_bf16 v[126:129], v[134:137], v[190:193], v[126:129]
	v_mfma_f32_16x16x32_bf16 v[114:117], v[152:155], v[190:193], v[114:117]
	v_mfma_f32_16x16x32_bf16 v[110:113], v[134:137], v[214:217], v[110:113]
	v_mfma_f32_16x16x32_bf16 v[98:101], v[152:155], v[214:217], v[98:101]
	v_mfma_f32_16x16x32_bf16 v[94:97], v[134:137], v[222:225], v[94:97]
	v_mfma_f32_16x16x32_bf16 v[82:85], v[152:155], v[222:225], v[82:85]
	v_mfma_f32_16x16x32_bf16 v[78:81], v[134:137], v[230:233], v[78:81]
	v_mfma_f32_16x16x32_bf16 v[66:69], v[152:155], v[230:233], v[66:69]
	v_mfma_f32_16x16x32_bf16 v[122:125], v[162:165], v[178:181], v[122:125]
	v_mfma_f32_16x16x32_bf16 v[118:121], v[170:173], v[178:181], v[118:121]
	v_mfma_f32_16x16x32_bf16 v[106:109], v[162:165], v[194:197], v[106:109]
	v_mfma_f32_16x16x32_bf16 v[102:105], v[170:173], v[194:197], v[102:105]
	v_mfma_f32_16x16x32_bf16 v[90:93], v[162:165], v[218:221], v[90:93]
	v_mfma_f32_16x16x32_bf16 v[86:89], v[170:173], v[218:221], v[86:89]
	v_mfma_f32_16x16x32_bf16 v[74:77], v[162:165], v[226:229], v[74:77]
	v_mfma_f32_16x16x32_bf16 v[70:73], v[170:173], v[226:229], v[70:73]
	v_mfma_f32_16x16x32_bf16 v[122:125], v[166:169], v[190:193], v[122:125]
	v_mfma_f32_16x16x32_bf16 v[118:121], v[174:177], v[190:193], v[118:121]
	v_mfma_f32_16x16x32_bf16 v[106:109], v[166:169], v[214:217], v[106:109]
	v_mfma_f32_16x16x32_bf16 v[102:105], v[174:177], v[214:217], v[102:105]
	v_mfma_f32_16x16x32_bf16 v[90:93], v[166:169], v[222:225], v[90:93]
	v_mfma_f32_16x16x32_bf16 v[86:89], v[174:177], v[222:225], v[86:89]
	v_mfma_f32_16x16x32_bf16 v[74:77], v[166:169], v[230:233], v[74:77]
	v_mfma_f32_16x16x32_bf16 v[70:73], v[174:177], v[230:233], v[70:73]
	s_barrier
	s_add_i32 s0, s48, s34
	v_lshl_add_u64 v[156:157], v[156:157], 0, s[96:97]
	s_mov_b32 m0, s0
	ds_read_b128 v[178:181], v161 offset:49152
	ds_read_b128 v[190:193], v161 offset:50176
	ds_read_b128 v[194:197], v161 offset:51200
	ds_read_b128 v[214:217], v161 offset:52224
	ds_read_b128 v[218:221], v161 offset:53248
	ds_read_b128 v[222:225], v161 offset:54272
	ds_read_b128 v[226:229], v161 offset:55296
	ds_read_b128 v[230:233], v161 offset:56320
	global_load_lds_dwordx4 v[156:157], off
	s_add_i32 m0, s0, 0x2000
	s_add_u32 s0, s24, 0x40080
	v_lshl_add_u64 v[156:157], v[182:183], 0, s[96:97]
	s_addc_u32 s1, s25, 0
	s_add_i32 s24, s49, s34
	global_load_lds_dwordx4 v[156:157], off
	v_lshl_add_u64 v[156:157], s[0:1], 0, v[0:1]
	s_mov_b32 m0, s24
	s_nop 0
	global_load_lds_dwordx4 v[156:157], off
	v_lshl_add_u64 v[156:157], s[0:1], 0, v[138:139]
	s_add_i32 m0, s24, 0x2000
	s_nop 0
	global_load_lds_dwordx4 v[156:157], off
	v_lshl_add_u64 v[156:157], v[234:235], 0, s[96:97]
	s_mov_b32 m0, s39
	s_nop 0
	global_load_lds_dwordx4 v[156:157], off
	v_lshl_add_u64 v[156:157], v[236:237], 0, s[96:97]
	s_mov_b32 m0, s41
	s_nop 0
	global_load_lds_dwordx4 v[156:157], off
	s_waitcnt vmcnt(8)
	s_waitcnt lgkmcnt(0)
	s_barrier
	v_mfma_f32_16x16x32_bf16 v[62:65], v[130:133], v[178:181], v[62:65]
	v_mfma_f32_16x16x32_bf16 v[50:53], v[148:151], v[178:181], v[50:53]
	v_mfma_f32_16x16x32_bf16 v[46:49], v[130:133], v[194:197], v[46:49]
	v_mfma_f32_16x16x32_bf16 v[38:41], v[148:151], v[194:197], v[38:41]
	v_mfma_f32_16x16x32_bf16 v[30:33], v[130:133], v[218:221], v[30:33]
	v_mfma_f32_16x16x32_bf16 v[22:25], v[148:151], v[218:221], v[22:25]
	v_mfma_f32_16x16x32_bf16 v[14:17], v[130:133], v[226:229], v[14:17]
	v_mfma_f32_16x16x32_bf16 v[6:9], v[148:151], v[226:229], v[6:9]
	v_mfma_f32_16x16x32_bf16 v[62:65], v[134:137], v[190:193], v[62:65]
	v_mfma_f32_16x16x32_bf16 v[50:53], v[152:155], v[190:193], v[50:53]
	v_mfma_f32_16x16x32_bf16 v[46:49], v[134:137], v[214:217], v[46:49]
	v_mfma_f32_16x16x32_bf16 v[38:41], v[152:155], v[214:217], v[38:41]
	v_mfma_f32_16x16x32_bf16 v[30:33], v[134:137], v[222:225], v[30:33]
	v_mfma_f32_16x16x32_bf16 v[22:25], v[152:155], v[222:225], v[22:25]
	v_mfma_f32_16x16x32_bf16 v[14:17], v[134:137], v[230:233], v[14:17]
	v_mfma_f32_16x16x32_bf16 v[6:9], v[152:155], v[230:233], v[6:9]
	v_mfma_f32_16x16x32_bf16 v[58:61], v[162:165], v[178:181], v[58:61]
	v_mfma_f32_16x16x32_bf16 v[54:57], v[170:173], v[178:181], v[54:57]
	v_mfma_f32_16x16x32_bf16 v[42:45], v[162:165], v[194:197], v[42:45]
	v_mfma_f32_16x16x32_bf16 v[34:37], v[170:173], v[194:197], v[34:37]
	v_mfma_f32_16x16x32_bf16 v[26:29], v[162:165], v[218:221], v[26:29]
	v_mfma_f32_16x16x32_bf16 v[18:21], v[170:173], v[218:221], v[18:21]
	v_mfma_f32_16x16x32_bf16 v[10:13], v[162:165], v[226:229], v[10:13]
	v_mfma_f32_16x16x32_bf16 v[2:5], v[170:173], v[226:229], v[2:5]
	v_mfma_f32_16x16x32_bf16 v[58:61], v[166:169], v[190:193], v[58:61]
	v_mfma_f32_16x16x32_bf16 v[54:57], v[174:177], v[190:193], v[54:57]
	v_mfma_f32_16x16x32_bf16 v[42:45], v[166:169], v[214:217], v[42:45]
	v_mfma_f32_16x16x32_bf16 v[34:37], v[174:177], v[214:217], v[34:37]
	v_mfma_f32_16x16x32_bf16 v[26:29], v[166:169], v[222:225], v[26:29]
	v_mfma_f32_16x16x32_bf16 v[18:21], v[174:177], v[222:225], v[18:21]
	v_mfma_f32_16x16x32_bf16 v[10:13], v[166:169], v[230:233], v[10:13]
	v_mfma_f32_16x16x32_bf16 v[2:5], v[174:177], v[230:233], v[2:5]
	s_barrier
	s_add_i32 s57, s57, 2
	s_add_u32 s22, s22, 0x100
	s_addc_u32 s23, s23, 0
	s_add_u32 s47, s47, 0x100
	s_addc_u32 s56, s56, 0
	s_cmp_gt_u32 s57, 13
	s_cbranch_scc0 .LBB11_926
	s_and_b64 vcc, exec, s[14:15]
	s_cbranch_vccz .LBB11_929
	s_barrier

.LBB11_1172:
	s_add_u32 s0, s16, 0xfffc0080
	s_addc_u32 s1, s17, -1
	s_add_i32 s48, 0, 0x10000
	s_cmp_eq_u32 vcc_hi, 12
	s_cselect_b32 s39, s9, s1
	s_cselect_b32 s38, s68, s0
	s_cselect_b32 s29, s69, vcc_lo
	s_cselect_b32 s28, s70, s71
	s_add_i32 s49, 0, 0x14000
	v_add_u32_e32 v158, s48, v146
	v_add_u32_e32 v174, s49, v146
	ds_read_b128 v[140:143], v158
	ds_read_b128 v[150:153], v158 offset:1024
	ds_read_b128 v[154:157], v158 offset:2048
	ds_read_b128 v[158:161], v158 offset:3072
	ds_read_b128 v[162:165], v174
	ds_read_b128 v[166:169], v174 offset:1024
	ds_read_b128 v[170:173], v174 offset:2048
	ds_read_b128 v[174:177], v174 offset:3072
	v_lshl_add_u64 v[182:183], s[16:17], 0, v[136:137]
	s_add_i32 m0, s46, 0xc000
	ds_read_b128 v[178:181], v149
	ds_read_b128 v[190:193], v149 offset:1024
	ds_read_b128 v[194:197], v149 offset:2048
	ds_read_b128 v[214:217], v149 offset:3072
	ds_read_b128 v[218:221], v149 offset:4096
	ds_read_b128 v[222:225], v149 offset:5120
	ds_read_b128 v[226:229], v149 offset:6144
	ds_read_b128 v[230:233], v149 offset:7168
	global_load_lds_dwordx4 v[182:183], off
	v_lshl_add_u64 v[182:183], s[16:17], 0, v[138:139]
	s_add_i32 m0, s46, 0xe000
	s_nop 0
	global_load_lds_dwordx4 v[182:183], off
	s_waitcnt vmcnt(8)
	s_waitcnt lgkmcnt(0)
	s_barrier
	v_mfma_f32_16x16x32_bf16 v[126:129], v[140:143], v[178:181], v[126:129]
	v_mfma_f32_16x16x32_bf16 v[122:125], v[154:157], v[178:181], v[122:125]
	v_mfma_f32_16x16x32_bf16 v[110:113], v[140:143], v[194:197], v[110:113]
	v_mfma_f32_16x16x32_bf16 v[106:109], v[154:157], v[194:197], v[106:109]
	v_mfma_f32_16x16x32_bf16 v[94:97], v[140:143], v[218:221], v[94:97]
	v_mfma_f32_16x16x32_bf16 v[90:93], v[154:157], v[218:221], v[90:93]
	v_mfma_f32_16x16x32_bf16 v[78:81], v[140:143], v[226:229], v[78:81]
	v_mfma_f32_16x16x32_bf16 v[74:77], v[154:157], v[226:229], v[74:77]
	v_mfma_f32_16x16x32_bf16 v[126:129], v[150:153], v[190:193], v[126:129]
	v_mfma_f32_16x16x32_bf16 v[122:125], v[158:161], v[190:193], v[122:125]
	v_mfma_f32_16x16x32_bf16 v[110:113], v[150:153], v[214:217], v[110:113]
	v_mfma_f32_16x16x32_bf16 v[106:109], v[158:161], v[214:217], v[106:109]
	v_mfma_f32_16x16x32_bf16 v[94:97], v[150:153], v[222:225], v[94:97]
	v_mfma_f32_16x16x32_bf16 v[90:93], v[158:161], v[222:225], v[90:93]
	v_mfma_f32_16x16x32_bf16 v[78:81], v[150:153], v[230:233], v[78:81]
	v_mfma_f32_16x16x32_bf16 v[74:77], v[158:161], v[230:233], v[74:77]
	v_mfma_f32_16x16x32_bf16 v[118:121], v[162:165], v[178:181], v[118:121]
	v_mfma_f32_16x16x32_bf16 v[114:117], v[170:173], v[178:181], v[114:117]
	v_mfma_f32_16x16x32_bf16 v[102:105], v[162:165], v[194:197], v[102:105]
	v_mfma_f32_16x16x32_bf16 v[98:101], v[170:173], v[194:197], v[98:101]
	v_mfma_f32_16x16x32_bf16 v[86:89], v[162:165], v[218:221], v[86:89]
	v_mfma_f32_16x16x32_bf16 v[82:85], v[170:173], v[218:221], v[82:85]
	v_mfma_f32_16x16x32_bf16 v[70:73], v[162:165], v[226:229], v[70:73]
	v_mfma_f32_16x16x32_bf16 v[66:69], v[170:173], v[226:229], v[66:69]
	v_mfma_f32_16x16x32_bf16 v[118:121], v[166:169], v[190:193], v[118:121]
	v_mfma_f32_16x16x32_bf16 v[114:117], v[174:177], v[190:193], v[114:117]
	v_mfma_f32_16x16x32_bf16 v[102:105], v[166:169], v[214:217], v[102:105]
	v_mfma_f32_16x16x32_bf16 v[98:101], v[174:177], v[214:217], v[98:101]
	v_mfma_f32_16x16x32_bf16 v[86:89], v[166:169], v[222:225], v[86:89]
	v_mfma_f32_16x16x32_bf16 v[82:85], v[174:177], v[222:225], v[82:85]
	v_mfma_f32_16x16x32_bf16 v[70:73], v[166:169], v[230:233], v[70:73]
	v_mfma_f32_16x16x32_bf16 v[66:69], v[174:177], v[230:233], v[66:69]
	s_barrier
	s_add_i32 s0, s48, s45
	v_lshl_add_u64 v[182:183], s[28:29], 0, v[0:1]
	s_mov_b32 m0, s0
	ds_read_b128 v[178:181], v149 offset:16384
	ds_read_b128 v[190:193], v149 offset:17408
	ds_read_b128 v[194:197], v149 offset:18432
	ds_read_b128 v[214:217], v149 offset:19456
	ds_read_b128 v[218:221], v149 offset:20480
	ds_read_b128 v[222:225], v149 offset:21504
	ds_read_b128 v[226:229], v149 offset:22528
	ds_read_b128 v[230:233], v149 offset:23552
	global_load_lds_dwordx4 v[182:183], off
	s_add_i32 m0, s0, 0x2000
	s_add_u32 s0, s28, 0x40000
	v_lshl_add_u64 v[234:235], s[28:29], 0, v[134:135]
	s_addc_u32 s1, s29, 0
	s_add_i32 s48, s49, s45
	global_load_lds_dwordx4 v[234:235], off
	v_lshl_add_u64 v[236:237], s[0:1], 0, v[0:1]
	s_mov_b32 m0, s48
	v_lshl_add_u64 v[238:239], s[38:39], 0, v[132:133]
	global_load_lds_dwordx4 v[236:237], off
	v_lshl_add_u64 v[236:237], s[0:1], 0, v[134:135]
	s_add_i32 m0, s48, 0x2000
	s_nop 0
	global_load_lds_dwordx4 v[236:237], off
	v_lshl_add_u64 v[236:237], s[38:39], 0, v[130:131]
	s_mov_b32 m0, s46
	s_nop 0
	global_load_lds_dwordx4 v[236:237], off
	s_mov_b32 m0, s47
	s_nop 0
	global_load_lds_dwordx4 v[238:239], off
	s_waitcnt vmcnt(8)
	s_waitcnt lgkmcnt(0)
	s_barrier
	v_mfma_f32_16x16x32_bf16 v[62:65], v[140:143], v[178:181], v[62:65]
	v_mfma_f32_16x16x32_bf16 v[58:61], v[154:157], v[178:181], v[58:61]
	v_mfma_f32_16x16x32_bf16 v[46:49], v[140:143], v[194:197], v[46:49]
	v_mfma_f32_16x16x32_bf16 v[42:45], v[154:157], v[194:197], v[42:45]
	v_mfma_f32_16x16x32_bf16 v[30:33], v[140:143], v[218:221], v[30:33]
	v_mfma_f32_16x16x32_bf16 v[26:29], v[154:157], v[218:221], v[26:29]
	v_mfma_f32_16x16x32_bf16 v[14:17], v[140:143], v[226:229], v[14:17]
	v_mfma_f32_16x16x32_bf16 v[10:13], v[154:157], v[226:229], v[10:13]
	v_mfma_f32_16x16x32_bf16 v[62:65], v[150:153], v[190:193], v[62:65]
	v_mfma_f32_16x16x32_bf16 v[58:61], v[158:161], v[190:193], v[58:61]
	v_mfma_f32_16x16x32_bf16 v[46:49], v[150:153], v[214:217], v[46:49]
	v_mfma_f32_16x16x32_bf16 v[42:45], v[158:161], v[214:217], v[42:45]
	v_mfma_f32_16x16x32_bf16 v[30:33], v[150:153], v[222:225], v[30:33]
	v_mfma_f32_16x16x32_bf16 v[26:29], v[158:161], v[222:225], v[26:29]
	v_mfma_f32_16x16x32_bf16 v[14:17], v[150:153], v[230:233], v[14:17]
	v_mfma_f32_16x16x32_bf16 v[10:13], v[158:161], v[230:233], v[10:13]
	v_mfma_f32_16x16x32_bf16 v[54:57], v[162:165], v[178:181], v[54:57]
	v_mfma_f32_16x16x32_bf16 v[50:53], v[170:173], v[178:181], v[50:53]
	v_mfma_f32_16x16x32_bf16 v[38:41], v[162:165], v[194:197], v[38:41]
	v_mfma_f32_16x16x32_bf16 v[34:37], v[170:173], v[194:197], v[34:37]
	v_mfma_f32_16x16x32_bf16 v[22:25], v[162:165], v[218:221], v[22:25]
	v_mfma_f32_16x16x32_bf16 v[18:21], v[170:173], v[218:221], v[18:21]
	v_mfma_f32_16x16x32_bf16 v[6:9], v[162:165], v[226:229], v[6:9]
	v_mfma_f32_16x16x32_bf16 v[2:5], v[170:173], v[226:229], v[2:5]
	v_mfma_f32_16x16x32_bf16 v[54:57], v[166:169], v[190:193], v[54:57]
	v_mfma_f32_16x16x32_bf16 v[50:53], v[174:177], v[190:193], v[50:53]
	v_mfma_f32_16x16x32_bf16 v[38:41], v[166:169], v[214:217], v[38:41]
	v_mfma_f32_16x16x32_bf16 v[34:37], v[174:177], v[214:217], v[34:37]
	v_mfma_f32_16x16x32_bf16 v[22:25], v[166:169], v[222:225], v[22:25]
	v_mfma_f32_16x16x32_bf16 v[18:21], v[174:177], v[222:225], v[18:21]
	v_mfma_f32_16x16x32_bf16 v[6:9], v[166:169], v[230:233], v[6:9]
	v_mfma_f32_16x16x32_bf16 v[2:5], v[174:177], v[230:233], v[2:5]
	s_barrier
	s_add_i32 s48, 0, 0x18000
	s_add_i32 s49, 0, 0x1c000
	v_add_u32_e32 v158, s48, v146
	v_add_u32_e32 v174, s49, v146
	ds_read_b128 v[140:143], v158
	ds_read_b128 v[150:153], v158 offset:1024
	ds_read_b128 v[154:157], v158 offset:2048
	ds_read_b128 v[158:161], v158 offset:3072
	ds_read_b128 v[162:165], v174
	ds_read_b128 v[166:169], v174 offset:1024
	ds_read_b128 v[170:173], v174 offset:2048
	ds_read_b128 v[174:177], v174 offset:3072
	s_add_u32 s0, s38, 0x40000
	s_addc_u32 s1, s39, 0
	s_mov_b32 m0, s56
	v_lshl_add_u64 v[240:241], s[0:1], 0, v[130:131]
	ds_read_b128 v[178:181], v149 offset:32768
	ds_read_b128 v[190:193], v149 offset:33792
	ds_read_b128 v[194:197], v149 offset:34816
	ds_read_b128 v[214:217], v149 offset:35840
	ds_read_b128 v[218:221], v149 offset:36864
	ds_read_b128 v[222:225], v149 offset:37888
	ds_read_b128 v[226:229], v149 offset:38912
	ds_read_b128 v[230:233], v149 offset:39936
	global_load_lds_dwordx4 v[240:241], off
	v_lshl_add_u64 v[240:241], s[0:1], 0, v[132:133]
	s_mov_b32 m0, s57
	s_nop 0
	global_load_lds_dwordx4 v[240:241], off
	s_waitcnt vmcnt(8)
	s_waitcnt lgkmcnt(0)
	s_barrier
	v_mfma_f32_16x16x32_bf16 v[126:129], v[140:143], v[178:181], v[126:129]
	v_mfma_f32_16x16x32_bf16 v[122:125], v[154:157], v[178:181], v[122:125]
	v_mfma_f32_16x16x32_bf16 v[110:113], v[140:143], v[194:197], v[110:113]
	v_mfma_f32_16x16x32_bf16 v[106:109], v[154:157], v[194:197], v[106:109]
	v_mfma_f32_16x16x32_bf16 v[94:97], v[140:143], v[218:221], v[94:97]
	v_mfma_f32_16x16x32_bf16 v[90:93], v[154:157], v[218:221], v[90:93]
	v_mfma_f32_16x16x32_bf16 v[78:81], v[140:143], v[226:229], v[78:81]
	v_mfma_f32_16x16x32_bf16 v[74:77], v[154:157], v[226:229], v[74:77]
	v_mfma_f32_16x16x32_bf16 v[126:129], v[150:153], v[190:193], v[126:129]
	v_mfma_f32_16x16x32_bf16 v[122:125], v[158:161], v[190:193], v[122:125]
	v_mfma_f32_16x16x32_bf16 v[110:113], v[150:153], v[214:217], v[110:113]
	v_mfma_f32_16x16x32_bf16 v[106:109], v[158:161], v[214:217], v[106:109]
	v_mfma_f32_16x16x32_bf16 v[94:97], v[150:153], v[222:225], v[94:97]
	v_mfma_f32_16x16x32_bf16 v[90:93], v[158:161], v[222:225], v[90:93]
	v_mfma_f32_16x16x32_bf16 v[78:81], v[150:153], v[230:233], v[78:81]
	v_mfma_f32_16x16x32_bf16 v[74:77], v[158:161], v[230:233], v[74:77]
	v_mfma_f32_16x16x32_bf16 v[118:121], v[162:165], v[178:181], v[118:121]
	v_mfma_f32_16x16x32_bf16 v[114:117], v[170:173], v[178:181], v[114:117]
	v_mfma_f32_16x16x32_bf16 v[102:105], v[162:165], v[194:197], v[102:105]
	v_mfma_f32_16x16x32_bf16 v[98:101], v[170:173], v[194:197], v[98:101]
	v_mfma_f32_16x16x32_bf16 v[86:89], v[162:165], v[218:221], v[86:89]
	v_mfma_f32_16x16x32_bf16 v[82:85], v[170:173], v[218:221], v[82:85]
	v_mfma_f32_16x16x32_bf16 v[70:73], v[162:165], v[226:229], v[70:73]
	v_mfma_f32_16x16x32_bf16 v[66:69], v[170:173], v[226:229], v[66:69]
	v_mfma_f32_16x16x32_bf16 v[118:121], v[166:169], v[190:193], v[118:121]
	v_mfma_f32_16x16x32_bf16 v[114:117], v[174:177], v[190:193], v[114:117]
	v_mfma_f32_16x16x32_bf16 v[102:105], v[166:169], v[214:217], v[102:105]
	v_mfma_f32_16x16x32_bf16 v[98:101], v[174:177], v[214:217], v[98:101]
	v_mfma_f32_16x16x32_bf16 v[86:89], v[166:169], v[222:225], v[86:89]
	v_mfma_f32_16x16x32_bf16 v[82:85], v[174:177], v[222:225], v[82:85]
	v_mfma_f32_16x16x32_bf16 v[70:73], v[166:169], v[230:233], v[70:73]
	v_mfma_f32_16x16x32_bf16 v[66:69], v[174:177], v[230:233], v[66:69]
	s_barrier
	s_add_i32 s0, s48, s45
	v_lshl_add_u64 v[182:183], v[182:183], 0, s[96:97]
	s_mov_b32 m0, s0
	ds_read_b128 v[178:181], v149 offset:49152
	ds_read_b128 v[190:193], v149 offset:50176
	ds_read_b128 v[194:197], v149 offset:51200
	ds_read_b128 v[214:217], v149 offset:52224
	ds_read_b128 v[218:221], v149 offset:53248
	ds_read_b128 v[222:225], v149 offset:54272
	ds_read_b128 v[226:229], v149 offset:55296
	ds_read_b128 v[230:233], v149 offset:56320
	global_load_lds_dwordx4 v[182:183], off
	s_add_i32 m0, s0, 0x2000
	s_add_u32 s0, s28, 0x40080
	v_lshl_add_u64 v[182:183], v[234:235], 0, s[96:97]
	s_addc_u32 s1, s29, 0
	s_add_i32 s28, s49, s45
	global_load_lds_dwordx4 v[182:183], off
	v_lshl_add_u64 v[182:183], s[0:1], 0, v[0:1]
	s_mov_b32 m0, s28
	s_nop 0
	global_load_lds_dwordx4 v[182:183], off
	v_lshl_add_u64 v[182:183], s[0:1], 0, v[134:135]
	s_add_i32 m0, s28, 0x2000
	s_nop 0
	global_load_lds_dwordx4 v[182:183], off
	v_lshl_add_u64 v[182:183], v[236:237], 0, s[96:97]
	s_mov_b32 m0, s58
	s_nop 0
	global_load_lds_dwordx4 v[182:183], off
	v_lshl_add_u64 v[182:183], v[238:239], 0, s[96:97]
	s_mov_b32 m0, s59
	s_nop 0
	global_load_lds_dwordx4 v[182:183], off
	s_waitcnt vmcnt(8)
	s_waitcnt lgkmcnt(0)
	s_barrier
	v_mfma_f32_16x16x32_bf16 v[62:65], v[140:143], v[178:181], v[62:65]
	v_mfma_f32_16x16x32_bf16 v[58:61], v[154:157], v[178:181], v[58:61]
	v_mfma_f32_16x16x32_bf16 v[46:49], v[140:143], v[194:197], v[46:49]
	v_mfma_f32_16x16x32_bf16 v[42:45], v[154:157], v[194:197], v[42:45]
	v_mfma_f32_16x16x32_bf16 v[30:33], v[140:143], v[218:221], v[30:33]
	v_mfma_f32_16x16x32_bf16 v[26:29], v[154:157], v[218:221], v[26:29]
	v_mfma_f32_16x16x32_bf16 v[14:17], v[140:143], v[226:229], v[14:17]
	v_mfma_f32_16x16x32_bf16 v[10:13], v[154:157], v[226:229], v[10:13]
	v_mfma_f32_16x16x32_bf16 v[62:65], v[150:153], v[190:193], v[62:65]
	v_mfma_f32_16x16x32_bf16 v[58:61], v[158:161], v[190:193], v[58:61]
	v_mfma_f32_16x16x32_bf16 v[46:49], v[150:153], v[214:217], v[46:49]
	v_mfma_f32_16x16x32_bf16 v[42:45], v[158:161], v[214:217], v[42:45]
	v_mfma_f32_16x16x32_bf16 v[30:33], v[150:153], v[222:225], v[30:33]
	v_mfma_f32_16x16x32_bf16 v[26:29], v[158:161], v[222:225], v[26:29]
	v_mfma_f32_16x16x32_bf16 v[14:17], v[150:153], v[230:233], v[14:17]
	v_mfma_f32_16x16x32_bf16 v[10:13], v[158:161], v[230:233], v[10:13]
	v_mfma_f32_16x16x32_bf16 v[54:57], v[162:165], v[178:181], v[54:57]
	v_mfma_f32_16x16x32_bf16 v[50:53], v[170:173], v[178:181], v[50:53]
	v_mfma_f32_16x16x32_bf16 v[38:41], v[162:165], v[194:197], v[38:41]
	v_mfma_f32_16x16x32_bf16 v[34:37], v[170:173], v[194:197], v[34:37]
	v_mfma_f32_16x16x32_bf16 v[22:25], v[162:165], v[218:221], v[22:25]
	v_mfma_f32_16x16x32_bf16 v[18:21], v[170:173], v[218:221], v[18:21]
	v_mfma_f32_16x16x32_bf16 v[6:9], v[162:165], v[226:229], v[6:9]
	v_mfma_f32_16x16x32_bf16 v[2:5], v[170:173], v[226:229], v[2:5]
	v_mfma_f32_16x16x32_bf16 v[54:57], v[166:169], v[190:193], v[54:57]
	v_mfma_f32_16x16x32_bf16 v[50:53], v[174:177], v[190:193], v[50:53]
	v_mfma_f32_16x16x32_bf16 v[38:41], v[166:169], v[214:217], v[38:41]
	v_mfma_f32_16x16x32_bf16 v[34:37], v[174:177], v[214:217], v[34:37]
	v_mfma_f32_16x16x32_bf16 v[22:25], v[166:169], v[222:225], v[22:25]
	v_mfma_f32_16x16x32_bf16 v[18:21], v[174:177], v[222:225], v[18:21]
	v_mfma_f32_16x16x32_bf16 v[6:9], v[166:169], v[230:233], v[6:9]
	v_mfma_f32_16x16x32_bf16 v[2:5], v[174:177], v[230:233], v[2:5]
	s_barrier
	s_add_i32 vcc_hi, vcc_hi, 2
	s_add_u32 s16, s16, 0x100
	s_addc_u32 s17, s17, 0
	s_add_u32 s71, s71, 0x100
	s_addc_u32 vcc_lo, vcc_lo, 0
	s_cmp_gt_u32 vcc_hi, 13
	s_cbranch_scc0 .LBB11_1172
	s_and_b64 vcc, exec, s[20:21]
	s_cbranch_vccz .LBB11_1175
	s_barrier

.LBB11_1629:
	s_add_u32 s0, s22, 0xfff80080
	s_addc_u32 s1, s23, -1
	s_add_i32 s48, 0, 0x10000
	s_cmp_eq_u32 s57, 28
	s_cselect_b32 s27, s8, s1
	s_cselect_b32 s26, s9, s0
	v_add_u32_e32 v148, s48, v151
	s_cselect_b32 s25, s40, s56
	s_cselect_b32 s24, s46, s47
	s_add_i32 s49, 0, 0x14000
	ds_read_b128 v[140:143], v148
	ds_read_b128 v[144:147], v148 offset:1024
	ds_read_b128 v[154:157], v148 offset:2048
	ds_read_b128 v[158:161], v148 offset:3072
	v_add_u32_e32 v148, s49, v151
	ds_read_b128 v[162:165], v148
	ds_read_b128 v[166:169], v148 offset:1024
	ds_read_b128 v[170:173], v148 offset:2048
	ds_read_b128 v[174:177], v148 offset:3072
	v_lshl_add_u64 v[148:149], s[22:23], 0, v[136:137]
	s_add_i32 m0, s35, 0xc000
	ds_read_b128 v[178:181], v153
	ds_read_b128 v[190:193], v153 offset:1024
	ds_read_b128 v[194:197], v153 offset:2048
	ds_read_b128 v[214:217], v153 offset:3072
	ds_read_b128 v[218:221], v153 offset:4096
	ds_read_b128 v[222:225], v153 offset:5120
	ds_read_b128 v[226:229], v153 offset:6144
	ds_read_b128 v[230:233], v153 offset:7168
	global_load_lds_dwordx4 v[148:149], off
	v_lshl_add_u64 v[148:149], s[22:23], 0, v[138:139]
	s_add_i32 m0, s35, 0xe000
	s_nop 0
	global_load_lds_dwordx4 v[148:149], off
	s_waitcnt vmcnt(8)
	s_waitcnt lgkmcnt(0)
	s_barrier
	v_mfma_f32_16x16x32_bf16 v[126:129], v[140:143], v[178:181], v[126:129]
	v_mfma_f32_16x16x32_bf16 v[122:125], v[154:157], v[178:181], v[122:125]
	v_mfma_f32_16x16x32_bf16 v[110:113], v[140:143], v[194:197], v[110:113]
	v_mfma_f32_16x16x32_bf16 v[106:109], v[154:157], v[194:197], v[106:109]
	v_mfma_f32_16x16x32_bf16 v[94:97], v[140:143], v[218:221], v[94:97]
	v_mfma_f32_16x16x32_bf16 v[90:93], v[154:157], v[218:221], v[90:93]
	v_mfma_f32_16x16x32_bf16 v[78:81], v[140:143], v[226:229], v[78:81]
	v_mfma_f32_16x16x32_bf16 v[74:77], v[154:157], v[226:229], v[74:77]
	v_mfma_f32_16x16x32_bf16 v[126:129], v[144:147], v[190:193], v[126:129]
	v_mfma_f32_16x16x32_bf16 v[122:125], v[158:161], v[190:193], v[122:125]
	v_mfma_f32_16x16x32_bf16 v[110:113], v[144:147], v[214:217], v[110:113]
	v_mfma_f32_16x16x32_bf16 v[106:109], v[158:161], v[214:217], v[106:109]
	v_mfma_f32_16x16x32_bf16 v[94:97], v[144:147], v[222:225], v[94:97]
	v_mfma_f32_16x16x32_bf16 v[90:93], v[158:161], v[222:225], v[90:93]
	v_mfma_f32_16x16x32_bf16 v[78:81], v[144:147], v[230:233], v[78:81]
	v_mfma_f32_16x16x32_bf16 v[74:77], v[158:161], v[230:233], v[74:77]
	v_mfma_f32_16x16x32_bf16 v[118:121], v[162:165], v[178:181], v[118:121]
	v_mfma_f32_16x16x32_bf16 v[114:117], v[170:173], v[178:181], v[114:117]
	v_mfma_f32_16x16x32_bf16 v[102:105], v[162:165], v[194:197], v[102:105]
	v_mfma_f32_16x16x32_bf16 v[98:101], v[170:173], v[194:197], v[98:101]
	v_mfma_f32_16x16x32_bf16 v[86:89], v[162:165], v[218:221], v[86:89]
	v_mfma_f32_16x16x32_bf16 v[82:85], v[170:173], v[218:221], v[82:85]
	v_mfma_f32_16x16x32_bf16 v[70:73], v[162:165], v[226:229], v[70:73]
	v_mfma_f32_16x16x32_bf16 v[66:69], v[170:173], v[226:229], v[66:69]
	v_mfma_f32_16x16x32_bf16 v[118:121], v[166:169], v[190:193], v[118:121]
	v_mfma_f32_16x16x32_bf16 v[114:117], v[174:177], v[190:193], v[114:117]
	v_mfma_f32_16x16x32_bf16 v[102:105], v[166:169], v[214:217], v[102:105]
	v_mfma_f32_16x16x32_bf16 v[98:101], v[174:177], v[214:217], v[98:101]
	v_mfma_f32_16x16x32_bf16 v[86:89], v[166:169], v[222:225], v[86:89]
	v_mfma_f32_16x16x32_bf16 v[82:85], v[174:177], v[222:225], v[82:85]
	v_mfma_f32_16x16x32_bf16 v[70:73], v[166:169], v[230:233], v[70:73]
	v_mfma_f32_16x16x32_bf16 v[66:69], v[174:177], v[230:233], v[66:69]
	s_barrier
	s_add_i32 s0, s48, s34
	v_lshl_add_u64 v[148:149], s[24:25], 0, v[0:1]
	s_mov_b32 m0, s0
	ds_read_b128 v[178:181], v153 offset:16384
	ds_read_b128 v[190:193], v153 offset:17408
	ds_read_b128 v[194:197], v153 offset:18432
	ds_read_b128 v[214:217], v153 offset:19456
	ds_read_b128 v[218:221], v153 offset:20480
	ds_read_b128 v[222:225], v153 offset:21504
	ds_read_b128 v[226:229], v153 offset:22528
	ds_read_b128 v[230:233], v153 offset:23552
	global_load_lds_dwordx4 v[148:149], off
	s_add_i32 m0, s0, 0x2000
	s_add_u32 s0, s24, 0x80000
	v_lshl_add_u64 v[182:183], s[24:25], 0, v[130:131]
	s_addc_u32 s1, s25, 0
	s_add_i32 s48, s49, s34
	global_load_lds_dwordx4 v[182:183], off
	v_lshl_add_u64 v[234:235], s[0:1], 0, v[0:1]
	s_mov_b32 m0, s48
	v_lshl_add_u64 v[236:237], s[26:27], 0, v[132:133]
	global_load_lds_dwordx4 v[234:235], off
	v_lshl_add_u64 v[234:235], s[0:1], 0, v[130:131]
	s_add_i32 m0, s48, 0x2000
	s_nop 0
	global_load_lds_dwordx4 v[234:235], off
	v_lshl_add_u64 v[234:235], s[26:27], 0, v[134:135]
	s_mov_b32 m0, s35
	s_nop 0
	global_load_lds_dwordx4 v[234:235], off
	s_mov_b32 m0, s36
	s_nop 0
	global_load_lds_dwordx4 v[236:237], off
	s_waitcnt vmcnt(8)
	s_waitcnt lgkmcnt(0)
	s_barrier
	v_mfma_f32_16x16x32_bf16 v[62:65], v[140:143], v[178:181], v[62:65]
	v_mfma_f32_16x16x32_bf16 v[58:61], v[154:157], v[178:181], v[58:61]
	v_mfma_f32_16x16x32_bf16 v[46:49], v[140:143], v[194:197], v[46:49]
	v_mfma_f32_16x16x32_bf16 v[42:45], v[154:157], v[194:197], v[42:45]
	v_mfma_f32_16x16x32_bf16 v[30:33], v[140:143], v[218:221], v[30:33]
	v_mfma_f32_16x16x32_bf16 v[26:29], v[154:157], v[218:221], v[26:29]
	v_mfma_f32_16x16x32_bf16 v[14:17], v[140:143], v[226:229], v[14:17]
	v_mfma_f32_16x16x32_bf16 v[10:13], v[154:157], v[226:229], v[10:13]
	v_mfma_f32_16x16x32_bf16 v[62:65], v[144:147], v[190:193], v[62:65]
	v_mfma_f32_16x16x32_bf16 v[58:61], v[158:161], v[190:193], v[58:61]
	v_mfma_f32_16x16x32_bf16 v[46:49], v[144:147], v[214:217], v[46:49]
	v_mfma_f32_16x16x32_bf16 v[42:45], v[158:161], v[214:217], v[42:45]
	v_mfma_f32_16x16x32_bf16 v[30:33], v[144:147], v[222:225], v[30:33]
	v_mfma_f32_16x16x32_bf16 v[26:29], v[158:161], v[222:225], v[26:29]
	v_mfma_f32_16x16x32_bf16 v[14:17], v[144:147], v[230:233], v[14:17]
	v_mfma_f32_16x16x32_bf16 v[10:13], v[158:161], v[230:233], v[10:13]
	v_mfma_f32_16x16x32_bf16 v[54:57], v[162:165], v[178:181], v[54:57]
	v_mfma_f32_16x16x32_bf16 v[50:53], v[170:173], v[178:181], v[50:53]
	v_mfma_f32_16x16x32_bf16 v[38:41], v[162:165], v[194:197], v[38:41]
	v_mfma_f32_16x16x32_bf16 v[34:37], v[170:173], v[194:197], v[34:37]
	v_mfma_f32_16x16x32_bf16 v[22:25], v[162:165], v[218:221], v[22:25]
	v_mfma_f32_16x16x32_bf16 v[18:21], v[170:173], v[218:221], v[18:21]
	v_mfma_f32_16x16x32_bf16 v[6:9], v[162:165], v[226:229], v[6:9]
	v_mfma_f32_16x16x32_bf16 v[2:5], v[170:173], v[226:229], v[2:5]
	v_mfma_f32_16x16x32_bf16 v[54:57], v[166:169], v[190:193], v[54:57]
	v_mfma_f32_16x16x32_bf16 v[50:53], v[174:177], v[190:193], v[50:53]
	v_mfma_f32_16x16x32_bf16 v[38:41], v[166:169], v[214:217], v[38:41]
	v_mfma_f32_16x16x32_bf16 v[34:37], v[174:177], v[214:217], v[34:37]
	v_mfma_f32_16x16x32_bf16 v[22:25], v[166:169], v[222:225], v[22:25]
	v_mfma_f32_16x16x32_bf16 v[18:21], v[174:177], v[222:225], v[18:21]
	v_mfma_f32_16x16x32_bf16 v[6:9], v[166:169], v[230:233], v[6:9]
	v_mfma_f32_16x16x32_bf16 v[2:5], v[174:177], v[230:233], v[2:5]
	s_barrier
	s_add_i32 s48, 0, 0x18000
	s_add_i32 s49, 0, 0x1c000
	v_add_u32_e32 v158, s48, v151
	v_add_u32_e32 v174, s49, v151
	ds_read_b128 v[140:143], v158
	ds_read_b128 v[144:147], v158 offset:1024
	ds_read_b128 v[154:157], v158 offset:2048
	ds_read_b128 v[158:161], v158 offset:3072
	ds_read_b128 v[162:165], v174
	ds_read_b128 v[166:169], v174 offset:1024
	ds_read_b128 v[170:173], v174 offset:2048
	ds_read_b128 v[174:177], v174 offset:3072
	s_add_u32 s0, s26, 0x80000
	s_addc_u32 s1, s27, 0
	s_mov_b32 m0, s37
	v_lshl_add_u64 v[238:239], s[0:1], 0, v[134:135]
	ds_read_b128 v[178:181], v153 offset:32768
	ds_read_b128 v[190:193], v153 offset:33792
	ds_read_b128 v[194:197], v153 offset:34816
	ds_read_b128 v[214:217], v153 offset:35840
	ds_read_b128 v[218:221], v153 offset:36864
	ds_read_b128 v[222:225], v153 offset:37888
	ds_read_b128 v[226:229], v153 offset:38912
	ds_read_b128 v[230:233], v153 offset:39936
	global_load_lds_dwordx4 v[238:239], off
	v_lshl_add_u64 v[238:239], s[0:1], 0, v[132:133]
	s_mov_b32 m0, s38
	s_nop 0
	global_load_lds_dwordx4 v[238:239], off
	s_waitcnt vmcnt(8)
	s_waitcnt lgkmcnt(0)
	s_barrier
	v_mfma_f32_16x16x32_bf16 v[126:129], v[140:143], v[178:181], v[126:129]
	v_mfma_f32_16x16x32_bf16 v[122:125], v[154:157], v[178:181], v[122:125]
	v_mfma_f32_16x16x32_bf16 v[110:113], v[140:143], v[194:197], v[110:113]
	v_mfma_f32_16x16x32_bf16 v[106:109], v[154:157], v[194:197], v[106:109]
	v_mfma_f32_16x16x32_bf16 v[94:97], v[140:143], v[218:221], v[94:97]
	v_mfma_f32_16x16x32_bf16 v[90:93], v[154:157], v[218:221], v[90:93]
	v_mfma_f32_16x16x32_bf16 v[78:81], v[140:143], v[226:229], v[78:81]
	v_mfma_f32_16x16x32_bf16 v[74:77], v[154:157], v[226:229], v[74:77]
	v_mfma_f32_16x16x32_bf16 v[126:129], v[144:147], v[190:193], v[126:129]
	v_mfma_f32_16x16x32_bf16 v[122:125], v[158:161], v[190:193], v[122:125]
	v_mfma_f32_16x16x32_bf16 v[110:113], v[144:147], v[214:217], v[110:113]
	v_mfma_f32_16x16x32_bf16 v[106:109], v[158:161], v[214:217], v[106:109]
	v_mfma_f32_16x16x32_bf16 v[94:97], v[144:147], v[222:225], v[94:97]
	v_mfma_f32_16x16x32_bf16 v[90:93], v[158:161], v[222:225], v[90:93]
	v_mfma_f32_16x16x32_bf16 v[78:81], v[144:147], v[230:233], v[78:81]
	v_mfma_f32_16x16x32_bf16 v[74:77], v[158:161], v[230:233], v[74:77]
	v_mfma_f32_16x16x32_bf16 v[118:121], v[162:165], v[178:181], v[118:121]
	v_mfma_f32_16x16x32_bf16 v[114:117], v[170:173], v[178:181], v[114:117]
	v_mfma_f32_16x16x32_bf16 v[102:105], v[162:165], v[194:197], v[102:105]
	v_mfma_f32_16x16x32_bf16 v[98:101], v[170:173], v[194:197], v[98:101]
	v_mfma_f32_16x16x32_bf16 v[86:89], v[162:165], v[218:221], v[86:89]
	v_mfma_f32_16x16x32_bf16 v[82:85], v[170:173], v[218:221], v[82:85]
	v_mfma_f32_16x16x32_bf16 v[70:73], v[162:165], v[226:229], v[70:73]
	v_mfma_f32_16x16x32_bf16 v[66:69], v[170:173], v[226:229], v[66:69]
	v_mfma_f32_16x16x32_bf16 v[118:121], v[166:169], v[190:193], v[118:121]
	v_mfma_f32_16x16x32_bf16 v[114:117], v[174:177], v[190:193], v[114:117]
	v_mfma_f32_16x16x32_bf16 v[102:105], v[166:169], v[214:217], v[102:105]
	v_mfma_f32_16x16x32_bf16 v[98:101], v[174:177], v[214:217], v[98:101]
	v_mfma_f32_16x16x32_bf16 v[86:89], v[166:169], v[222:225], v[86:89]
	v_mfma_f32_16x16x32_bf16 v[82:85], v[174:177], v[222:225], v[82:85]
	v_mfma_f32_16x16x32_bf16 v[70:73], v[166:169], v[230:233], v[70:73]
	v_mfma_f32_16x16x32_bf16 v[66:69], v[174:177], v[230:233], v[66:69]
	s_barrier
	s_add_i32 s0, s48, s34
	v_lshl_add_u64 v[148:149], v[148:149], 0, s[96:97]
	s_mov_b32 m0, s0
	ds_read_b128 v[178:181], v153 offset:49152
	ds_read_b128 v[190:193], v153 offset:50176
	ds_read_b128 v[194:197], v153 offset:51200
	ds_read_b128 v[214:217], v153 offset:52224
	ds_read_b128 v[218:221], v153 offset:53248
	ds_read_b128 v[222:225], v153 offset:54272
	ds_read_b128 v[226:229], v153 offset:55296
	ds_read_b128 v[230:233], v153 offset:56320
	global_load_lds_dwordx4 v[148:149], off
	s_add_i32 m0, s0, 0x2000
	s_add_u32 s0, s24, 0x80080
	v_lshl_add_u64 v[148:149], v[182:183], 0, s[96:97]
	s_addc_u32 s1, s25, 0
	s_add_i32 s24, s49, s34
	global_load_lds_dwordx4 v[148:149], off
	v_lshl_add_u64 v[148:149], s[0:1], 0, v[0:1]
	s_mov_b32 m0, s24
	s_nop 0
	global_load_lds_dwordx4 v[148:149], off
	v_lshl_add_u64 v[148:149], s[0:1], 0, v[130:131]
	s_add_i32 m0, s24, 0x2000
	s_nop 0
	global_load_lds_dwordx4 v[148:149], off
	v_lshl_add_u64 v[148:149], v[234:235], 0, s[96:97]
	s_mov_b32 m0, s39
	s_nop 0
	global_load_lds_dwordx4 v[148:149], off
	v_lshl_add_u64 v[148:149], v[236:237], 0, s[96:97]
	s_mov_b32 m0, s41
	s_nop 0
	global_load_lds_dwordx4 v[148:149], off
	s_waitcnt vmcnt(8)
	s_waitcnt lgkmcnt(0)
	s_barrier
	v_mfma_f32_16x16x32_bf16 v[62:65], v[140:143], v[178:181], v[62:65]
	v_mfma_f32_16x16x32_bf16 v[58:61], v[154:157], v[178:181], v[58:61]
	v_mfma_f32_16x16x32_bf16 v[46:49], v[140:143], v[194:197], v[46:49]
	v_mfma_f32_16x16x32_bf16 v[42:45], v[154:157], v[194:197], v[42:45]
	v_mfma_f32_16x16x32_bf16 v[30:33], v[140:143], v[218:221], v[30:33]
	v_mfma_f32_16x16x32_bf16 v[26:29], v[154:157], v[218:221], v[26:29]
	v_mfma_f32_16x16x32_bf16 v[14:17], v[140:143], v[226:229], v[14:17]
	v_mfma_f32_16x16x32_bf16 v[10:13], v[154:157], v[226:229], v[10:13]
	v_mfma_f32_16x16x32_bf16 v[62:65], v[144:147], v[190:193], v[62:65]
	v_mfma_f32_16x16x32_bf16 v[58:61], v[158:161], v[190:193], v[58:61]
	v_mfma_f32_16x16x32_bf16 v[46:49], v[144:147], v[214:217], v[46:49]
	v_mfma_f32_16x16x32_bf16 v[42:45], v[158:161], v[214:217], v[42:45]
	v_mfma_f32_16x16x32_bf16 v[30:33], v[144:147], v[222:225], v[30:33]
	v_mfma_f32_16x16x32_bf16 v[26:29], v[158:161], v[222:225], v[26:29]
	v_mfma_f32_16x16x32_bf16 v[14:17], v[144:147], v[230:233], v[14:17]
	v_mfma_f32_16x16x32_bf16 v[10:13], v[158:161], v[230:233], v[10:13]
	v_mfma_f32_16x16x32_bf16 v[54:57], v[162:165], v[178:181], v[54:57]
	v_mfma_f32_16x16x32_bf16 v[50:53], v[170:173], v[178:181], v[50:53]
	v_mfma_f32_16x16x32_bf16 v[38:41], v[162:165], v[194:197], v[38:41]
	v_mfma_f32_16x16x32_bf16 v[34:37], v[170:173], v[194:197], v[34:37]
	v_mfma_f32_16x16x32_bf16 v[22:25], v[162:165], v[218:221], v[22:25]
	v_mfma_f32_16x16x32_bf16 v[18:21], v[170:173], v[218:221], v[18:21]
	v_mfma_f32_16x16x32_bf16 v[6:9], v[162:165], v[226:229], v[6:9]
	v_mfma_f32_16x16x32_bf16 v[2:5], v[170:173], v[226:229], v[2:5]
	v_mfma_f32_16x16x32_bf16 v[54:57], v[166:169], v[190:193], v[54:57]
	v_mfma_f32_16x16x32_bf16 v[50:53], v[174:177], v[190:193], v[50:53]
	v_mfma_f32_16x16x32_bf16 v[38:41], v[166:169], v[214:217], v[38:41]
	v_mfma_f32_16x16x32_bf16 v[34:37], v[174:177], v[214:217], v[34:37]
	v_mfma_f32_16x16x32_bf16 v[22:25], v[166:169], v[222:225], v[22:25]
	v_mfma_f32_16x16x32_bf16 v[18:21], v[174:177], v[222:225], v[18:21]
	v_mfma_f32_16x16x32_bf16 v[6:9], v[166:169], v[230:233], v[6:9]
	v_mfma_f32_16x16x32_bf16 v[2:5], v[174:177], v[230:233], v[2:5]
	s_barrier
	s_add_i32 s57, s57, 2
	s_add_u32 s22, s22, 0x100
	s_addc_u32 s23, s23, 0
	s_add_u32 s47, s47, 0x100
	s_addc_u32 s56, s56, 0
	s_cmp_gt_u32 s57, 29
	s_cbranch_scc0 .LBB11_1629
	s_and_b64 vcc, exec, s[14:15]
	s_cbranch_vccz .LBB11_1632
	s_barrier

.LBB11_1869:
	s_add_u32 s0, s24, 0xfffc0080
	s_addc_u32 s1, s25, -1
	s_add_i32 s48, 0, 0x10000
	s_cmp_eq_u32 s57, 12
	s_cselect_b32 s27, s43, s1
	s_cselect_b32 s26, s44, s0
	s_cselect_b32 s11, s45, s56
	s_cselect_b32 s10, s46, s47
	s_add_i32 s49, 0, 0x14000
	v_add_u32_e32 v158, s48, v146
	v_add_u32_e32 v174, s49, v146
	ds_read_b128 v[140:143], v158
	ds_read_b128 v[150:153], v158 offset:1024
	ds_read_b128 v[154:157], v158 offset:2048
	ds_read_b128 v[158:161], v158 offset:3072
	ds_read_b128 v[162:165], v174
	ds_read_b128 v[166:169], v174 offset:1024
	ds_read_b128 v[170:173], v174 offset:2048
	ds_read_b128 v[174:177], v174 offset:3072
	v_lshl_add_u64 v[182:183], s[24:25], 0, v[136:137]
	s_add_i32 m0, s7, 0xc000
	ds_read_b128 v[178:181], v149
	ds_read_b128 v[190:193], v149 offset:1024
	ds_read_b128 v[194:197], v149 offset:2048
	ds_read_b128 v[214:217], v149 offset:3072
	ds_read_b128 v[218:221], v149 offset:4096
	ds_read_b128 v[222:225], v149 offset:5120
	ds_read_b128 v[226:229], v149 offset:6144
	ds_read_b128 v[230:233], v149 offset:7168
	global_load_lds_dwordx4 v[182:183], off
	v_lshl_add_u64 v[182:183], s[24:25], 0, v[138:139]
	s_add_i32 m0, s7, 0xe000
	s_nop 0
	global_load_lds_dwordx4 v[182:183], off
	s_waitcnt vmcnt(8)
	s_waitcnt lgkmcnt(0)
	s_barrier
	v_mfma_f32_16x16x32_bf16 v[126:129], v[140:143], v[178:181], v[126:129]
	v_mfma_f32_16x16x32_bf16 v[122:125], v[154:157], v[178:181], v[122:125]
	v_mfma_f32_16x16x32_bf16 v[110:113], v[140:143], v[194:197], v[110:113]
	v_mfma_f32_16x16x32_bf16 v[106:109], v[154:157], v[194:197], v[106:109]
	v_mfma_f32_16x16x32_bf16 v[94:97], v[140:143], v[218:221], v[94:97]
	v_mfma_f32_16x16x32_bf16 v[90:93], v[154:157], v[218:221], v[90:93]
	v_mfma_f32_16x16x32_bf16 v[78:81], v[140:143], v[226:229], v[78:81]
	v_mfma_f32_16x16x32_bf16 v[74:77], v[154:157], v[226:229], v[74:77]
	v_mfma_f32_16x16x32_bf16 v[126:129], v[150:153], v[190:193], v[126:129]
	v_mfma_f32_16x16x32_bf16 v[122:125], v[158:161], v[190:193], v[122:125]
	v_mfma_f32_16x16x32_bf16 v[110:113], v[150:153], v[214:217], v[110:113]
	v_mfma_f32_16x16x32_bf16 v[106:109], v[158:161], v[214:217], v[106:109]
	v_mfma_f32_16x16x32_bf16 v[94:97], v[150:153], v[222:225], v[94:97]
	v_mfma_f32_16x16x32_bf16 v[90:93], v[158:161], v[222:225], v[90:93]
	v_mfma_f32_16x16x32_bf16 v[78:81], v[150:153], v[230:233], v[78:81]
	v_mfma_f32_16x16x32_bf16 v[74:77], v[158:161], v[230:233], v[74:77]
	v_mfma_f32_16x16x32_bf16 v[118:121], v[162:165], v[178:181], v[118:121]
	v_mfma_f32_16x16x32_bf16 v[114:117], v[170:173], v[178:181], v[114:117]
	v_mfma_f32_16x16x32_bf16 v[102:105], v[162:165], v[194:197], v[102:105]
	v_mfma_f32_16x16x32_bf16 v[98:101], v[170:173], v[194:197], v[98:101]
	v_mfma_f32_16x16x32_bf16 v[86:89], v[162:165], v[218:221], v[86:89]
	v_mfma_f32_16x16x32_bf16 v[82:85], v[170:173], v[218:221], v[82:85]
	v_mfma_f32_16x16x32_bf16 v[70:73], v[162:165], v[226:229], v[70:73]
	v_mfma_f32_16x16x32_bf16 v[66:69], v[170:173], v[226:229], v[66:69]
	v_mfma_f32_16x16x32_bf16 v[118:121], v[166:169], v[190:193], v[118:121]
	v_mfma_f32_16x16x32_bf16 v[114:117], v[174:177], v[190:193], v[114:117]
	v_mfma_f32_16x16x32_bf16 v[102:105], v[166:169], v[214:217], v[102:105]
	v_mfma_f32_16x16x32_bf16 v[98:101], v[174:177], v[214:217], v[98:101]
	v_mfma_f32_16x16x32_bf16 v[86:89], v[166:169], v[222:225], v[86:89]
	v_mfma_f32_16x16x32_bf16 v[82:85], v[174:177], v[222:225], v[82:85]
	v_mfma_f32_16x16x32_bf16 v[70:73], v[166:169], v[230:233], v[70:73]
	v_mfma_f32_16x16x32_bf16 v[66:69], v[174:177], v[230:233], v[66:69]
	s_barrier
	s_add_i32 s0, s48, s6
	v_lshl_add_u64 v[182:183], s[10:11], 0, v[0:1]
	s_mov_b32 m0, s0
	ds_read_b128 v[178:181], v149 offset:16384
	ds_read_b128 v[190:193], v149 offset:17408
	ds_read_b128 v[194:197], v149 offset:18432
	ds_read_b128 v[214:217], v149 offset:19456
	ds_read_b128 v[218:221], v149 offset:20480
	ds_read_b128 v[222:225], v149 offset:21504
	ds_read_b128 v[226:229], v149 offset:22528
	ds_read_b128 v[230:233], v149 offset:23552
	global_load_lds_dwordx4 v[182:183], off
	s_add_i32 m0, s0, 0x2000
	s_add_u32 s0, s10, 0x40000
	v_lshl_add_u64 v[234:235], s[10:11], 0, v[134:135]
	s_addc_u32 s1, s11, 0
	s_add_i32 s48, s49, s6
	global_load_lds_dwordx4 v[234:235], off
	v_lshl_add_u64 v[236:237], s[0:1], 0, v[0:1]
	s_mov_b32 m0, s48
	v_lshl_add_u64 v[238:239], s[26:27], 0, v[132:133]
	global_load_lds_dwordx4 v[236:237], off
	v_lshl_add_u64 v[236:237], s[0:1], 0, v[134:135]
	s_add_i32 m0, s48, 0x2000
	s_nop 0
	global_load_lds_dwordx4 v[236:237], off
	v_lshl_add_u64 v[236:237], s[26:27], 0, v[130:131]
	s_mov_b32 m0, s7
	s_nop 0
	global_load_lds_dwordx4 v[236:237], off
	s_mov_b32 m0, s28
	s_nop 0
	global_load_lds_dwordx4 v[238:239], off
	s_waitcnt vmcnt(8)
	s_waitcnt lgkmcnt(0)
	s_barrier
	v_mfma_f32_16x16x32_bf16 v[62:65], v[140:143], v[178:181], v[62:65]
	v_mfma_f32_16x16x32_bf16 v[58:61], v[154:157], v[178:181], v[58:61]
	v_mfma_f32_16x16x32_bf16 v[46:49], v[140:143], v[194:197], v[46:49]
	v_mfma_f32_16x16x32_bf16 v[42:45], v[154:157], v[194:197], v[42:45]
	v_mfma_f32_16x16x32_bf16 v[30:33], v[140:143], v[218:221], v[30:33]
	v_mfma_f32_16x16x32_bf16 v[26:29], v[154:157], v[218:221], v[26:29]
	v_mfma_f32_16x16x32_bf16 v[14:17], v[140:143], v[226:229], v[14:17]
	v_mfma_f32_16x16x32_bf16 v[10:13], v[154:157], v[226:229], v[10:13]
	v_mfma_f32_16x16x32_bf16 v[62:65], v[150:153], v[190:193], v[62:65]
	v_mfma_f32_16x16x32_bf16 v[58:61], v[158:161], v[190:193], v[58:61]
	v_mfma_f32_16x16x32_bf16 v[46:49], v[150:153], v[214:217], v[46:49]
	v_mfma_f32_16x16x32_bf16 v[42:45], v[158:161], v[214:217], v[42:45]
	v_mfma_f32_16x16x32_bf16 v[30:33], v[150:153], v[222:225], v[30:33]
	v_mfma_f32_16x16x32_bf16 v[26:29], v[158:161], v[222:225], v[26:29]
	v_mfma_f32_16x16x32_bf16 v[14:17], v[150:153], v[230:233], v[14:17]
	v_mfma_f32_16x16x32_bf16 v[10:13], v[158:161], v[230:233], v[10:13]
	v_mfma_f32_16x16x32_bf16 v[54:57], v[162:165], v[178:181], v[54:57]
	v_mfma_f32_16x16x32_bf16 v[50:53], v[170:173], v[178:181], v[50:53]
	v_mfma_f32_16x16x32_bf16 v[38:41], v[162:165], v[194:197], v[38:41]
	v_mfma_f32_16x16x32_bf16 v[34:37], v[170:173], v[194:197], v[34:37]
	v_mfma_f32_16x16x32_bf16 v[22:25], v[162:165], v[218:221], v[22:25]
	v_mfma_f32_16x16x32_bf16 v[18:21], v[170:173], v[218:221], v[18:21]
	v_mfma_f32_16x16x32_bf16 v[6:9], v[162:165], v[226:229], v[6:9]
	v_mfma_f32_16x16x32_bf16 v[2:5], v[170:173], v[226:229], v[2:5]
	v_mfma_f32_16x16x32_bf16 v[54:57], v[166:169], v[190:193], v[54:57]
	v_mfma_f32_16x16x32_bf16 v[50:53], v[174:177], v[190:193], v[50:53]
	v_mfma_f32_16x16x32_bf16 v[38:41], v[166:169], v[214:217], v[38:41]
	v_mfma_f32_16x16x32_bf16 v[34:37], v[174:177], v[214:217], v[34:37]
	v_mfma_f32_16x16x32_bf16 v[22:25], v[166:169], v[222:225], v[22:25]
	v_mfma_f32_16x16x32_bf16 v[18:21], v[174:177], v[222:225], v[18:21]
	v_mfma_f32_16x16x32_bf16 v[6:9], v[166:169], v[230:233], v[6:9]
	v_mfma_f32_16x16x32_bf16 v[2:5], v[174:177], v[230:233], v[2:5]
	s_barrier
	s_add_i32 s48, 0, 0x18000
	s_add_i32 s49, 0, 0x1c000
	v_add_u32_e32 v158, s48, v146
	v_add_u32_e32 v174, s49, v146
	ds_read_b128 v[140:143], v158
	ds_read_b128 v[150:153], v158 offset:1024
	ds_read_b128 v[154:157], v158 offset:2048
	ds_read_b128 v[158:161], v158 offset:3072
	ds_read_b128 v[162:165], v174
	ds_read_b128 v[166:169], v174 offset:1024
	ds_read_b128 v[170:173], v174 offset:2048
	ds_read_b128 v[174:177], v174 offset:3072
	s_add_u32 s0, s26, 0x40000
	s_addc_u32 s1, s27, 0
	s_mov_b32 m0, s29
	v_lshl_add_u64 v[240:241], s[0:1], 0, v[130:131]
	ds_read_b128 v[178:181], v149 offset:32768
	ds_read_b128 v[190:193], v149 offset:33792
	ds_read_b128 v[194:197], v149 offset:34816
	ds_read_b128 v[214:217], v149 offset:35840
	ds_read_b128 v[218:221], v149 offset:36864
	ds_read_b128 v[222:225], v149 offset:37888
	ds_read_b128 v[226:229], v149 offset:38912
	ds_read_b128 v[230:233], v149 offset:39936
	global_load_lds_dwordx4 v[240:241], off
	v_lshl_add_u64 v[240:241], s[0:1], 0, v[132:133]
	s_mov_b32 m0, s36
	s_nop 0
	global_load_lds_dwordx4 v[240:241], off
	s_waitcnt vmcnt(8)
	s_waitcnt lgkmcnt(0)
	s_barrier
	v_mfma_f32_16x16x32_bf16 v[126:129], v[140:143], v[178:181], v[126:129]
	v_mfma_f32_16x16x32_bf16 v[122:125], v[154:157], v[178:181], v[122:125]
	v_mfma_f32_16x16x32_bf16 v[110:113], v[140:143], v[194:197], v[110:113]
	v_mfma_f32_16x16x32_bf16 v[106:109], v[154:157], v[194:197], v[106:109]
	v_mfma_f32_16x16x32_bf16 v[94:97], v[140:143], v[218:221], v[94:97]
	v_mfma_f32_16x16x32_bf16 v[90:93], v[154:157], v[218:221], v[90:93]
	v_mfma_f32_16x16x32_bf16 v[78:81], v[140:143], v[226:229], v[78:81]
	v_mfma_f32_16x16x32_bf16 v[74:77], v[154:157], v[226:229], v[74:77]
	v_mfma_f32_16x16x32_bf16 v[126:129], v[150:153], v[190:193], v[126:129]
	v_mfma_f32_16x16x32_bf16 v[122:125], v[158:161], v[190:193], v[122:125]
	v_mfma_f32_16x16x32_bf16 v[110:113], v[150:153], v[214:217], v[110:113]
	v_mfma_f32_16x16x32_bf16 v[106:109], v[158:161], v[214:217], v[106:109]
	v_mfma_f32_16x16x32_bf16 v[94:97], v[150:153], v[222:225], v[94:97]
	v_mfma_f32_16x16x32_bf16 v[90:93], v[158:161], v[222:225], v[90:93]
	v_mfma_f32_16x16x32_bf16 v[78:81], v[150:153], v[230:233], v[78:81]
	v_mfma_f32_16x16x32_bf16 v[74:77], v[158:161], v[230:233], v[74:77]
	v_mfma_f32_16x16x32_bf16 v[118:121], v[162:165], v[178:181], v[118:121]
	v_mfma_f32_16x16x32_bf16 v[114:117], v[170:173], v[178:181], v[114:117]
	v_mfma_f32_16x16x32_bf16 v[102:105], v[162:165], v[194:197], v[102:105]
	v_mfma_f32_16x16x32_bf16 v[98:101], v[170:173], v[194:197], v[98:101]
	v_mfma_f32_16x16x32_bf16 v[86:89], v[162:165], v[218:221], v[86:89]
	v_mfma_f32_16x16x32_bf16 v[82:85], v[170:173], v[218:221], v[82:85]
	v_mfma_f32_16x16x32_bf16 v[70:73], v[162:165], v[226:229], v[70:73]
	v_mfma_f32_16x16x32_bf16 v[66:69], v[170:173], v[226:229], v[66:69]
	v_mfma_f32_16x16x32_bf16 v[118:121], v[166:169], v[190:193], v[118:121]
	v_mfma_f32_16x16x32_bf16 v[114:117], v[174:177], v[190:193], v[114:117]
	v_mfma_f32_16x16x32_bf16 v[102:105], v[166:169], v[214:217], v[102:105]
	v_mfma_f32_16x16x32_bf16 v[98:101], v[174:177], v[214:217], v[98:101]
	v_mfma_f32_16x16x32_bf16 v[86:89], v[166:169], v[222:225], v[86:89]
	v_mfma_f32_16x16x32_bf16 v[82:85], v[174:177], v[222:225], v[82:85]
	v_mfma_f32_16x16x32_bf16 v[70:73], v[166:169], v[230:233], v[70:73]
	v_mfma_f32_16x16x32_bf16 v[66:69], v[174:177], v[230:233], v[66:69]
	s_barrier
	s_add_i32 s0, s48, s6
	v_lshl_add_u64 v[182:183], v[182:183], 0, s[96:97]
	s_mov_b32 m0, s0
	ds_read_b128 v[178:181], v149 offset:49152
	ds_read_b128 v[190:193], v149 offset:50176
	ds_read_b128 v[194:197], v149 offset:51200
	ds_read_b128 v[214:217], v149 offset:52224
	ds_read_b128 v[218:221], v149 offset:53248
	ds_read_b128 v[222:225], v149 offset:54272
	ds_read_b128 v[226:229], v149 offset:55296
	ds_read_b128 v[230:233], v149 offset:56320
	global_load_lds_dwordx4 v[182:183], off
	s_add_i32 m0, s0, 0x2000
	s_add_u32 s0, s10, 0x40080
	v_lshl_add_u64 v[182:183], v[234:235], 0, s[96:97]
	s_addc_u32 s1, s11, 0
	s_add_i32 s10, s49, s6
	global_load_lds_dwordx4 v[182:183], off
	v_lshl_add_u64 v[182:183], s[0:1], 0, v[0:1]
	s_mov_b32 m0, s10
	s_nop 0
	global_load_lds_dwordx4 v[182:183], off
	v_lshl_add_u64 v[182:183], s[0:1], 0, v[134:135]
	s_add_i32 m0, s10, 0x2000
	s_nop 0
	global_load_lds_dwordx4 v[182:183], off
	v_lshl_add_u64 v[182:183], v[236:237], 0, s[96:97]
	s_mov_b32 m0, s37
	s_nop 0
	global_load_lds_dwordx4 v[182:183], off
	v_lshl_add_u64 v[182:183], v[238:239], 0, s[96:97]
	s_mov_b32 m0, s38
	s_nop 0
	global_load_lds_dwordx4 v[182:183], off
	s_waitcnt vmcnt(8)
	s_waitcnt lgkmcnt(0)
	s_barrier
	v_mfma_f32_16x16x32_bf16 v[62:65], v[140:143], v[178:181], v[62:65]
	v_mfma_f32_16x16x32_bf16 v[58:61], v[154:157], v[178:181], v[58:61]
	v_mfma_f32_16x16x32_bf16 v[46:49], v[140:143], v[194:197], v[46:49]
	v_mfma_f32_16x16x32_bf16 v[42:45], v[154:157], v[194:197], v[42:45]
	v_mfma_f32_16x16x32_bf16 v[30:33], v[140:143], v[218:221], v[30:33]
	v_mfma_f32_16x16x32_bf16 v[26:29], v[154:157], v[218:221], v[26:29]
	v_mfma_f32_16x16x32_bf16 v[14:17], v[140:143], v[226:229], v[14:17]
	v_mfma_f32_16x16x32_bf16 v[10:13], v[154:157], v[226:229], v[10:13]
	v_mfma_f32_16x16x32_bf16 v[62:65], v[150:153], v[190:193], v[62:65]
	v_mfma_f32_16x16x32_bf16 v[58:61], v[158:161], v[190:193], v[58:61]
	v_mfma_f32_16x16x32_bf16 v[46:49], v[150:153], v[214:217], v[46:49]
	v_mfma_f32_16x16x32_bf16 v[42:45], v[158:161], v[214:217], v[42:45]
	v_mfma_f32_16x16x32_bf16 v[30:33], v[150:153], v[222:225], v[30:33]
	v_mfma_f32_16x16x32_bf16 v[26:29], v[158:161], v[222:225], v[26:29]
	v_mfma_f32_16x16x32_bf16 v[14:17], v[150:153], v[230:233], v[14:17]
	v_mfma_f32_16x16x32_bf16 v[10:13], v[158:161], v[230:233], v[10:13]
	v_mfma_f32_16x16x32_bf16 v[54:57], v[162:165], v[178:181], v[54:57]
	v_mfma_f32_16x16x32_bf16 v[50:53], v[170:173], v[178:181], v[50:53]
	v_mfma_f32_16x16x32_bf16 v[38:41], v[162:165], v[194:197], v[38:41]
	v_mfma_f32_16x16x32_bf16 v[34:37], v[170:173], v[194:197], v[34:37]
	v_mfma_f32_16x16x32_bf16 v[22:25], v[162:165], v[218:221], v[22:25]
	v_mfma_f32_16x16x32_bf16 v[18:21], v[170:173], v[218:221], v[18:21]
	v_mfma_f32_16x16x32_bf16 v[6:9], v[162:165], v[226:229], v[6:9]
	v_mfma_f32_16x16x32_bf16 v[2:5], v[170:173], v[226:229], v[2:5]
	v_mfma_f32_16x16x32_bf16 v[54:57], v[166:169], v[190:193], v[54:57]
	v_mfma_f32_16x16x32_bf16 v[50:53], v[174:177], v[190:193], v[50:53]
	v_mfma_f32_16x16x32_bf16 v[38:41], v[166:169], v[214:217], v[38:41]
	v_mfma_f32_16x16x32_bf16 v[34:37], v[174:177], v[214:217], v[34:37]
	v_mfma_f32_16x16x32_bf16 v[22:25], v[166:169], v[222:225], v[22:25]
	v_mfma_f32_16x16x32_bf16 v[18:21], v[174:177], v[222:225], v[18:21]
	v_mfma_f32_16x16x32_bf16 v[6:9], v[166:169], v[230:233], v[6:9]
	v_mfma_f32_16x16x32_bf16 v[2:5], v[174:177], v[230:233], v[2:5]
	s_barrier
	s_add_i32 s57, s57, 2
	s_add_u32 s24, s24, 0x100
	s_addc_u32 s25, s25, 0
	s_add_u32 s47, s47, 0x100
	s_addc_u32 s56, s56, 0
	s_cmp_gt_u32 s57, 13
	s_cbranch_scc0 .LBB11_1869
	s_and_b64 vcc, exec, s[16:17]
	s_cbranch_vccz .LBB11_1872
	s_barrier

.LBB11_2045:
	s_add_u32 s40, s26, s34
	s_addc_u32 s41, s27, s35
	s_add_u32 s36, s40, 0x100
	s_addc_u32 s37, s41, 0
	s_and_b64 s[0:1], s[10:11], exec
	s_cselect_b32 s37, s7, s37
	s_cselect_b32 s36, s8, s36
	s_add_u32 s0, s24, s34
	s_addc_u32 s1, s25, s35
	s_add_u32 s34, s0, 0x100
	s_addc_u32 s35, s1, 0
	s_add_i32 s51, 0, 0x10000
	s_and_b64 s[0:1], s[10:11], exec
	s_cselect_b32 s39, s9, s35
	s_cselect_b32 s38, s68, s34
	s_add_i32 s0, 0, 0x14000
	s_add_u32 s42, s40, 0x40080
	s_addc_u32 s43, s41, 0
	s_add_i32 vcc_hi, s51, s46
	s_add_i32 m0, s47, 0xc000
	s_add_i32 s1, s47, 0xe000
	s_add_i32 s50, vcc_hi, 0x2000
	v_add_u32_e32 v136, s51, v139
	s_add_u32 s40, s38, 0x40000
	ds_read_b128 v[142:145], v136
	ds_read_b128 v[146:149], v136 offset:1024
	ds_read_b128 v[150:153], v136 offset:2048
	ds_read_b128 v[154:157], v136 offset:3072
	v_add_u32_e32 v136, s0, v139
	s_addc_u32 s41, s39, 0
	s_add_i32 s49, s0, s46
	ds_read_b128 v[158:161], v136
	ds_read_b128 v[162:165], v136 offset:1024
	ds_read_b128 v[166:169], v136 offset:2048
	ds_read_b128 v[170:173], v136 offset:3072
	s_add_i32 s48, s49, 0x2000
	s_add_i32 vcc_lo, 0, 0x18000
	s_add_i32 s71, 0, 0x1c000
	s_add_u32 s34, s36, 0x40000
	s_addc_u32 s35, s37, 0
	s_add_i32 s70, vcc_lo, s46
	s_add_i32 s69, s70, 0x2000
	s_add_u32 s10, s38, 0x40080
	s_addc_u32 s11, s39, 0
	s_add_i32 s51, s71, s46
	s_add_i32 s0, s51, 0x2000
	v_lshl_add_u64 v[136:137], s[42:43], 0, v[134:135]
	ds_read_b128 v[174:177], v141
	ds_read_b128 v[178:181], v141 offset:1024
	ds_read_b128 v[190:193], v141 offset:2048
	ds_read_b128 v[194:197], v141 offset:3072
	ds_read_b128 v[214:217], v141 offset:4096
	ds_read_b128 v[218:221], v141 offset:5120
	ds_read_b128 v[222:225], v141 offset:6144
	ds_read_b128 v[226:229], v141 offset:7168
	global_load_lds_dwordx4 v[136:137], off
	v_lshl_add_u64 v[136:137], s[42:43], 0, v[132:133]
	s_mov_b32 m0, s1
	s_nop 0
	global_load_lds_dwordx4 v[136:137], off
	s_waitcnt vmcnt(8)
	s_waitcnt lgkmcnt(0)
	s_barrier
	v_mfma_f32_16x16x32_bf16 v[126:129], v[142:145], v[174:177], v[126:129]
	v_mfma_f32_16x16x32_bf16 v[122:125], v[150:153], v[174:177], v[122:125]
	v_mfma_f32_16x16x32_bf16 v[110:113], v[142:145], v[190:193], v[110:113]
	v_mfma_f32_16x16x32_bf16 v[106:109], v[150:153], v[190:193], v[106:109]
	v_mfma_f32_16x16x32_bf16 v[94:97], v[142:145], v[214:217], v[94:97]
	v_mfma_f32_16x16x32_bf16 v[90:93], v[150:153], v[214:217], v[90:93]
	v_mfma_f32_16x16x32_bf16 v[78:81], v[142:145], v[222:225], v[78:81]
	v_mfma_f32_16x16x32_bf16 v[74:77], v[150:153], v[222:225], v[74:77]
	v_mfma_f32_16x16x32_bf16 v[126:129], v[146:149], v[178:181], v[126:129]
	v_mfma_f32_16x16x32_bf16 v[122:125], v[154:157], v[178:181], v[122:125]
	v_mfma_f32_16x16x32_bf16 v[110:113], v[146:149], v[194:197], v[110:113]
	v_mfma_f32_16x16x32_bf16 v[106:109], v[154:157], v[194:197], v[106:109]
	v_mfma_f32_16x16x32_bf16 v[94:97], v[146:149], v[218:221], v[94:97]
	v_mfma_f32_16x16x32_bf16 v[90:93], v[154:157], v[218:221], v[90:93]
	v_mfma_f32_16x16x32_bf16 v[78:81], v[146:149], v[226:229], v[78:81]
	v_mfma_f32_16x16x32_bf16 v[74:77], v[154:157], v[226:229], v[74:77]
	v_mfma_f32_16x16x32_bf16 v[118:121], v[158:161], v[174:177], v[118:121]
	v_mfma_f32_16x16x32_bf16 v[114:117], v[166:169], v[174:177], v[114:117]
	v_mfma_f32_16x16x32_bf16 v[102:105], v[158:161], v[190:193], v[102:105]
	v_mfma_f32_16x16x32_bf16 v[98:101], v[166:169], v[190:193], v[98:101]
	v_mfma_f32_16x16x32_bf16 v[86:89], v[158:161], v[214:217], v[86:89]
	v_mfma_f32_16x16x32_bf16 v[82:85], v[166:169], v[214:217], v[82:85]
	v_mfma_f32_16x16x32_bf16 v[70:73], v[158:161], v[222:225], v[70:73]
	v_mfma_f32_16x16x32_bf16 v[66:69], v[166:169], v[222:225], v[66:69]
	v_mfma_f32_16x16x32_bf16 v[118:121], v[162:165], v[178:181], v[118:121]
	v_mfma_f32_16x16x32_bf16 v[114:117], v[170:173], v[178:181], v[114:117]
	v_mfma_f32_16x16x32_bf16 v[102:105], v[162:165], v[194:197], v[102:105]
	v_mfma_f32_16x16x32_bf16 v[98:101], v[170:173], v[194:197], v[98:101]
	v_mfma_f32_16x16x32_bf16 v[86:89], v[162:165], v[218:221], v[86:89]
	v_mfma_f32_16x16x32_bf16 v[82:85], v[170:173], v[218:221], v[82:85]
	v_mfma_f32_16x16x32_bf16 v[70:73], v[162:165], v[226:229], v[70:73]
	v_mfma_f32_16x16x32_bf16 v[66:69], v[170:173], v[226:229], v[66:69]
	s_barrier
	s_mov_b32 m0, vcc_hi
	v_lshl_add_u64 v[136:137], s[38:39], 0, v[0:1]
	ds_read_b128 v[174:177], v141 offset:16384
	ds_read_b128 v[178:181], v141 offset:17408
	ds_read_b128 v[190:193], v141 offset:18432
	ds_read_b128 v[194:197], v141 offset:19456
	ds_read_b128 v[214:217], v141 offset:20480
	ds_read_b128 v[218:221], v141 offset:21504
	ds_read_b128 v[222:225], v141 offset:22528
	ds_read_b128 v[226:229], v141 offset:23552
	global_load_lds_dwordx4 v[136:137], off
	v_lshl_add_u64 v[182:183], s[38:39], 0, v[130:131]
	s_mov_b32 m0, s50
	v_lshl_add_u64 v[230:231], s[40:41], 0, v[0:1]
	global_load_lds_dwordx4 v[182:183], off
	s_mov_b32 m0, s49
	v_lshl_add_u64 v[232:233], s[36:37], 0, v[132:133]
	global_load_lds_dwordx4 v[230:231], off
	v_lshl_add_u64 v[230:231], s[40:41], 0, v[130:131]
	s_mov_b32 m0, s48
	s_nop 0
	global_load_lds_dwordx4 v[230:231], off
	v_lshl_add_u64 v[230:231], s[36:37], 0, v[134:135]
	s_mov_b32 m0, s47
	s_nop 0
	global_load_lds_dwordx4 v[230:231], off
	s_mov_b32 m0, s56
	s_nop 0
	global_load_lds_dwordx4 v[232:233], off
	s_waitcnt vmcnt(8)
	s_waitcnt lgkmcnt(0)
	s_barrier
	v_mfma_f32_16x16x32_bf16 v[62:65], v[142:145], v[174:177], v[62:65]
	v_mfma_f32_16x16x32_bf16 v[58:61], v[150:153], v[174:177], v[58:61]
	v_mfma_f32_16x16x32_bf16 v[46:49], v[142:145], v[190:193], v[46:49]
	v_mfma_f32_16x16x32_bf16 v[42:45], v[150:153], v[190:193], v[42:45]
	v_mfma_f32_16x16x32_bf16 v[30:33], v[142:145], v[214:217], v[30:33]
	v_mfma_f32_16x16x32_bf16 v[26:29], v[150:153], v[214:217], v[26:29]
	v_mfma_f32_16x16x32_bf16 v[14:17], v[142:145], v[222:225], v[14:17]
	v_mfma_f32_16x16x32_bf16 v[10:13], v[150:153], v[222:225], v[10:13]
	v_mfma_f32_16x16x32_bf16 v[62:65], v[146:149], v[178:181], v[62:65]
	v_mfma_f32_16x16x32_bf16 v[58:61], v[154:157], v[178:181], v[58:61]
	v_mfma_f32_16x16x32_bf16 v[46:49], v[146:149], v[194:197], v[46:49]
	v_mfma_f32_16x16x32_bf16 v[42:45], v[154:157], v[194:197], v[42:45]
	v_mfma_f32_16x16x32_bf16 v[30:33], v[146:149], v[218:221], v[30:33]
	v_mfma_f32_16x16x32_bf16 v[26:29], v[154:157], v[218:221], v[26:29]
	v_mfma_f32_16x16x32_bf16 v[14:17], v[146:149], v[226:229], v[14:17]
	v_mfma_f32_16x16x32_bf16 v[10:13], v[154:157], v[226:229], v[10:13]
	v_mfma_f32_16x16x32_bf16 v[54:57], v[158:161], v[174:177], v[54:57]
	v_mfma_f32_16x16x32_bf16 v[50:53], v[166:169], v[174:177], v[50:53]
	v_mfma_f32_16x16x32_bf16 v[38:41], v[158:161], v[190:193], v[38:41]
	v_mfma_f32_16x16x32_bf16 v[34:37], v[166:169], v[190:193], v[34:37]
	v_mfma_f32_16x16x32_bf16 v[22:25], v[158:161], v[214:217], v[22:25]
	v_mfma_f32_16x16x32_bf16 v[18:21], v[166:169], v[214:217], v[18:21]
	v_mfma_f32_16x16x32_bf16 v[6:9], v[158:161], v[222:225], v[6:9]
	v_mfma_f32_16x16x32_bf16 v[2:5], v[166:169], v[222:225], v[2:5]
	v_mfma_f32_16x16x32_bf16 v[54:57], v[162:165], v[178:181], v[54:57]
	v_mfma_f32_16x16x32_bf16 v[50:53], v[170:173], v[178:181], v[50:53]
	v_mfma_f32_16x16x32_bf16 v[38:41], v[162:165], v[194:197], v[38:41]
	v_mfma_f32_16x16x32_bf16 v[34:37], v[170:173], v[194:197], v[34:37]
	v_mfma_f32_16x16x32_bf16 v[22:25], v[162:165], v[218:221], v[22:25]
	v_mfma_f32_16x16x32_bf16 v[18:21], v[170:173], v[218:221], v[18:21]
	v_mfma_f32_16x16x32_bf16 v[6:9], v[162:165], v[226:229], v[6:9]
	v_mfma_f32_16x16x32_bf16 v[2:5], v[170:173], v[226:229], v[2:5]
	s_barrier
	v_add_u32_e32 v154, vcc_lo, v139
	v_add_u32_e32 v170, s71, v139
	ds_read_b128 v[142:145], v154
	ds_read_b128 v[146:149], v154 offset:1024
	ds_read_b128 v[150:153], v154 offset:2048
	ds_read_b128 v[154:157], v154 offset:3072
	ds_read_b128 v[158:161], v170
	ds_read_b128 v[162:165], v170 offset:1024
	ds_read_b128 v[166:169], v170 offset:2048
	ds_read_b128 v[170:173], v170 offset:3072
	s_mov_b32 m0, s57
	v_lshl_add_u64 v[234:235], s[34:35], 0, v[134:135]
	ds_read_b128 v[174:177], v141 offset:32768
	ds_read_b128 v[178:181], v141 offset:33792
	ds_read_b128 v[190:193], v141 offset:34816
	ds_read_b128 v[194:197], v141 offset:35840
	ds_read_b128 v[214:217], v141 offset:36864
	ds_read_b128 v[218:221], v141 offset:37888
	ds_read_b128 v[222:225], v141 offset:38912
	ds_read_b128 v[226:229], v141 offset:39936
	global_load_lds_dwordx4 v[234:235], off
	v_lshl_add_u64 v[234:235], s[34:35], 0, v[132:133]
	s_mov_b32 m0, s58
	s_nop 0
	global_load_lds_dwordx4 v[234:235], off
	s_waitcnt vmcnt(8)
	s_waitcnt lgkmcnt(0)
	s_barrier
	v_mfma_f32_16x16x32_bf16 v[126:129], v[142:145], v[174:177], v[126:129]
	v_mfma_f32_16x16x32_bf16 v[122:125], v[150:153], v[174:177], v[122:125]
	v_mfma_f32_16x16x32_bf16 v[110:113], v[142:145], v[190:193], v[110:113]
	v_mfma_f32_16x16x32_bf16 v[106:109], v[150:153], v[190:193], v[106:109]
	v_mfma_f32_16x16x32_bf16 v[94:97], v[142:145], v[214:217], v[94:97]
	v_mfma_f32_16x16x32_bf16 v[90:93], v[150:153], v[214:217], v[90:93]
	v_mfma_f32_16x16x32_bf16 v[78:81], v[142:145], v[222:225], v[78:81]
	v_mfma_f32_16x16x32_bf16 v[74:77], v[150:153], v[222:225], v[74:77]
	v_mfma_f32_16x16x32_bf16 v[126:129], v[146:149], v[178:181], v[126:129]
	v_mfma_f32_16x16x32_bf16 v[122:125], v[154:157], v[178:181], v[122:125]
	v_mfma_f32_16x16x32_bf16 v[110:113], v[146:149], v[194:197], v[110:113]
	v_mfma_f32_16x16x32_bf16 v[106:109], v[154:157], v[194:197], v[106:109]
	v_mfma_f32_16x16x32_bf16 v[94:97], v[146:149], v[218:221], v[94:97]
	v_mfma_f32_16x16x32_bf16 v[90:93], v[154:157], v[218:221], v[90:93]
	v_mfma_f32_16x16x32_bf16 v[78:81], v[146:149], v[226:229], v[78:81]
	v_mfma_f32_16x16x32_bf16 v[74:77], v[154:157], v[226:229], v[74:77]
	v_mfma_f32_16x16x32_bf16 v[118:121], v[158:161], v[174:177], v[118:121]
	v_mfma_f32_16x16x32_bf16 v[114:117], v[166:169], v[174:177], v[114:117]
	v_mfma_f32_16x16x32_bf16 v[102:105], v[158:161], v[190:193], v[102:105]
	v_mfma_f32_16x16x32_bf16 v[98:101], v[166:169], v[190:193], v[98:101]
	v_mfma_f32_16x16x32_bf16 v[86:89], v[158:161], v[214:217], v[86:89]
	v_mfma_f32_16x16x32_bf16 v[82:85], v[166:169], v[214:217], v[82:85]
	v_mfma_f32_16x16x32_bf16 v[70:73], v[158:161], v[222:225], v[70:73]
	v_mfma_f32_16x16x32_bf16 v[66:69], v[166:169], v[222:225], v[66:69]
	v_mfma_f32_16x16x32_bf16 v[118:121], v[162:165], v[178:181], v[118:121]
	v_mfma_f32_16x16x32_bf16 v[114:117], v[170:173], v[178:181], v[114:117]
	v_mfma_f32_16x16x32_bf16 v[102:105], v[162:165], v[194:197], v[102:105]
	v_mfma_f32_16x16x32_bf16 v[98:101], v[170:173], v[194:197], v[98:101]
	v_mfma_f32_16x16x32_bf16 v[86:89], v[162:165], v[218:221], v[86:89]
	v_mfma_f32_16x16x32_bf16 v[82:85], v[170:173], v[218:221], v[82:85]
	v_mfma_f32_16x16x32_bf16 v[70:73], v[162:165], v[226:229], v[70:73]
	v_mfma_f32_16x16x32_bf16 v[66:69], v[170:173], v[226:229], v[66:69]
	s_barrier
	s_mov_b32 m0, s70
	v_lshl_add_u64 v[136:137], v[136:137], 0, s[96:97]
	ds_read_b128 v[174:177], v141 offset:49152
	ds_read_b128 v[178:181], v141 offset:50176
	ds_read_b128 v[190:193], v141 offset:51200
	ds_read_b128 v[194:197], v141 offset:52224
	ds_read_b128 v[214:217], v141 offset:53248
	ds_read_b128 v[218:221], v141 offset:54272
	ds_read_b128 v[222:225], v141 offset:55296
	ds_read_b128 v[226:229], v141 offset:56320
	global_load_lds_dwordx4 v[136:137], off
	v_lshl_add_u64 v[136:137], v[182:183], 0, s[96:97]
	s_mov_b32 m0, s69
	s_nop 0
	global_load_lds_dwordx4 v[136:137], off
	v_lshl_add_u64 v[136:137], s[10:11], 0, v[0:1]
	s_mov_b32 m0, s51
	s_nop 0
	global_load_lds_dwordx4 v[136:137], off
	v_lshl_add_u64 v[136:137], s[10:11], 0, v[130:131]
	s_mov_b32 m0, s0
	s_nop 0
	global_load_lds_dwordx4 v[136:137], off
	v_lshl_add_u64 v[136:137], v[230:231], 0, s[96:97]
	s_mov_b32 m0, s59
	s_nop 0
	global_load_lds_dwordx4 v[136:137], off
	v_lshl_add_u64 v[136:137], v[232:233], 0, s[96:97]
	s_mov_b32 m0, s60
	s_nop 0
	global_load_lds_dwordx4 v[136:137], off
	s_waitcnt vmcnt(8)
	s_waitcnt lgkmcnt(0)
	s_barrier
	v_mfma_f32_16x16x32_bf16 v[62:65], v[142:145], v[174:177], v[62:65]
	v_mfma_f32_16x16x32_bf16 v[58:61], v[150:153], v[174:177], v[58:61]
	v_mfma_f32_16x16x32_bf16 v[46:49], v[142:145], v[190:193], v[46:49]
	v_mfma_f32_16x16x32_bf16 v[42:45], v[150:153], v[190:193], v[42:45]
	v_mfma_f32_16x16x32_bf16 v[30:33], v[142:145], v[214:217], v[30:33]
	v_mfma_f32_16x16x32_bf16 v[26:29], v[150:153], v[214:217], v[26:29]
	v_mfma_f32_16x16x32_bf16 v[14:17], v[142:145], v[222:225], v[14:17]
	v_mfma_f32_16x16x32_bf16 v[10:13], v[150:153], v[222:225], v[10:13]
	v_mfma_f32_16x16x32_bf16 v[62:65], v[146:149], v[178:181], v[62:65]
	v_mfma_f32_16x16x32_bf16 v[58:61], v[154:157], v[178:181], v[58:61]
	v_mfma_f32_16x16x32_bf16 v[46:49], v[146:149], v[194:197], v[46:49]
	v_mfma_f32_16x16x32_bf16 v[42:45], v[154:157], v[194:197], v[42:45]
	v_mfma_f32_16x16x32_bf16 v[30:33], v[146:149], v[218:221], v[30:33]
	v_mfma_f32_16x16x32_bf16 v[26:29], v[154:157], v[218:221], v[26:29]
	v_mfma_f32_16x16x32_bf16 v[14:17], v[146:149], v[226:229], v[14:17]
	v_mfma_f32_16x16x32_bf16 v[10:13], v[154:157], v[226:229], v[10:13]
	v_mfma_f32_16x16x32_bf16 v[54:57], v[158:161], v[174:177], v[54:57]
	v_mfma_f32_16x16x32_bf16 v[50:53], v[166:169], v[174:177], v[50:53]
	v_mfma_f32_16x16x32_bf16 v[38:41], v[158:161], v[190:193], v[38:41]
	v_mfma_f32_16x16x32_bf16 v[34:37], v[166:169], v[190:193], v[34:37]
	v_mfma_f32_16x16x32_bf16 v[22:25], v[158:161], v[214:217], v[22:25]
	v_mfma_f32_16x16x32_bf16 v[18:21], v[166:169], v[214:217], v[18:21]
	v_mfma_f32_16x16x32_bf16 v[6:9], v[158:161], v[222:225], v[6:9]
	v_mfma_f32_16x16x32_bf16 v[2:5], v[166:169], v[222:225], v[2:5]
	v_mfma_f32_16x16x32_bf16 v[54:57], v[162:165], v[178:181], v[54:57]
	v_mfma_f32_16x16x32_bf16 v[50:53], v[170:173], v[178:181], v[50:53]
	v_mfma_f32_16x16x32_bf16 v[38:41], v[162:165], v[194:197], v[38:41]
	v_mfma_f32_16x16x32_bf16 v[34:37], v[170:173], v[194:197], v[34:37]
	v_mfma_f32_16x16x32_bf16 v[22:25], v[162:165], v[218:221], v[22:25]
	v_mfma_f32_16x16x32_bf16 v[18:21], v[170:173], v[218:221], v[18:21]
	v_mfma_f32_16x16x32_bf16 v[6:9], v[162:165], v[226:229], v[6:9]
	v_mfma_f32_16x16x32_bf16 v[2:5], v[170:173], v[226:229], v[2:5]
	s_barrier
	s_andn2_b64 vcc, exec, s[30:31]
	s_mov_b64 s[10:11], -1
	s_mov_b64 s[30:31], 0
	s_mov_b64 s[34:35], 0x100
	s_cbranch_vccz .LBB11_2045
	s_and_b64 vcc, exec, s[16:17]
	s_cbranch_vccz .LBB11_2048
	s_barrier

.LBB11_2093:
	s_add_u32 s36, s24, s28
	s_addc_u32 s37, s25, s29
	s_add_u32 s30, s36, 0x100
	s_addc_u32 s31, s37, 0
	s_and_b64 s[0:1], s[10:11], exec
	s_cselect_b32 s31, s58, s31
	s_cselect_b32 s30, s59, s30
	s_add_u32 s0, s22, s28
	s_addc_u32 s1, s23, s29
	s_add_u32 s28, s0, 0x100
	s_addc_u32 s29, s1, 0
	s_add_i32 s51, 0, 0x10000
	s_and_b64 s[0:1], s[10:11], exec
	s_cselect_b32 s35, s60, s29
	s_cselect_b32 s34, s68, s28
	s_add_i32 s0, 0, 0x14000
	s_add_u32 s38, s36, 0x40080
	s_addc_u32 s39, s37, 0
	s_add_i32 s50, s51, s40
	s_add_i32 m0, s41, 0xc000
	s_add_i32 s1, s41, 0xe000
	s_add_i32 s48, s50, 0x2000
	s_add_u32 s36, s34, 0x10000
	v_add_u32_e32 v152, s51, v141
	v_add_u32_e32 v168, s0, v141
	s_addc_u32 s37, s35, 0
	s_add_i32 s89, s0, s40
	ds_read_b128 v[136:139], v152
	ds_read_b128 v[144:147], v152 offset:1024
	ds_read_b128 v[148:151], v152 offset:2048
	ds_read_b128 v[152:155], v152 offset:3072
	ds_read_b128 v[156:159], v168
	ds_read_b128 v[160:163], v168 offset:1024
	ds_read_b128 v[164:167], v168 offset:2048
	ds_read_b128 v[168:171], v168 offset:3072
	s_add_i32 s49, s89, 0x2000
	s_add_i32 s88, 0, 0x18000
	s_add_i32 s71, 0, 0x1c000
	s_add_u32 s28, s30, 0x40000
	s_addc_u32 s29, s31, 0
	s_add_i32 s70, s88, s40
	s_add_i32 s69, s70, 0x2000
	s_add_u32 s10, s34, 0x10080
	s_addc_u32 s11, s35, 0
	s_add_i32 s0, s71, s40
	s_add_i32 s51, s0, 0x2000
	v_lshl_add_u64 v[226:227], s[38:39], 0, v[134:135]
	ds_read_b128 v[172:175], v143
	ds_read_b128 v[176:179], v143 offset:1024
	ds_read_b128 v[180:183], v143 offset:2048
	ds_read_b128 v[190:193], v143 offset:3072
	ds_read_b128 v[194:197], v143 offset:4096
	ds_read_b128 v[214:217], v143 offset:5120
	ds_read_b128 v[218:221], v143 offset:6144
	ds_read_b128 v[222:225], v143 offset:7168
	global_load_lds_dwordx4 v[226:227], off
	v_lshl_add_u64 v[226:227], s[38:39], 0, v[132:133]
	s_mov_b32 m0, s1
	s_nop 0
	global_load_lds_dwordx4 v[226:227], off
	s_waitcnt vmcnt(8)
	s_waitcnt lgkmcnt(0)
	s_barrier
	v_mfma_f32_16x16x32_bf16 v[126:129], v[136:139], v[172:175], v[126:129]
	v_mfma_f32_16x16x32_bf16 v[122:125], v[148:151], v[172:175], v[122:125]
	v_mfma_f32_16x16x32_bf16 v[114:117], v[136:139], v[180:183], v[114:117]
	v_mfma_f32_16x16x32_bf16 v[106:109], v[148:151], v[180:183], v[106:109]
	v_mfma_f32_16x16x32_bf16 v[98:101], v[136:139], v[194:197], v[98:101]
	v_mfma_f32_16x16x32_bf16 v[90:93], v[148:151], v[194:197], v[90:93]
	v_mfma_f32_16x16x32_bf16 v[82:85], v[136:139], v[218:221], v[82:85]
	v_mfma_f32_16x16x32_bf16 v[74:77], v[148:151], v[218:221], v[74:77]
	v_mfma_f32_16x16x32_bf16 v[126:129], v[144:147], v[176:179], v[126:129]
	v_mfma_f32_16x16x32_bf16 v[122:125], v[152:155], v[176:179], v[122:125]
	v_mfma_f32_16x16x32_bf16 v[114:117], v[144:147], v[190:193], v[114:117]
	v_mfma_f32_16x16x32_bf16 v[106:109], v[152:155], v[190:193], v[106:109]
	v_mfma_f32_16x16x32_bf16 v[98:101], v[144:147], v[214:217], v[98:101]
	v_mfma_f32_16x16x32_bf16 v[90:93], v[152:155], v[214:217], v[90:93]
	v_mfma_f32_16x16x32_bf16 v[82:85], v[144:147], v[222:225], v[82:85]
	v_mfma_f32_16x16x32_bf16 v[74:77], v[152:155], v[222:225], v[74:77]
	v_mfma_f32_16x16x32_bf16 v[118:121], v[156:159], v[172:175], v[118:121]
	v_mfma_f32_16x16x32_bf16 v[110:113], v[164:167], v[172:175], v[110:113]
	v_mfma_f32_16x16x32_bf16 v[102:105], v[156:159], v[180:183], v[102:105]
	v_mfma_f32_16x16x32_bf16 v[94:97], v[164:167], v[180:183], v[94:97]
	v_mfma_f32_16x16x32_bf16 v[86:89], v[156:159], v[194:197], v[86:89]
	v_mfma_f32_16x16x32_bf16 v[78:81], v[164:167], v[194:197], v[78:81]
	v_mfma_f32_16x16x32_bf16 v[70:73], v[156:159], v[218:221], v[70:73]
	v_mfma_f32_16x16x32_bf16 v[66:69], v[164:167], v[218:221], v[66:69]
	v_mfma_f32_16x16x32_bf16 v[118:121], v[160:163], v[176:179], v[118:121]
	v_mfma_f32_16x16x32_bf16 v[110:113], v[168:171], v[176:179], v[110:113]
	v_mfma_f32_16x16x32_bf16 v[102:105], v[160:163], v[190:193], v[102:105]
	v_mfma_f32_16x16x32_bf16 v[94:97], v[168:171], v[190:193], v[94:97]
	v_mfma_f32_16x16x32_bf16 v[86:89], v[160:163], v[214:217], v[86:89]
	v_mfma_f32_16x16x32_bf16 v[78:81], v[168:171], v[214:217], v[78:81]
	v_mfma_f32_16x16x32_bf16 v[70:73], v[160:163], v[222:225], v[70:73]
	v_mfma_f32_16x16x32_bf16 v[66:69], v[168:171], v[222:225], v[66:69]
	s_barrier
	s_mov_b32 m0, s50
	v_lshl_add_u64 v[226:227], s[34:35], 0, v[0:1]
	ds_read_b128 v[172:175], v143 offset:16384
	ds_read_b128 v[176:179], v143 offset:17408
	ds_read_b128 v[180:183], v143 offset:18432
	ds_read_b128 v[190:193], v143 offset:19456
	ds_read_b128 v[194:197], v143 offset:20480
	ds_read_b128 v[214:217], v143 offset:21504
	ds_read_b128 v[218:221], v143 offset:22528
	ds_read_b128 v[222:225], v143 offset:23552
	global_load_lds_dwordx4 v[226:227], off
	v_lshl_add_u64 v[228:229], s[34:35], 0, v[130:131]
	s_mov_b32 m0, s48
	v_lshl_add_u64 v[230:231], s[36:37], 0, v[0:1]
	global_load_lds_dwordx4 v[228:229], off
	s_mov_b32 m0, s89
	v_lshl_add_u64 v[232:233], s[30:31], 0, v[132:133]
	global_load_lds_dwordx4 v[230:231], off
	v_lshl_add_u64 v[230:231], s[36:37], 0, v[130:131]
	s_mov_b32 m0, s49
	s_nop 0
	global_load_lds_dwordx4 v[230:231], off
	v_lshl_add_u64 v[230:231], s[30:31], 0, v[134:135]
	s_mov_b32 m0, s41
	s_nop 0
	global_load_lds_dwordx4 v[230:231], off
	s_mov_b32 m0, s42
	s_nop 0
	global_load_lds_dwordx4 v[232:233], off
	s_waitcnt vmcnt(8)
	s_waitcnt lgkmcnt(0)
	s_barrier
	v_mfma_f32_16x16x32_bf16 v[62:65], v[136:139], v[172:175], v[62:65]
	v_mfma_f32_16x16x32_bf16 v[58:61], v[148:151], v[172:175], v[58:61]
	v_mfma_f32_16x16x32_bf16 v[50:53], v[136:139], v[180:183], v[50:53]
	v_mfma_f32_16x16x32_bf16 v[42:45], v[148:151], v[180:183], v[42:45]
	v_mfma_f32_16x16x32_bf16 v[34:37], v[136:139], v[194:197], v[34:37]
	v_mfma_f32_16x16x32_bf16 v[26:29], v[148:151], v[194:197], v[26:29]
	v_mfma_f32_16x16x32_bf16 v[18:21], v[136:139], v[218:221], v[18:21]
	v_mfma_f32_16x16x32_bf16 v[10:13], v[148:151], v[218:221], v[10:13]
	v_mfma_f32_16x16x32_bf16 v[62:65], v[144:147], v[176:179], v[62:65]
	v_mfma_f32_16x16x32_bf16 v[58:61], v[152:155], v[176:179], v[58:61]
	v_mfma_f32_16x16x32_bf16 v[50:53], v[144:147], v[190:193], v[50:53]
	v_mfma_f32_16x16x32_bf16 v[42:45], v[152:155], v[190:193], v[42:45]
	v_mfma_f32_16x16x32_bf16 v[34:37], v[144:147], v[214:217], v[34:37]
	v_mfma_f32_16x16x32_bf16 v[26:29], v[152:155], v[214:217], v[26:29]
	v_mfma_f32_16x16x32_bf16 v[18:21], v[144:147], v[222:225], v[18:21]
	v_mfma_f32_16x16x32_bf16 v[10:13], v[152:155], v[222:225], v[10:13]
	v_mfma_f32_16x16x32_bf16 v[54:57], v[156:159], v[172:175], v[54:57]
	v_mfma_f32_16x16x32_bf16 v[46:49], v[164:167], v[172:175], v[46:49]
	v_mfma_f32_16x16x32_bf16 v[38:41], v[156:159], v[180:183], v[38:41]
	v_mfma_f32_16x16x32_bf16 v[30:33], v[164:167], v[180:183], v[30:33]
	v_mfma_f32_16x16x32_bf16 v[22:25], v[156:159], v[194:197], v[22:25]
	v_mfma_f32_16x16x32_bf16 v[14:17], v[164:167], v[194:197], v[14:17]
	v_mfma_f32_16x16x32_bf16 v[6:9], v[156:159], v[218:221], v[6:9]
	v_mfma_f32_16x16x32_bf16 v[2:5], v[164:167], v[218:221], v[2:5]
	v_mfma_f32_16x16x32_bf16 v[54:57], v[160:163], v[176:179], v[54:57]
	v_mfma_f32_16x16x32_bf16 v[46:49], v[168:171], v[176:179], v[46:49]
	v_mfma_f32_16x16x32_bf16 v[38:41], v[160:163], v[190:193], v[38:41]
	v_mfma_f32_16x16x32_bf16 v[30:33], v[168:171], v[190:193], v[30:33]
	v_mfma_f32_16x16x32_bf16 v[22:25], v[160:163], v[214:217], v[22:25]
	v_mfma_f32_16x16x32_bf16 v[14:17], v[168:171], v[214:217], v[14:17]
	v_mfma_f32_16x16x32_bf16 v[6:9], v[160:163], v[222:225], v[6:9]
	v_mfma_f32_16x16x32_bf16 v[2:5], v[168:171], v[222:225], v[2:5]
	s_barrier
	v_add_u32_e32 v152, s88, v141
	v_add_u32_e32 v168, s71, v141
	ds_read_b128 v[136:139], v152
	ds_read_b128 v[144:147], v152 offset:1024
	ds_read_b128 v[148:151], v152 offset:2048
	ds_read_b128 v[152:155], v152 offset:3072
	ds_read_b128 v[156:159], v168
	ds_read_b128 v[160:163], v168 offset:1024
	ds_read_b128 v[164:167], v168 offset:2048
	ds_read_b128 v[168:171], v168 offset:3072
	s_mov_b32 m0, s43
	v_lshl_add_u64 v[234:235], s[28:29], 0, v[134:135]
	ds_read_b128 v[172:175], v143 offset:32768
	ds_read_b128 v[176:179], v143 offset:33792
	ds_read_b128 v[180:183], v143 offset:34816
	ds_read_b128 v[190:193], v143 offset:35840
	ds_read_b128 v[194:197], v143 offset:36864
	ds_read_b128 v[214:217], v143 offset:37888
	ds_read_b128 v[218:221], v143 offset:38912
	ds_read_b128 v[222:225], v143 offset:39936
	global_load_lds_dwordx4 v[234:235], off
	v_lshl_add_u64 v[234:235], s[28:29], 0, v[132:133]
	s_mov_b32 m0, s44
	s_nop 0
	global_load_lds_dwordx4 v[234:235], off
	s_waitcnt vmcnt(8)
	s_waitcnt lgkmcnt(0)
	s_barrier
	v_mfma_f32_16x16x32_bf16 v[126:129], v[136:139], v[172:175], v[126:129]
	v_mfma_f32_16x16x32_bf16 v[122:125], v[148:151], v[172:175], v[122:125]
	v_mfma_f32_16x16x32_bf16 v[114:117], v[136:139], v[180:183], v[114:117]
	v_mfma_f32_16x16x32_bf16 v[106:109], v[148:151], v[180:183], v[106:109]
	v_mfma_f32_16x16x32_bf16 v[98:101], v[136:139], v[194:197], v[98:101]
	v_mfma_f32_16x16x32_bf16 v[90:93], v[148:151], v[194:197], v[90:93]
	v_mfma_f32_16x16x32_bf16 v[82:85], v[136:139], v[218:221], v[82:85]
	v_mfma_f32_16x16x32_bf16 v[74:77], v[148:151], v[218:221], v[74:77]
	v_mfma_f32_16x16x32_bf16 v[126:129], v[144:147], v[176:179], v[126:129]
	v_mfma_f32_16x16x32_bf16 v[122:125], v[152:155], v[176:179], v[122:125]
	v_mfma_f32_16x16x32_bf16 v[114:117], v[144:147], v[190:193], v[114:117]
	v_mfma_f32_16x16x32_bf16 v[106:109], v[152:155], v[190:193], v[106:109]
	v_mfma_f32_16x16x32_bf16 v[98:101], v[144:147], v[214:217], v[98:101]
	v_mfma_f32_16x16x32_bf16 v[90:93], v[152:155], v[214:217], v[90:93]
	v_mfma_f32_16x16x32_bf16 v[82:85], v[144:147], v[222:225], v[82:85]
	v_mfma_f32_16x16x32_bf16 v[74:77], v[152:155], v[222:225], v[74:77]
	v_mfma_f32_16x16x32_bf16 v[118:121], v[156:159], v[172:175], v[118:121]
	v_mfma_f32_16x16x32_bf16 v[110:113], v[164:167], v[172:175], v[110:113]
	v_mfma_f32_16x16x32_bf16 v[102:105], v[156:159], v[180:183], v[102:105]
	v_mfma_f32_16x16x32_bf16 v[94:97], v[164:167], v[180:183], v[94:97]
	v_mfma_f32_16x16x32_bf16 v[86:89], v[156:159], v[194:197], v[86:89]
	v_mfma_f32_16x16x32_bf16 v[78:81], v[164:167], v[194:197], v[78:81]
	v_mfma_f32_16x16x32_bf16 v[70:73], v[156:159], v[218:221], v[70:73]
	v_mfma_f32_16x16x32_bf16 v[66:69], v[164:167], v[218:221], v[66:69]
	v_mfma_f32_16x16x32_bf16 v[118:121], v[160:163], v[176:179], v[118:121]
	v_mfma_f32_16x16x32_bf16 v[110:113], v[168:171], v[176:179], v[110:113]
	v_mfma_f32_16x16x32_bf16 v[102:105], v[160:163], v[190:193], v[102:105]
	v_mfma_f32_16x16x32_bf16 v[94:97], v[168:171], v[190:193], v[94:97]
	v_mfma_f32_16x16x32_bf16 v[86:89], v[160:163], v[214:217], v[86:89]
	v_mfma_f32_16x16x32_bf16 v[78:81], v[168:171], v[214:217], v[78:81]
	v_mfma_f32_16x16x32_bf16 v[70:73], v[160:163], v[222:225], v[70:73]
	v_mfma_f32_16x16x32_bf16 v[66:69], v[168:171], v[222:225], v[66:69]
	s_barrier
	s_mov_b32 m0, s70
	v_lshl_add_u64 v[226:227], v[226:227], 0, s[96:97]
	ds_read_b128 v[172:175], v143 offset:49152
	ds_read_b128 v[176:179], v143 offset:50176
	ds_read_b128 v[180:183], v143 offset:51200
	ds_read_b128 v[190:193], v143 offset:52224
	ds_read_b128 v[194:197], v143 offset:53248
	ds_read_b128 v[214:217], v143 offset:54272
	ds_read_b128 v[218:221], v143 offset:55296
	ds_read_b128 v[222:225], v143 offset:56320
	global_load_lds_dwordx4 v[226:227], off
	v_lshl_add_u64 v[226:227], v[228:229], 0, s[96:97]
	s_mov_b32 m0, s69
	s_nop 0
	global_load_lds_dwordx4 v[226:227], off
	v_lshl_add_u64 v[226:227], s[10:11], 0, v[0:1]
	s_mov_b32 m0, s0
	s_nop 0
	global_load_lds_dwordx4 v[226:227], off
	v_lshl_add_u64 v[226:227], s[10:11], 0, v[130:131]
	s_mov_b32 m0, s51
	s_nop 0
	global_load_lds_dwordx4 v[226:227], off
	v_lshl_add_u64 v[226:227], v[230:231], 0, s[96:97]
	s_mov_b32 m0, s45
	s_nop 0
	global_load_lds_dwordx4 v[226:227], off
	v_lshl_add_u64 v[226:227], v[232:233], 0, s[96:97]
	s_mov_b32 m0, s46
	s_nop 0
	global_load_lds_dwordx4 v[226:227], off
	s_waitcnt vmcnt(8)
	s_waitcnt lgkmcnt(0)
	s_barrier
	v_mfma_f32_16x16x32_bf16 v[62:65], v[136:139], v[172:175], v[62:65]
	v_mfma_f32_16x16x32_bf16 v[58:61], v[148:151], v[172:175], v[58:61]
	v_mfma_f32_16x16x32_bf16 v[50:53], v[136:139], v[180:183], v[50:53]
	v_mfma_f32_16x16x32_bf16 v[42:45], v[148:151], v[180:183], v[42:45]
	v_mfma_f32_16x16x32_bf16 v[34:37], v[136:139], v[194:197], v[34:37]
	v_mfma_f32_16x16x32_bf16 v[26:29], v[148:151], v[194:197], v[26:29]
	v_mfma_f32_16x16x32_bf16 v[18:21], v[136:139], v[218:221], v[18:21]
	v_mfma_f32_16x16x32_bf16 v[10:13], v[148:151], v[218:221], v[10:13]
	v_mfma_f32_16x16x32_bf16 v[62:65], v[144:147], v[176:179], v[62:65]
	v_mfma_f32_16x16x32_bf16 v[58:61], v[152:155], v[176:179], v[58:61]
	v_mfma_f32_16x16x32_bf16 v[50:53], v[144:147], v[190:193], v[50:53]
	v_mfma_f32_16x16x32_bf16 v[42:45], v[152:155], v[190:193], v[42:45]
	v_mfma_f32_16x16x32_bf16 v[34:37], v[144:147], v[214:217], v[34:37]
	v_mfma_f32_16x16x32_bf16 v[26:29], v[152:155], v[214:217], v[26:29]
	v_mfma_f32_16x16x32_bf16 v[18:21], v[144:147], v[222:225], v[18:21]
	v_mfma_f32_16x16x32_bf16 v[10:13], v[152:155], v[222:225], v[10:13]
	v_mfma_f32_16x16x32_bf16 v[54:57], v[156:159], v[172:175], v[54:57]
	v_mfma_f32_16x16x32_bf16 v[46:49], v[164:167], v[172:175], v[46:49]
	v_mfma_f32_16x16x32_bf16 v[38:41], v[156:159], v[180:183], v[38:41]
	v_mfma_f32_16x16x32_bf16 v[30:33], v[164:167], v[180:183], v[30:33]
	v_mfma_f32_16x16x32_bf16 v[22:25], v[156:159], v[194:197], v[22:25]
	v_mfma_f32_16x16x32_bf16 v[14:17], v[164:167], v[194:197], v[14:17]
	v_mfma_f32_16x16x32_bf16 v[6:9], v[156:159], v[218:221], v[6:9]
	v_mfma_f32_16x16x32_bf16 v[2:5], v[164:167], v[218:221], v[2:5]
	v_mfma_f32_16x16x32_bf16 v[54:57], v[160:163], v[176:179], v[54:57]
	v_mfma_f32_16x16x32_bf16 v[46:49], v[168:171], v[176:179], v[46:49]
	v_mfma_f32_16x16x32_bf16 v[38:41], v[160:163], v[190:193], v[38:41]
	v_mfma_f32_16x16x32_bf16 v[30:33], v[168:171], v[190:193], v[30:33]
	v_mfma_f32_16x16x32_bf16 v[22:25], v[160:163], v[214:217], v[22:25]
	v_mfma_f32_16x16x32_bf16 v[14:17], v[168:171], v[214:217], v[14:17]
	v_mfma_f32_16x16x32_bf16 v[6:9], v[160:163], v[222:225], v[6:9]
	v_mfma_f32_16x16x32_bf16 v[2:5], v[168:171], v[222:225], v[2:5]
	s_barrier
	s_andn2_b64 vcc, exec, s[26:27]
	s_mov_b64 s[10:11], -1
	s_mov_b64 s[26:27], 0
	s_mov_b64 s[28:29], 0x100
	s_cbranch_vccz .LBB11_2093
	s_and_b64 vcc, exec, s[14:15]
	s_cbranch_vccz .LBB11_2096
	s_barrier

.LBB11_2329:
	s_add_u32 s0, s22, 0xfffc0080
	s_addc_u32 s1, s23, -1
	s_add_i32 s48, 0, 0x10000
	s_cmp_eq_u32 s57, 12
	s_cselect_b32 s27, s8, s1
	s_cselect_b32 s26, s9, s0
	v_add_u32_e32 v148, s48, v151
	s_cselect_b32 s25, s45, s56
	s_cselect_b32 s24, s46, s47
	s_add_i32 s49, 0, 0x14000
	ds_read_b128 v[140:143], v148
	ds_read_b128 v[144:147], v148 offset:1024
	ds_read_b128 v[154:157], v148 offset:2048
	ds_read_b128 v[158:161], v148 offset:3072
	v_add_u32_e32 v148, s49, v151
	ds_read_b128 v[162:165], v148
	ds_read_b128 v[166:169], v148 offset:1024
	ds_read_b128 v[170:173], v148 offset:2048
	ds_read_b128 v[174:177], v148 offset:3072
	v_lshl_add_u64 v[148:149], s[22:23], 0, v[136:137]
	s_add_i32 m0, s35, 0xc000
	ds_read_b128 v[178:181], v153
	ds_read_b128 v[190:193], v153 offset:1024
	ds_read_b128 v[194:197], v153 offset:2048
	ds_read_b128 v[214:217], v153 offset:3072
	ds_read_b128 v[218:221], v153 offset:4096
	ds_read_b128 v[222:225], v153 offset:5120
	ds_read_b128 v[226:229], v153 offset:6144
	ds_read_b128 v[230:233], v153 offset:7168
	global_load_lds_dwordx4 v[148:149], off
	v_lshl_add_u64 v[148:149], s[22:23], 0, v[138:139]
	s_add_i32 m0, s35, 0xe000
	s_nop 0
	global_load_lds_dwordx4 v[148:149], off
	s_waitcnt vmcnt(8)
	s_waitcnt lgkmcnt(0)
	s_barrier
	v_mfma_f32_16x16x32_bf16 v[126:129], v[140:143], v[178:181], v[126:129]
	v_mfma_f32_16x16x32_bf16 v[122:125], v[154:157], v[178:181], v[122:125]
	v_mfma_f32_16x16x32_bf16 v[110:113], v[140:143], v[194:197], v[110:113]
	v_mfma_f32_16x16x32_bf16 v[106:109], v[154:157], v[194:197], v[106:109]
	v_mfma_f32_16x16x32_bf16 v[94:97], v[140:143], v[218:221], v[94:97]
	v_mfma_f32_16x16x32_bf16 v[90:93], v[154:157], v[218:221], v[90:93]
	v_mfma_f32_16x16x32_bf16 v[78:81], v[140:143], v[226:229], v[78:81]
	v_mfma_f32_16x16x32_bf16 v[74:77], v[154:157], v[226:229], v[74:77]
	v_mfma_f32_16x16x32_bf16 v[126:129], v[144:147], v[190:193], v[126:129]
	v_mfma_f32_16x16x32_bf16 v[122:125], v[158:161], v[190:193], v[122:125]
	v_mfma_f32_16x16x32_bf16 v[110:113], v[144:147], v[214:217], v[110:113]
	v_mfma_f32_16x16x32_bf16 v[106:109], v[158:161], v[214:217], v[106:109]
	v_mfma_f32_16x16x32_bf16 v[94:97], v[144:147], v[222:225], v[94:97]
	v_mfma_f32_16x16x32_bf16 v[90:93], v[158:161], v[222:225], v[90:93]
	v_mfma_f32_16x16x32_bf16 v[78:81], v[144:147], v[230:233], v[78:81]
	v_mfma_f32_16x16x32_bf16 v[74:77], v[158:161], v[230:233], v[74:77]
	v_mfma_f32_16x16x32_bf16 v[118:121], v[162:165], v[178:181], v[118:121]
	v_mfma_f32_16x16x32_bf16 v[114:117], v[170:173], v[178:181], v[114:117]
	v_mfma_f32_16x16x32_bf16 v[102:105], v[162:165], v[194:197], v[102:105]
	v_mfma_f32_16x16x32_bf16 v[98:101], v[170:173], v[194:197], v[98:101]
	v_mfma_f32_16x16x32_bf16 v[86:89], v[162:165], v[218:221], v[86:89]
	v_mfma_f32_16x16x32_bf16 v[82:85], v[170:173], v[218:221], v[82:85]
	v_mfma_f32_16x16x32_bf16 v[70:73], v[162:165], v[226:229], v[70:73]
	v_mfma_f32_16x16x32_bf16 v[66:69], v[170:173], v[226:229], v[66:69]
	v_mfma_f32_16x16x32_bf16 v[118:121], v[166:169], v[190:193], v[118:121]
	v_mfma_f32_16x16x32_bf16 v[114:117], v[174:177], v[190:193], v[114:117]
	v_mfma_f32_16x16x32_bf16 v[102:105], v[166:169], v[214:217], v[102:105]
	v_mfma_f32_16x16x32_bf16 v[98:101], v[174:177], v[214:217], v[98:101]
	v_mfma_f32_16x16x32_bf16 v[86:89], v[166:169], v[222:225], v[86:89]
	v_mfma_f32_16x16x32_bf16 v[82:85], v[174:177], v[222:225], v[82:85]
	v_mfma_f32_16x16x32_bf16 v[70:73], v[166:169], v[230:233], v[70:73]
	v_mfma_f32_16x16x32_bf16 v[66:69], v[174:177], v[230:233], v[66:69]
	s_barrier
	s_add_i32 s0, s48, s34
	v_lshl_add_u64 v[148:149], s[24:25], 0, v[0:1]
	s_mov_b32 m0, s0
	ds_read_b128 v[178:181], v153 offset:16384
	ds_read_b128 v[190:193], v153 offset:17408
	ds_read_b128 v[194:197], v153 offset:18432
	ds_read_b128 v[214:217], v153 offset:19456
	ds_read_b128 v[218:221], v153 offset:20480
	ds_read_b128 v[222:225], v153 offset:21504
	ds_read_b128 v[226:229], v153 offset:22528
	ds_read_b128 v[230:233], v153 offset:23552
	global_load_lds_dwordx4 v[148:149], off
	s_add_i32 m0, s0, 0x2000
	s_add_u32 s0, s24, 0x40000
	v_lshl_add_u64 v[182:183], s[24:25], 0, v[130:131]
	s_addc_u32 s1, s25, 0
	s_add_i32 s48, s49, s34
	global_load_lds_dwordx4 v[182:183], off
	v_lshl_add_u64 v[234:235], s[0:1], 0, v[0:1]
	s_mov_b32 m0, s48
	v_lshl_add_u64 v[236:237], s[26:27], 0, v[132:133]
	global_load_lds_dwordx4 v[234:235], off
	v_lshl_add_u64 v[234:235], s[0:1], 0, v[130:131]
	s_add_i32 m0, s48, 0x2000
	s_nop 0
	global_load_lds_dwordx4 v[234:235], off
	v_lshl_add_u64 v[234:235], s[26:27], 0, v[134:135]
	s_mov_b32 m0, s35
	s_nop 0
	global_load_lds_dwordx4 v[234:235], off
	s_mov_b32 m0, s36
	s_nop 0
	global_load_lds_dwordx4 v[236:237], off
	s_waitcnt vmcnt(8)
	s_waitcnt lgkmcnt(0)
	s_barrier
	v_mfma_f32_16x16x32_bf16 v[62:65], v[140:143], v[178:181], v[62:65]
	v_mfma_f32_16x16x32_bf16 v[58:61], v[154:157], v[178:181], v[58:61]
	v_mfma_f32_16x16x32_bf16 v[46:49], v[140:143], v[194:197], v[46:49]
	v_mfma_f32_16x16x32_bf16 v[42:45], v[154:157], v[194:197], v[42:45]
	v_mfma_f32_16x16x32_bf16 v[30:33], v[140:143], v[218:221], v[30:33]
	v_mfma_f32_16x16x32_bf16 v[26:29], v[154:157], v[218:221], v[26:29]
	v_mfma_f32_16x16x32_bf16 v[14:17], v[140:143], v[226:229], v[14:17]
	v_mfma_f32_16x16x32_bf16 v[10:13], v[154:157], v[226:229], v[10:13]
	v_mfma_f32_16x16x32_bf16 v[62:65], v[144:147], v[190:193], v[62:65]
	v_mfma_f32_16x16x32_bf16 v[58:61], v[158:161], v[190:193], v[58:61]
	v_mfma_f32_16x16x32_bf16 v[46:49], v[144:147], v[214:217], v[46:49]
	v_mfma_f32_16x16x32_bf16 v[42:45], v[158:161], v[214:217], v[42:45]
	v_mfma_f32_16x16x32_bf16 v[30:33], v[144:147], v[222:225], v[30:33]
	v_mfma_f32_16x16x32_bf16 v[26:29], v[158:161], v[222:225], v[26:29]
	v_mfma_f32_16x16x32_bf16 v[14:17], v[144:147], v[230:233], v[14:17]
	v_mfma_f32_16x16x32_bf16 v[10:13], v[158:161], v[230:233], v[10:13]
	v_mfma_f32_16x16x32_bf16 v[54:57], v[162:165], v[178:181], v[54:57]
	v_mfma_f32_16x16x32_bf16 v[50:53], v[170:173], v[178:181], v[50:53]
	v_mfma_f32_16x16x32_bf16 v[38:41], v[162:165], v[194:197], v[38:41]
	v_mfma_f32_16x16x32_bf16 v[34:37], v[170:173], v[194:197], v[34:37]
	v_mfma_f32_16x16x32_bf16 v[22:25], v[162:165], v[218:221], v[22:25]
	v_mfma_f32_16x16x32_bf16 v[18:21], v[170:173], v[218:221], v[18:21]
	v_mfma_f32_16x16x32_bf16 v[6:9], v[162:165], v[226:229], v[6:9]
	v_mfma_f32_16x16x32_bf16 v[2:5], v[170:173], v[226:229], v[2:5]
	v_mfma_f32_16x16x32_bf16 v[54:57], v[166:169], v[190:193], v[54:57]
	v_mfma_f32_16x16x32_bf16 v[50:53], v[174:177], v[190:193], v[50:53]
	v_mfma_f32_16x16x32_bf16 v[38:41], v[166:169], v[214:217], v[38:41]
	v_mfma_f32_16x16x32_bf16 v[34:37], v[174:177], v[214:217], v[34:37]
	v_mfma_f32_16x16x32_bf16 v[22:25], v[166:169], v[222:225], v[22:25]
	v_mfma_f32_16x16x32_bf16 v[18:21], v[174:177], v[222:225], v[18:21]
	v_mfma_f32_16x16x32_bf16 v[6:9], v[166:169], v[230:233], v[6:9]
	v_mfma_f32_16x16x32_bf16 v[2:5], v[174:177], v[230:233], v[2:5]
	s_barrier
	s_add_i32 s48, 0, 0x18000
	s_add_i32 s49, 0, 0x1c000
	v_add_u32_e32 v158, s48, v151
	v_add_u32_e32 v174, s49, v151
	ds_read_b128 v[140:143], v158
	ds_read_b128 v[144:147], v158 offset:1024
	ds_read_b128 v[154:157], v158 offset:2048
	ds_read_b128 v[158:161], v158 offset:3072
	ds_read_b128 v[162:165], v174
	ds_read_b128 v[166:169], v174 offset:1024
	ds_read_b128 v[170:173], v174 offset:2048
	ds_read_b128 v[174:177], v174 offset:3072
	s_add_u32 s0, s26, 0x40000
	s_addc_u32 s1, s27, 0
	s_mov_b32 m0, s37
	v_lshl_add_u64 v[238:239], s[0:1], 0, v[134:135]
	ds_read_b128 v[178:181], v153 offset:32768
	ds_read_b128 v[190:193], v153 offset:33792
	ds_read_b128 v[194:197], v153 offset:34816
	ds_read_b128 v[214:217], v153 offset:35840
	ds_read_b128 v[218:221], v153 offset:36864
	ds_read_b128 v[222:225], v153 offset:37888
	ds_read_b128 v[226:229], v153 offset:38912
	ds_read_b128 v[230:233], v153 offset:39936
	global_load_lds_dwordx4 v[238:239], off
	v_lshl_add_u64 v[238:239], s[0:1], 0, v[132:133]
	s_mov_b32 m0, s38
	s_nop 0
	global_load_lds_dwordx4 v[238:239], off
	s_waitcnt vmcnt(8)
	s_waitcnt lgkmcnt(0)
	s_barrier
	v_mfma_f32_16x16x32_bf16 v[126:129], v[140:143], v[178:181], v[126:129]
	v_mfma_f32_16x16x32_bf16 v[122:125], v[154:157], v[178:181], v[122:125]
	v_mfma_f32_16x16x32_bf16 v[110:113], v[140:143], v[194:197], v[110:113]
	v_mfma_f32_16x16x32_bf16 v[106:109], v[154:157], v[194:197], v[106:109]
	v_mfma_f32_16x16x32_bf16 v[94:97], v[140:143], v[218:221], v[94:97]
	v_mfma_f32_16x16x32_bf16 v[90:93], v[154:157], v[218:221], v[90:93]
	v_mfma_f32_16x16x32_bf16 v[78:81], v[140:143], v[226:229], v[78:81]
	v_mfma_f32_16x16x32_bf16 v[74:77], v[154:157], v[226:229], v[74:77]
	v_mfma_f32_16x16x32_bf16 v[126:129], v[144:147], v[190:193], v[126:129]
	v_mfma_f32_16x16x32_bf16 v[122:125], v[158:161], v[190:193], v[122:125]
	v_mfma_f32_16x16x32_bf16 v[110:113], v[144:147], v[214:217], v[110:113]
	v_mfma_f32_16x16x32_bf16 v[106:109], v[158:161], v[214:217], v[106:109]
	v_mfma_f32_16x16x32_bf16 v[94:97], v[144:147], v[222:225], v[94:97]
	v_mfma_f32_16x16x32_bf16 v[90:93], v[158:161], v[222:225], v[90:93]
	v_mfma_f32_16x16x32_bf16 v[78:81], v[144:147], v[230:233], v[78:81]
	v_mfma_f32_16x16x32_bf16 v[74:77], v[158:161], v[230:233], v[74:77]
	v_mfma_f32_16x16x32_bf16 v[118:121], v[162:165], v[178:181], v[118:121]
	v_mfma_f32_16x16x32_bf16 v[114:117], v[170:173], v[178:181], v[114:117]
	v_mfma_f32_16x16x32_bf16 v[102:105], v[162:165], v[194:197], v[102:105]
	v_mfma_f32_16x16x32_bf16 v[98:101], v[170:173], v[194:197], v[98:101]
	v_mfma_f32_16x16x32_bf16 v[86:89], v[162:165], v[218:221], v[86:89]
	v_mfma_f32_16x16x32_bf16 v[82:85], v[170:173], v[218:221], v[82:85]
	v_mfma_f32_16x16x32_bf16 v[70:73], v[162:165], v[226:229], v[70:73]
	v_mfma_f32_16x16x32_bf16 v[66:69], v[170:173], v[226:229], v[66:69]
	v_mfma_f32_16x16x32_bf16 v[118:121], v[166:169], v[190:193], v[118:121]
	v_mfma_f32_16x16x32_bf16 v[114:117], v[174:177], v[190:193], v[114:117]
	v_mfma_f32_16x16x32_bf16 v[102:105], v[166:169], v[214:217], v[102:105]
	v_mfma_f32_16x16x32_bf16 v[98:101], v[174:177], v[214:217], v[98:101]
	v_mfma_f32_16x16x32_bf16 v[86:89], v[166:169], v[222:225], v[86:89]
	v_mfma_f32_16x16x32_bf16 v[82:85], v[174:177], v[222:225], v[82:85]
	v_mfma_f32_16x16x32_bf16 v[70:73], v[166:169], v[230:233], v[70:73]
	v_mfma_f32_16x16x32_bf16 v[66:69], v[174:177], v[230:233], v[66:69]
	s_barrier
	s_add_i32 s0, s48, s34
	v_lshl_add_u64 v[148:149], v[148:149], 0, s[96:97]
	s_mov_b32 m0, s0
	ds_read_b128 v[178:181], v153 offset:49152
	ds_read_b128 v[190:193], v153 offset:50176
	ds_read_b128 v[194:197], v153 offset:51200
	ds_read_b128 v[214:217], v153 offset:52224
	ds_read_b128 v[218:221], v153 offset:53248
	ds_read_b128 v[222:225], v153 offset:54272
	ds_read_b128 v[226:229], v153 offset:55296
	ds_read_b128 v[230:233], v153 offset:56320
	global_load_lds_dwordx4 v[148:149], off
	s_add_i32 m0, s0, 0x2000
	s_add_u32 s0, s24, 0x40080
	v_lshl_add_u64 v[148:149], v[182:183], 0, s[96:97]
	s_addc_u32 s1, s25, 0
	s_add_i32 s24, s49, s34
	global_load_lds_dwordx4 v[148:149], off
	v_lshl_add_u64 v[148:149], s[0:1], 0, v[0:1]
	s_mov_b32 m0, s24
	s_nop 0
	global_load_lds_dwordx4 v[148:149], off
	v_lshl_add_u64 v[148:149], s[0:1], 0, v[130:131]
	s_add_i32 m0, s24, 0x2000
	s_nop 0
	global_load_lds_dwordx4 v[148:149], off
	v_lshl_add_u64 v[148:149], v[234:235], 0, s[96:97]
	s_mov_b32 m0, s39
	s_nop 0
	global_load_lds_dwordx4 v[148:149], off
	v_lshl_add_u64 v[148:149], v[236:237], 0, s[96:97]
	s_mov_b32 m0, s40
	s_nop 0
	global_load_lds_dwordx4 v[148:149], off
	s_waitcnt vmcnt(8)
	s_waitcnt lgkmcnt(0)
	s_barrier
	v_mfma_f32_16x16x32_bf16 v[62:65], v[140:143], v[178:181], v[62:65]
	v_mfma_f32_16x16x32_bf16 v[58:61], v[154:157], v[178:181], v[58:61]
	v_mfma_f32_16x16x32_bf16 v[46:49], v[140:143], v[194:197], v[46:49]
	v_mfma_f32_16x16x32_bf16 v[42:45], v[154:157], v[194:197], v[42:45]
	v_mfma_f32_16x16x32_bf16 v[30:33], v[140:143], v[218:221], v[30:33]
	v_mfma_f32_16x16x32_bf16 v[26:29], v[154:157], v[218:221], v[26:29]
	v_mfma_f32_16x16x32_bf16 v[14:17], v[140:143], v[226:229], v[14:17]
	v_mfma_f32_16x16x32_bf16 v[10:13], v[154:157], v[226:229], v[10:13]
	v_mfma_f32_16x16x32_bf16 v[62:65], v[144:147], v[190:193], v[62:65]
	v_mfma_f32_16x16x32_bf16 v[58:61], v[158:161], v[190:193], v[58:61]
	v_mfma_f32_16x16x32_bf16 v[46:49], v[144:147], v[214:217], v[46:49]
	v_mfma_f32_16x16x32_bf16 v[42:45], v[158:161], v[214:217], v[42:45]
	v_mfma_f32_16x16x32_bf16 v[30:33], v[144:147], v[222:225], v[30:33]
	v_mfma_f32_16x16x32_bf16 v[26:29], v[158:161], v[222:225], v[26:29]
	v_mfma_f32_16x16x32_bf16 v[14:17], v[144:147], v[230:233], v[14:17]
	v_mfma_f32_16x16x32_bf16 v[10:13], v[158:161], v[230:233], v[10:13]
	v_mfma_f32_16x16x32_bf16 v[54:57], v[162:165], v[178:181], v[54:57]
	v_mfma_f32_16x16x32_bf16 v[50:53], v[170:173], v[178:181], v[50:53]
	v_mfma_f32_16x16x32_bf16 v[38:41], v[162:165], v[194:197], v[38:41]
	v_mfma_f32_16x16x32_bf16 v[34:37], v[170:173], v[194:197], v[34:37]
	v_mfma_f32_16x16x32_bf16 v[22:25], v[162:165], v[218:221], v[22:25]
	v_mfma_f32_16x16x32_bf16 v[18:21], v[170:173], v[218:221], v[18:21]
	v_mfma_f32_16x16x32_bf16 v[6:9], v[162:165], v[226:229], v[6:9]
	v_mfma_f32_16x16x32_bf16 v[2:5], v[170:173], v[226:229], v[2:5]
	v_mfma_f32_16x16x32_bf16 v[54:57], v[166:169], v[190:193], v[54:57]
	v_mfma_f32_16x16x32_bf16 v[50:53], v[174:177], v[190:193], v[50:53]
	v_mfma_f32_16x16x32_bf16 v[38:41], v[166:169], v[214:217], v[38:41]
	v_mfma_f32_16x16x32_bf16 v[34:37], v[174:177], v[214:217], v[34:37]
	v_mfma_f32_16x16x32_bf16 v[22:25], v[166:169], v[222:225], v[22:25]
	v_mfma_f32_16x16x32_bf16 v[18:21], v[174:177], v[222:225], v[18:21]
	v_mfma_f32_16x16x32_bf16 v[6:9], v[166:169], v[230:233], v[6:9]
	v_mfma_f32_16x16x32_bf16 v[2:5], v[174:177], v[230:233], v[2:5]
	s_barrier
	s_add_i32 s57, s57, 2
	s_add_u32 s22, s22, 0x100
	s_addc_u32 s23, s23, 0
	s_add_u32 s47, s47, 0x100
	s_addc_u32 s56, s56, 0
	s_cmp_gt_u32 s57, 13
	s_cbranch_scc0 .LBB11_2329
	s_and_b64 vcc, exec, s[14:15]
	s_cbranch_vccz .LBB11_2332
	s_barrier

.LBB11_2567:
	s_add_u32 s0, s26, 0xfffc0080
	s_addc_u32 s1, s27, -1
	s_add_i32 s48, 0, 0x10000
	s_cmp_eq_u32 s68, 12
	s_cselect_b32 s31, s9, s1
	s_cselect_b32 s30, s47, s0
	s_cselect_b32 s29, s56, s59
	s_cselect_b32 s28, s57, s58
	s_add_i32 s49, 0, 0x14000
	v_add_u32_e32 v158, s48, v142
	v_add_u32_e32 v174, s49, v142
	ds_read_b128 v[146:149], v158
	ds_read_b128 v[150:153], v158 offset:1024
	ds_read_b128 v[154:157], v158 offset:2048
	ds_read_b128 v[158:161], v158 offset:3072
	ds_read_b128 v[162:165], v174
	ds_read_b128 v[166:169], v174 offset:1024
	ds_read_b128 v[170:173], v174 offset:2048
	ds_read_b128 v[174:177], v174 offset:3072
	v_lshl_add_u64 v[182:183], s[26:27], 0, v[136:137]
	s_add_i32 m0, s36, 0xc000
	ds_read_b128 v[178:181], v145
	ds_read_b128 v[190:193], v145 offset:1024
	ds_read_b128 v[194:197], v145 offset:2048
	ds_read_b128 v[214:217], v145 offset:3072
	ds_read_b128 v[218:221], v145 offset:4096
	ds_read_b128 v[222:225], v145 offset:5120
	ds_read_b128 v[226:229], v145 offset:6144
	ds_read_b128 v[230:233], v145 offset:7168
	global_load_lds_dwordx4 v[182:183], off
	v_lshl_add_u64 v[182:183], s[26:27], 0, v[138:139]
	s_add_i32 m0, s36, 0xe000
	s_nop 0
	global_load_lds_dwordx4 v[182:183], off
	s_waitcnt vmcnt(8)
	s_waitcnt lgkmcnt(0)
	s_barrier
	v_mfma_f32_16x16x32_bf16 v[126:129], v[146:149], v[178:181], v[126:129]
	v_mfma_f32_16x16x32_bf16 v[118:121], v[154:157], v[178:181], v[118:121]
	v_mfma_f32_16x16x32_bf16 v[110:113], v[146:149], v[194:197], v[110:113]
	v_mfma_f32_16x16x32_bf16 v[102:105], v[154:157], v[194:197], v[102:105]
	v_mfma_f32_16x16x32_bf16 v[94:97], v[146:149], v[218:221], v[94:97]
	v_mfma_f32_16x16x32_bf16 v[86:89], v[154:157], v[218:221], v[86:89]
	v_mfma_f32_16x16x32_bf16 v[78:81], v[146:149], v[226:229], v[78:81]
	v_mfma_f32_16x16x32_bf16 v[70:73], v[154:157], v[226:229], v[70:73]
	v_mfma_f32_16x16x32_bf16 v[126:129], v[150:153], v[190:193], v[126:129]
	v_mfma_f32_16x16x32_bf16 v[118:121], v[158:161], v[190:193], v[118:121]
	v_mfma_f32_16x16x32_bf16 v[110:113], v[150:153], v[214:217], v[110:113]
	v_mfma_f32_16x16x32_bf16 v[102:105], v[158:161], v[214:217], v[102:105]
	v_mfma_f32_16x16x32_bf16 v[94:97], v[150:153], v[222:225], v[94:97]
	v_mfma_f32_16x16x32_bf16 v[86:89], v[158:161], v[222:225], v[86:89]
	v_mfma_f32_16x16x32_bf16 v[78:81], v[150:153], v[230:233], v[78:81]
	v_mfma_f32_16x16x32_bf16 v[70:73], v[158:161], v[230:233], v[70:73]
	v_mfma_f32_16x16x32_bf16 v[122:125], v[162:165], v[178:181], v[122:125]
	v_mfma_f32_16x16x32_bf16 v[114:117], v[170:173], v[178:181], v[114:117]
	v_mfma_f32_16x16x32_bf16 v[106:109], v[162:165], v[194:197], v[106:109]
	v_mfma_f32_16x16x32_bf16 v[98:101], v[170:173], v[194:197], v[98:101]
	v_mfma_f32_16x16x32_bf16 v[90:93], v[162:165], v[218:221], v[90:93]
	v_mfma_f32_16x16x32_bf16 v[82:85], v[170:173], v[218:221], v[82:85]
	v_mfma_f32_16x16x32_bf16 v[74:77], v[162:165], v[226:229], v[74:77]
	v_mfma_f32_16x16x32_bf16 v[66:69], v[170:173], v[226:229], v[66:69]
	v_mfma_f32_16x16x32_bf16 v[122:125], v[166:169], v[190:193], v[122:125]
	v_mfma_f32_16x16x32_bf16 v[114:117], v[174:177], v[190:193], v[114:117]
	v_mfma_f32_16x16x32_bf16 v[106:109], v[166:169], v[214:217], v[106:109]
	v_mfma_f32_16x16x32_bf16 v[98:101], v[174:177], v[214:217], v[98:101]
	v_mfma_f32_16x16x32_bf16 v[90:93], v[166:169], v[222:225], v[90:93]
	v_mfma_f32_16x16x32_bf16 v[82:85], v[174:177], v[222:225], v[82:85]
	v_mfma_f32_16x16x32_bf16 v[74:77], v[166:169], v[230:233], v[74:77]
	v_mfma_f32_16x16x32_bf16 v[66:69], v[174:177], v[230:233], v[66:69]
	s_barrier
	s_add_i32 s0, s48, s35
	v_lshl_add_u64 v[182:183], s[28:29], 0, v[0:1]
	s_mov_b32 m0, s0
	ds_read_b128 v[178:181], v145 offset:16384
	ds_read_b128 v[190:193], v145 offset:17408
	ds_read_b128 v[194:197], v145 offset:18432
	ds_read_b128 v[214:217], v145 offset:19456
	ds_read_b128 v[218:221], v145 offset:20480
	ds_read_b128 v[222:225], v145 offset:21504
	ds_read_b128 v[226:229], v145 offset:22528
	ds_read_b128 v[230:233], v145 offset:23552
	global_load_lds_dwordx4 v[182:183], off
	s_add_i32 m0, s0, 0x2000
	s_add_u32 s0, s28, 0x40000
	v_lshl_add_u64 v[234:235], s[28:29], 0, v[134:135]
	s_addc_u32 s1, s29, 0
	s_add_i32 s48, s49, s35
	global_load_lds_dwordx4 v[234:235], off
	v_lshl_add_u64 v[236:237], s[0:1], 0, v[0:1]
	s_mov_b32 m0, s48
	v_lshl_add_u64 v[238:239], s[30:31], 0, v[132:133]
	global_load_lds_dwordx4 v[236:237], off
	v_lshl_add_u64 v[236:237], s[0:1], 0, v[134:135]
	s_add_i32 m0, s48, 0x2000
	s_nop 0
	global_load_lds_dwordx4 v[236:237], off
	v_lshl_add_u64 v[236:237], s[30:31], 0, v[130:131]
	s_mov_b32 m0, s36
	s_nop 0
	global_load_lds_dwordx4 v[236:237], off
	s_mov_b32 m0, s37
	s_nop 0
	global_load_lds_dwordx4 v[238:239], off
	s_waitcnt vmcnt(8)
	s_waitcnt lgkmcnt(0)
	s_barrier
	v_mfma_f32_16x16x32_bf16 v[62:65], v[146:149], v[178:181], v[62:65]
	v_mfma_f32_16x16x32_bf16 v[54:57], v[154:157], v[178:181], v[54:57]
	v_mfma_f32_16x16x32_bf16 v[46:49], v[146:149], v[194:197], v[46:49]
	v_mfma_f32_16x16x32_bf16 v[38:41], v[154:157], v[194:197], v[38:41]
	v_mfma_f32_16x16x32_bf16 v[30:33], v[146:149], v[218:221], v[30:33]
	v_mfma_f32_16x16x32_bf16 v[22:25], v[154:157], v[218:221], v[22:25]
	v_mfma_f32_16x16x32_bf16 v[14:17], v[146:149], v[226:229], v[14:17]
	v_mfma_f32_16x16x32_bf16 v[6:9], v[154:157], v[226:229], v[6:9]
	v_mfma_f32_16x16x32_bf16 v[62:65], v[150:153], v[190:193], v[62:65]
	v_mfma_f32_16x16x32_bf16 v[54:57], v[158:161], v[190:193], v[54:57]
	v_mfma_f32_16x16x32_bf16 v[46:49], v[150:153], v[214:217], v[46:49]
	v_mfma_f32_16x16x32_bf16 v[38:41], v[158:161], v[214:217], v[38:41]
	v_mfma_f32_16x16x32_bf16 v[30:33], v[150:153], v[222:225], v[30:33]
	v_mfma_f32_16x16x32_bf16 v[22:25], v[158:161], v[222:225], v[22:25]
	v_mfma_f32_16x16x32_bf16 v[14:17], v[150:153], v[230:233], v[14:17]
	v_mfma_f32_16x16x32_bf16 v[6:9], v[158:161], v[230:233], v[6:9]
	v_mfma_f32_16x16x32_bf16 v[58:61], v[162:165], v[178:181], v[58:61]
	v_mfma_f32_16x16x32_bf16 v[50:53], v[170:173], v[178:181], v[50:53]
	v_mfma_f32_16x16x32_bf16 v[42:45], v[162:165], v[194:197], v[42:45]
	v_mfma_f32_16x16x32_bf16 v[34:37], v[170:173], v[194:197], v[34:37]
	v_mfma_f32_16x16x32_bf16 v[26:29], v[162:165], v[218:221], v[26:29]
	v_mfma_f32_16x16x32_bf16 v[18:21], v[170:173], v[218:221], v[18:21]
	v_mfma_f32_16x16x32_bf16 v[10:13], v[162:165], v[226:229], v[10:13]
	v_mfma_f32_16x16x32_bf16 v[2:5], v[170:173], v[226:229], v[2:5]
	v_mfma_f32_16x16x32_bf16 v[58:61], v[166:169], v[190:193], v[58:61]
	v_mfma_f32_16x16x32_bf16 v[50:53], v[174:177], v[190:193], v[50:53]
	v_mfma_f32_16x16x32_bf16 v[42:45], v[166:169], v[214:217], v[42:45]
	v_mfma_f32_16x16x32_bf16 v[34:37], v[174:177], v[214:217], v[34:37]
	v_mfma_f32_16x16x32_bf16 v[26:29], v[166:169], v[222:225], v[26:29]
	v_mfma_f32_16x16x32_bf16 v[18:21], v[174:177], v[222:225], v[18:21]
	v_mfma_f32_16x16x32_bf16 v[10:13], v[166:169], v[230:233], v[10:13]
	v_mfma_f32_16x16x32_bf16 v[2:5], v[174:177], v[230:233], v[2:5]
	s_barrier
	s_add_i32 s48, 0, 0x18000
	s_add_i32 s49, 0, 0x1c000
	v_add_u32_e32 v158, s48, v142
	v_add_u32_e32 v174, s49, v142
	ds_read_b128 v[146:149], v158
	ds_read_b128 v[150:153], v158 offset:1024
	ds_read_b128 v[154:157], v158 offset:2048
	ds_read_b128 v[158:161], v158 offset:3072
	ds_read_b128 v[162:165], v174
	ds_read_b128 v[166:169], v174 offset:1024
	ds_read_b128 v[170:173], v174 offset:2048
	ds_read_b128 v[174:177], v174 offset:3072
	s_add_u32 s0, s30, 0x40000
	s_addc_u32 s1, s31, 0
	s_mov_b32 m0, s38
	v_lshl_add_u64 v[240:241], s[0:1], 0, v[130:131]
	ds_read_b128 v[178:181], v145 offset:32768
	ds_read_b128 v[190:193], v145 offset:33792
	ds_read_b128 v[194:197], v145 offset:34816
	ds_read_b128 v[214:217], v145 offset:35840
	ds_read_b128 v[218:221], v145 offset:36864
	ds_read_b128 v[222:225], v145 offset:37888
	ds_read_b128 v[226:229], v145 offset:38912
	ds_read_b128 v[230:233], v145 offset:39936
	global_load_lds_dwordx4 v[240:241], off
	v_lshl_add_u64 v[240:241], s[0:1], 0, v[132:133]
	s_mov_b32 m0, s39
	s_nop 0
	global_load_lds_dwordx4 v[240:241], off
	s_waitcnt vmcnt(8)
	s_waitcnt lgkmcnt(0)
	s_barrier
	v_mfma_f32_16x16x32_bf16 v[126:129], v[146:149], v[178:181], v[126:129]
	v_mfma_f32_16x16x32_bf16 v[118:121], v[154:157], v[178:181], v[118:121]
	v_mfma_f32_16x16x32_bf16 v[110:113], v[146:149], v[194:197], v[110:113]
	v_mfma_f32_16x16x32_bf16 v[102:105], v[154:157], v[194:197], v[102:105]
	v_mfma_f32_16x16x32_bf16 v[94:97], v[146:149], v[218:221], v[94:97]
	v_mfma_f32_16x16x32_bf16 v[86:89], v[154:157], v[218:221], v[86:89]
	v_mfma_f32_16x16x32_bf16 v[78:81], v[146:149], v[226:229], v[78:81]
	v_mfma_f32_16x16x32_bf16 v[70:73], v[154:157], v[226:229], v[70:73]
	v_mfma_f32_16x16x32_bf16 v[126:129], v[150:153], v[190:193], v[126:129]
	v_mfma_f32_16x16x32_bf16 v[118:121], v[158:161], v[190:193], v[118:121]
	v_mfma_f32_16x16x32_bf16 v[110:113], v[150:153], v[214:217], v[110:113]
	v_mfma_f32_16x16x32_bf16 v[102:105], v[158:161], v[214:217], v[102:105]
	v_mfma_f32_16x16x32_bf16 v[94:97], v[150:153], v[222:225], v[94:97]
	v_mfma_f32_16x16x32_bf16 v[86:89], v[158:161], v[222:225], v[86:89]
	v_mfma_f32_16x16x32_bf16 v[78:81], v[150:153], v[230:233], v[78:81]
	v_mfma_f32_16x16x32_bf16 v[70:73], v[158:161], v[230:233], v[70:73]
	v_mfma_f32_16x16x32_bf16 v[122:125], v[162:165], v[178:181], v[122:125]
	v_mfma_f32_16x16x32_bf16 v[114:117], v[170:173], v[178:181], v[114:117]
	v_mfma_f32_16x16x32_bf16 v[106:109], v[162:165], v[194:197], v[106:109]
	v_mfma_f32_16x16x32_bf16 v[98:101], v[170:173], v[194:197], v[98:101]
	v_mfma_f32_16x16x32_bf16 v[90:93], v[162:165], v[218:221], v[90:93]
	v_mfma_f32_16x16x32_bf16 v[82:85], v[170:173], v[218:221], v[82:85]
	v_mfma_f32_16x16x32_bf16 v[74:77], v[162:165], v[226:229], v[74:77]
	v_mfma_f32_16x16x32_bf16 v[66:69], v[170:173], v[226:229], v[66:69]
	v_mfma_f32_16x16x32_bf16 v[122:125], v[166:169], v[190:193], v[122:125]
	v_mfma_f32_16x16x32_bf16 v[114:117], v[174:177], v[190:193], v[114:117]
	v_mfma_f32_16x16x32_bf16 v[106:109], v[166:169], v[214:217], v[106:109]
	v_mfma_f32_16x16x32_bf16 v[98:101], v[174:177], v[214:217], v[98:101]
	v_mfma_f32_16x16x32_bf16 v[90:93], v[166:169], v[222:225], v[90:93]
	v_mfma_f32_16x16x32_bf16 v[82:85], v[174:177], v[222:225], v[82:85]
	v_mfma_f32_16x16x32_bf16 v[74:77], v[166:169], v[230:233], v[74:77]
	v_mfma_f32_16x16x32_bf16 v[66:69], v[174:177], v[230:233], v[66:69]
	s_barrier
	s_add_i32 s0, s48, s35
	v_lshl_add_u64 v[182:183], v[182:183], 0, s[96:97]
	s_mov_b32 m0, s0
	ds_read_b128 v[178:181], v145 offset:49152
	ds_read_b128 v[190:193], v145 offset:50176
	ds_read_b128 v[194:197], v145 offset:51200
	ds_read_b128 v[214:217], v145 offset:52224
	ds_read_b128 v[218:221], v145 offset:53248
	ds_read_b128 v[222:225], v145 offset:54272
	ds_read_b128 v[226:229], v145 offset:55296
	ds_read_b128 v[230:233], v145 offset:56320
	global_load_lds_dwordx4 v[182:183], off
	s_add_i32 m0, s0, 0x2000
	s_add_u32 s0, s28, 0x40080
	v_lshl_add_u64 v[182:183], v[234:235], 0, s[96:97]
	s_addc_u32 s1, s29, 0
	s_add_i32 s28, s49, s35
	global_load_lds_dwordx4 v[182:183], off
	v_lshl_add_u64 v[182:183], s[0:1], 0, v[0:1]
	s_mov_b32 m0, s28
	s_nop 0
	global_load_lds_dwordx4 v[182:183], off
	v_lshl_add_u64 v[182:183], s[0:1], 0, v[134:135]
	s_add_i32 m0, s28, 0x2000
	s_nop 0
	global_load_lds_dwordx4 v[182:183], off
	v_lshl_add_u64 v[182:183], v[236:237], 0, s[96:97]
	s_mov_b32 m0, s40
	s_nop 0
	global_load_lds_dwordx4 v[182:183], off
	v_lshl_add_u64 v[182:183], v[238:239], 0, s[96:97]
	s_mov_b32 m0, s41
	s_nop 0
	global_load_lds_dwordx4 v[182:183], off
	s_waitcnt vmcnt(8)
	s_waitcnt lgkmcnt(0)
	s_barrier
	v_mfma_f32_16x16x32_bf16 v[62:65], v[146:149], v[178:181], v[62:65]
	v_mfma_f32_16x16x32_bf16 v[54:57], v[154:157], v[178:181], v[54:57]
	v_mfma_f32_16x16x32_bf16 v[46:49], v[146:149], v[194:197], v[46:49]
	v_mfma_f32_16x16x32_bf16 v[38:41], v[154:157], v[194:197], v[38:41]
	v_mfma_f32_16x16x32_bf16 v[30:33], v[146:149], v[218:221], v[30:33]
	v_mfma_f32_16x16x32_bf16 v[22:25], v[154:157], v[218:221], v[22:25]
	v_mfma_f32_16x16x32_bf16 v[14:17], v[146:149], v[226:229], v[14:17]
	v_mfma_f32_16x16x32_bf16 v[6:9], v[154:157], v[226:229], v[6:9]
	v_mfma_f32_16x16x32_bf16 v[62:65], v[150:153], v[190:193], v[62:65]
	v_mfma_f32_16x16x32_bf16 v[54:57], v[158:161], v[190:193], v[54:57]
	v_mfma_f32_16x16x32_bf16 v[46:49], v[150:153], v[214:217], v[46:49]
	v_mfma_f32_16x16x32_bf16 v[38:41], v[158:161], v[214:217], v[38:41]
	v_mfma_f32_16x16x32_bf16 v[30:33], v[150:153], v[222:225], v[30:33]
	v_mfma_f32_16x16x32_bf16 v[22:25], v[158:161], v[222:225], v[22:25]
	v_mfma_f32_16x16x32_bf16 v[14:17], v[150:153], v[230:233], v[14:17]
	v_mfma_f32_16x16x32_bf16 v[6:9], v[158:161], v[230:233], v[6:9]
	v_mfma_f32_16x16x32_bf16 v[58:61], v[162:165], v[178:181], v[58:61]
	v_mfma_f32_16x16x32_bf16 v[50:53], v[170:173], v[178:181], v[50:53]
	v_mfma_f32_16x16x32_bf16 v[42:45], v[162:165], v[194:197], v[42:45]
	v_mfma_f32_16x16x32_bf16 v[34:37], v[170:173], v[194:197], v[34:37]
	v_mfma_f32_16x16x32_bf16 v[26:29], v[162:165], v[218:221], v[26:29]
	v_mfma_f32_16x16x32_bf16 v[18:21], v[170:173], v[218:221], v[18:21]
	v_mfma_f32_16x16x32_bf16 v[10:13], v[162:165], v[226:229], v[10:13]
	v_mfma_f32_16x16x32_bf16 v[2:5], v[170:173], v[226:229], v[2:5]
	v_mfma_f32_16x16x32_bf16 v[58:61], v[166:169], v[190:193], v[58:61]
	v_mfma_f32_16x16x32_bf16 v[50:53], v[174:177], v[190:193], v[50:53]
	v_mfma_f32_16x16x32_bf16 v[42:45], v[166:169], v[214:217], v[42:45]
	v_mfma_f32_16x16x32_bf16 v[34:37], v[174:177], v[214:217], v[34:37]
	v_mfma_f32_16x16x32_bf16 v[26:29], v[166:169], v[222:225], v[26:29]
	v_mfma_f32_16x16x32_bf16 v[18:21], v[174:177], v[222:225], v[18:21]
	v_mfma_f32_16x16x32_bf16 v[10:13], v[166:169], v[230:233], v[10:13]
	v_mfma_f32_16x16x32_bf16 v[2:5], v[174:177], v[230:233], v[2:5]
	s_barrier
	s_add_i32 s68, s68, 2
	s_add_u32 s26, s26, 0x100
	s_addc_u32 s27, s27, 0
	s_add_u32 s58, s58, 0x100
	s_addc_u32 s59, s59, 0
	s_cmp_gt_u32 s68, 13
	s_cbranch_scc0 .LBB11_2567
	s_and_b64 vcc, exec, s[20:21]
	s_cbranch_vccz .LBB11_2570
	s_barrier

.LBB11_2770:
	s_add_u32 s24, s22, 0x100
	s_addc_u32 s25, s23, 0
	s_add_i32 s0, 0, 0x10000
	s_cmp_eq_u32 s59, 40
	s_cselect_b32 s29, s8, s25
	s_cselect_b32 s28, s9, s24
	v_add_u32_e32 v148, s0, v151
	s_cselect_b32 s27, s47, s58
	s_cselect_b32 s26, s56, s57
	s_add_i32 s48, 0, 0x14000
	ds_read_b128 v[140:143], v148
	ds_read_b128 v[144:147], v148 offset:1024
	ds_read_b128 v[154:157], v148 offset:2048
	ds_read_b128 v[158:161], v148 offset:3072
	v_add_u32_e32 v148, s48, v151
	ds_read_b128 v[162:165], v148
	ds_read_b128 v[166:169], v148 offset:1024
	ds_read_b128 v[170:173], v148 offset:2048
	ds_read_b128 v[174:177], v148 offset:3072
	v_lshl_add_u64 v[148:149], s[22:23], 0, v[136:137]
	s_add_i32 m0, s31, 0xc000
	ds_read_b128 v[178:181], v153
	ds_read_b128 v[190:193], v153 offset:1024
	ds_read_b128 v[194:197], v153 offset:2048
	ds_read_b128 v[214:217], v153 offset:3072
	ds_read_b128 v[218:221], v153 offset:4096
	ds_read_b128 v[222:225], v153 offset:5120
	ds_read_b128 v[226:229], v153 offset:6144
	ds_read_b128 v[230:233], v153 offset:7168
	global_load_lds_dwordx4 v[148:149], off
	v_lshl_add_u64 v[148:149], s[22:23], 0, v[138:139]
	s_add_i32 m0, s31, 0xe000
	s_nop 0
	global_load_lds_dwordx4 v[148:149], off
	s_waitcnt vmcnt(8)
	s_waitcnt lgkmcnt(0)
	s_barrier
	v_mfma_f32_16x16x32_bf16 v[126:129], v[140:143], v[178:181], v[126:129]
	v_mfma_f32_16x16x32_bf16 v[122:125], v[154:157], v[178:181], v[122:125]
	v_mfma_f32_16x16x32_bf16 v[110:113], v[140:143], v[194:197], v[110:113]
	v_mfma_f32_16x16x32_bf16 v[106:109], v[154:157], v[194:197], v[106:109]
	v_mfma_f32_16x16x32_bf16 v[94:97], v[140:143], v[218:221], v[94:97]
	v_mfma_f32_16x16x32_bf16 v[90:93], v[154:157], v[218:221], v[90:93]
	v_mfma_f32_16x16x32_bf16 v[78:81], v[140:143], v[226:229], v[78:81]
	v_mfma_f32_16x16x32_bf16 v[74:77], v[154:157], v[226:229], v[74:77]
	v_mfma_f32_16x16x32_bf16 v[126:129], v[144:147], v[190:193], v[126:129]
	v_mfma_f32_16x16x32_bf16 v[122:125], v[158:161], v[190:193], v[122:125]
	v_mfma_f32_16x16x32_bf16 v[110:113], v[144:147], v[214:217], v[110:113]
	v_mfma_f32_16x16x32_bf16 v[106:109], v[158:161], v[214:217], v[106:109]
	v_mfma_f32_16x16x32_bf16 v[94:97], v[144:147], v[222:225], v[94:97]
	v_mfma_f32_16x16x32_bf16 v[90:93], v[158:161], v[222:225], v[90:93]
	v_mfma_f32_16x16x32_bf16 v[78:81], v[144:147], v[230:233], v[78:81]
	v_mfma_f32_16x16x32_bf16 v[74:77], v[158:161], v[230:233], v[74:77]
	v_mfma_f32_16x16x32_bf16 v[118:121], v[162:165], v[178:181], v[118:121]
	v_mfma_f32_16x16x32_bf16 v[114:117], v[170:173], v[178:181], v[114:117]
	v_mfma_f32_16x16x32_bf16 v[102:105], v[162:165], v[194:197], v[102:105]
	v_mfma_f32_16x16x32_bf16 v[98:101], v[170:173], v[194:197], v[98:101]
	v_mfma_f32_16x16x32_bf16 v[86:89], v[162:165], v[218:221], v[86:89]
	v_mfma_f32_16x16x32_bf16 v[82:85], v[170:173], v[218:221], v[82:85]
	v_mfma_f32_16x16x32_bf16 v[70:73], v[162:165], v[226:229], v[70:73]
	v_mfma_f32_16x16x32_bf16 v[66:69], v[170:173], v[226:229], v[66:69]
	v_mfma_f32_16x16x32_bf16 v[118:121], v[166:169], v[190:193], v[118:121]
	v_mfma_f32_16x16x32_bf16 v[114:117], v[174:177], v[190:193], v[114:117]
	v_mfma_f32_16x16x32_bf16 v[102:105], v[166:169], v[214:217], v[102:105]
	v_mfma_f32_16x16x32_bf16 v[98:101], v[174:177], v[214:217], v[98:101]
	v_mfma_f32_16x16x32_bf16 v[86:89], v[166:169], v[222:225], v[86:89]
	v_mfma_f32_16x16x32_bf16 v[82:85], v[174:177], v[222:225], v[82:85]
	v_mfma_f32_16x16x32_bf16 v[70:73], v[166:169], v[230:233], v[70:73]
	v_mfma_f32_16x16x32_bf16 v[66:69], v[174:177], v[230:233], v[66:69]
	s_barrier
	s_add_i32 s0, s0, s30
	v_lshl_add_u64 v[148:149], s[26:27], 0, v[0:1]
	s_mov_b32 m0, s0
	ds_read_b128 v[178:181], v153 offset:16384
	ds_read_b128 v[190:193], v153 offset:17408
	ds_read_b128 v[194:197], v153 offset:18432
	ds_read_b128 v[214:217], v153 offset:19456
	ds_read_b128 v[218:221], v153 offset:20480
	ds_read_b128 v[222:225], v153 offset:21504
	ds_read_b128 v[226:229], v153 offset:22528
	ds_read_b128 v[230:233], v153 offset:23552
	global_load_lds_dwordx4 v[148:149], off
	s_add_i32 m0, s0, 0x2000
	s_add_u32 s0, s26, 0xb0000
	v_lshl_add_u64 v[182:183], s[26:27], 0, v[130:131]
	s_addc_u32 s1, s27, 0
	s_add_i32 s22, s48, s30
	global_load_lds_dwordx4 v[182:183], off
	v_lshl_add_u64 v[234:235], s[0:1], 0, v[0:1]
	s_mov_b32 m0, s22
	v_lshl_add_u64 v[236:237], s[28:29], 0, v[132:133]
	global_load_lds_dwordx4 v[234:235], off
	v_lshl_add_u64 v[234:235], s[0:1], 0, v[130:131]
	s_add_i32 m0, s22, 0x2000
	s_nop 0
	global_load_lds_dwordx4 v[234:235], off
	v_lshl_add_u64 v[234:235], s[28:29], 0, v[134:135]
	s_mov_b32 m0, s31
	s_nop 0
	global_load_lds_dwordx4 v[234:235], off
	s_mov_b32 m0, s34
	s_nop 0
	global_load_lds_dwordx4 v[236:237], off
	s_waitcnt vmcnt(8)
	s_waitcnt lgkmcnt(0)
	s_barrier
	v_mfma_f32_16x16x32_bf16 v[62:65], v[140:143], v[178:181], v[62:65]
	v_mfma_f32_16x16x32_bf16 v[58:61], v[154:157], v[178:181], v[58:61]
	v_mfma_f32_16x16x32_bf16 v[46:49], v[140:143], v[194:197], v[46:49]
	v_mfma_f32_16x16x32_bf16 v[42:45], v[154:157], v[194:197], v[42:45]
	v_mfma_f32_16x16x32_bf16 v[30:33], v[140:143], v[218:221], v[30:33]
	v_mfma_f32_16x16x32_bf16 v[26:29], v[154:157], v[218:221], v[26:29]
	v_mfma_f32_16x16x32_bf16 v[14:17], v[140:143], v[226:229], v[14:17]
	v_mfma_f32_16x16x32_bf16 v[10:13], v[154:157], v[226:229], v[10:13]
	v_mfma_f32_16x16x32_bf16 v[62:65], v[144:147], v[190:193], v[62:65]
	v_mfma_f32_16x16x32_bf16 v[58:61], v[158:161], v[190:193], v[58:61]
	v_mfma_f32_16x16x32_bf16 v[46:49], v[144:147], v[214:217], v[46:49]
	v_mfma_f32_16x16x32_bf16 v[42:45], v[158:161], v[214:217], v[42:45]
	v_mfma_f32_16x16x32_bf16 v[30:33], v[144:147], v[222:225], v[30:33]
	v_mfma_f32_16x16x32_bf16 v[26:29], v[158:161], v[222:225], v[26:29]
	v_mfma_f32_16x16x32_bf16 v[14:17], v[144:147], v[230:233], v[14:17]
	v_mfma_f32_16x16x32_bf16 v[10:13], v[158:161], v[230:233], v[10:13]
	v_mfma_f32_16x16x32_bf16 v[54:57], v[162:165], v[178:181], v[54:57]
	v_mfma_f32_16x16x32_bf16 v[50:53], v[170:173], v[178:181], v[50:53]
	v_mfma_f32_16x16x32_bf16 v[38:41], v[162:165], v[194:197], v[38:41]
	v_mfma_f32_16x16x32_bf16 v[34:37], v[170:173], v[194:197], v[34:37]
	v_mfma_f32_16x16x32_bf16 v[22:25], v[162:165], v[218:221], v[22:25]
	v_mfma_f32_16x16x32_bf16 v[18:21], v[170:173], v[218:221], v[18:21]
	v_mfma_f32_16x16x32_bf16 v[6:9], v[162:165], v[226:229], v[6:9]
	v_mfma_f32_16x16x32_bf16 v[2:5], v[170:173], v[226:229], v[2:5]
	v_mfma_f32_16x16x32_bf16 v[54:57], v[166:169], v[190:193], v[54:57]
	v_mfma_f32_16x16x32_bf16 v[50:53], v[174:177], v[190:193], v[50:53]
	v_mfma_f32_16x16x32_bf16 v[38:41], v[166:169], v[214:217], v[38:41]
	v_mfma_f32_16x16x32_bf16 v[34:37], v[174:177], v[214:217], v[34:37]
	v_mfma_f32_16x16x32_bf16 v[22:25], v[166:169], v[222:225], v[22:25]
	v_mfma_f32_16x16x32_bf16 v[18:21], v[174:177], v[222:225], v[18:21]
	v_mfma_f32_16x16x32_bf16 v[6:9], v[166:169], v[230:233], v[6:9]
	v_mfma_f32_16x16x32_bf16 v[2:5], v[174:177], v[230:233], v[2:5]
	s_barrier
	s_add_i32 s22, 0, 0x18000
	s_add_i32 s23, 0, 0x1c000
	v_add_u32_e32 v158, s22, v151
	v_add_u32_e32 v174, s23, v151
	ds_read_b128 v[140:143], v158
	ds_read_b128 v[144:147], v158 offset:1024
	ds_read_b128 v[154:157], v158 offset:2048
	ds_read_b128 v[158:161], v158 offset:3072
	ds_read_b128 v[162:165], v174
	ds_read_b128 v[166:169], v174 offset:1024
	ds_read_b128 v[170:173], v174 offset:2048
	ds_read_b128 v[174:177], v174 offset:3072
	s_add_u32 s0, s28, 0xb0000
	s_addc_u32 s1, s29, 0
	s_mov_b32 m0, s35
	v_lshl_add_u64 v[238:239], s[0:1], 0, v[134:135]
	ds_read_b128 v[178:181], v153 offset:32768
	ds_read_b128 v[190:193], v153 offset:33792
	ds_read_b128 v[194:197], v153 offset:34816
	ds_read_b128 v[214:217], v153 offset:35840
	ds_read_b128 v[218:221], v153 offset:36864
	ds_read_b128 v[222:225], v153 offset:37888
	ds_read_b128 v[226:229], v153 offset:38912
	ds_read_b128 v[230:233], v153 offset:39936
	global_load_lds_dwordx4 v[238:239], off
	v_lshl_add_u64 v[238:239], s[0:1], 0, v[132:133]
	s_mov_b32 m0, s40
	s_nop 0
	global_load_lds_dwordx4 v[238:239], off
	s_waitcnt vmcnt(8)
	s_waitcnt lgkmcnt(0)
	s_barrier
	v_mfma_f32_16x16x32_bf16 v[126:129], v[140:143], v[178:181], v[126:129]
	v_mfma_f32_16x16x32_bf16 v[122:125], v[154:157], v[178:181], v[122:125]
	v_mfma_f32_16x16x32_bf16 v[110:113], v[140:143], v[194:197], v[110:113]
	v_mfma_f32_16x16x32_bf16 v[106:109], v[154:157], v[194:197], v[106:109]
	v_mfma_f32_16x16x32_bf16 v[94:97], v[140:143], v[218:221], v[94:97]
	v_mfma_f32_16x16x32_bf16 v[90:93], v[154:157], v[218:221], v[90:93]
	v_mfma_f32_16x16x32_bf16 v[78:81], v[140:143], v[226:229], v[78:81]
	v_mfma_f32_16x16x32_bf16 v[74:77], v[154:157], v[226:229], v[74:77]
	v_mfma_f32_16x16x32_bf16 v[126:129], v[144:147], v[190:193], v[126:129]
	v_mfma_f32_16x16x32_bf16 v[122:125], v[158:161], v[190:193], v[122:125]
	v_mfma_f32_16x16x32_bf16 v[110:113], v[144:147], v[214:217], v[110:113]
	v_mfma_f32_16x16x32_bf16 v[106:109], v[158:161], v[214:217], v[106:109]
	v_mfma_f32_16x16x32_bf16 v[94:97], v[144:147], v[222:225], v[94:97]
	v_mfma_f32_16x16x32_bf16 v[90:93], v[158:161], v[222:225], v[90:93]
	v_mfma_f32_16x16x32_bf16 v[78:81], v[144:147], v[230:233], v[78:81]
	v_mfma_f32_16x16x32_bf16 v[74:77], v[158:161], v[230:233], v[74:77]
	v_mfma_f32_16x16x32_bf16 v[118:121], v[162:165], v[178:181], v[118:121]
	v_mfma_f32_16x16x32_bf16 v[114:117], v[170:173], v[178:181], v[114:117]
	v_mfma_f32_16x16x32_bf16 v[102:105], v[162:165], v[194:197], v[102:105]
	v_mfma_f32_16x16x32_bf16 v[98:101], v[170:173], v[194:197], v[98:101]
	v_mfma_f32_16x16x32_bf16 v[86:89], v[162:165], v[218:221], v[86:89]
	v_mfma_f32_16x16x32_bf16 v[82:85], v[170:173], v[218:221], v[82:85]
	v_mfma_f32_16x16x32_bf16 v[70:73], v[162:165], v[226:229], v[70:73]
	v_mfma_f32_16x16x32_bf16 v[66:69], v[170:173], v[226:229], v[66:69]
	v_mfma_f32_16x16x32_bf16 v[118:121], v[166:169], v[190:193], v[118:121]
	v_mfma_f32_16x16x32_bf16 v[114:117], v[174:177], v[190:193], v[114:117]
	v_mfma_f32_16x16x32_bf16 v[102:105], v[166:169], v[214:217], v[102:105]
	v_mfma_f32_16x16x32_bf16 v[98:101], v[174:177], v[214:217], v[98:101]
	v_mfma_f32_16x16x32_bf16 v[86:89], v[166:169], v[222:225], v[86:89]
	v_mfma_f32_16x16x32_bf16 v[82:85], v[174:177], v[222:225], v[82:85]
	v_mfma_f32_16x16x32_bf16 v[70:73], v[166:169], v[230:233], v[70:73]
	v_mfma_f32_16x16x32_bf16 v[66:69], v[174:177], v[230:233], v[66:69]
	s_barrier
	s_add_i32 s0, s22, s30
	v_lshl_add_u64 v[148:149], v[148:149], 0, s[96:97]
	s_mov_b32 m0, s0
	ds_read_b128 v[178:181], v153 offset:49152
	ds_read_b128 v[190:193], v153 offset:50176
	ds_read_b128 v[194:197], v153 offset:51200
	ds_read_b128 v[214:217], v153 offset:52224
	ds_read_b128 v[218:221], v153 offset:53248
	ds_read_b128 v[222:225], v153 offset:54272
	ds_read_b128 v[226:229], v153 offset:55296
	ds_read_b128 v[230:233], v153 offset:56320
	global_load_lds_dwordx4 v[148:149], off
	s_add_i32 m0, s0, 0x2000
	s_add_u32 s0, s26, 0xb0080
	v_lshl_add_u64 v[148:149], v[182:183], 0, s[96:97]
	s_addc_u32 s1, s27, 0
	s_add_i32 s22, s23, s30
	global_load_lds_dwordx4 v[148:149], off
	v_lshl_add_u64 v[148:149], s[0:1], 0, v[0:1]
	s_mov_b32 m0, s22
	s_nop 0
	global_load_lds_dwordx4 v[148:149], off
	v_lshl_add_u64 v[148:149], s[0:1], 0, v[130:131]
	s_add_i32 m0, s22, 0x2000
	s_nop 0
	global_load_lds_dwordx4 v[148:149], off
	v_lshl_add_u64 v[148:149], v[234:235], 0, s[96:97]
	s_mov_b32 m0, s41
	s_nop 0
	global_load_lds_dwordx4 v[148:149], off
	v_lshl_add_u64 v[148:149], v[236:237], 0, s[96:97]
	s_mov_b32 m0, s42
	s_nop 0
	global_load_lds_dwordx4 v[148:149], off
	s_waitcnt vmcnt(8)
	s_waitcnt lgkmcnt(0)
	s_barrier
	v_mfma_f32_16x16x32_bf16 v[62:65], v[140:143], v[178:181], v[62:65]
	v_mfma_f32_16x16x32_bf16 v[58:61], v[154:157], v[178:181], v[58:61]
	v_mfma_f32_16x16x32_bf16 v[46:49], v[140:143], v[194:197], v[46:49]
	v_mfma_f32_16x16x32_bf16 v[42:45], v[154:157], v[194:197], v[42:45]
	v_mfma_f32_16x16x32_bf16 v[30:33], v[140:143], v[218:221], v[30:33]
	v_mfma_f32_16x16x32_bf16 v[26:29], v[154:157], v[218:221], v[26:29]
	v_mfma_f32_16x16x32_bf16 v[14:17], v[140:143], v[226:229], v[14:17]
	v_mfma_f32_16x16x32_bf16 v[10:13], v[154:157], v[226:229], v[10:13]
	v_mfma_f32_16x16x32_bf16 v[62:65], v[144:147], v[190:193], v[62:65]
	v_mfma_f32_16x16x32_bf16 v[58:61], v[158:161], v[190:193], v[58:61]
	v_mfma_f32_16x16x32_bf16 v[46:49], v[144:147], v[214:217], v[46:49]
	v_mfma_f32_16x16x32_bf16 v[42:45], v[158:161], v[214:217], v[42:45]
	v_mfma_f32_16x16x32_bf16 v[30:33], v[144:147], v[222:225], v[30:33]
	v_mfma_f32_16x16x32_bf16 v[26:29], v[158:161], v[222:225], v[26:29]
	v_mfma_f32_16x16x32_bf16 v[14:17], v[144:147], v[230:233], v[14:17]
	v_mfma_f32_16x16x32_bf16 v[10:13], v[158:161], v[230:233], v[10:13]
	v_mfma_f32_16x16x32_bf16 v[54:57], v[162:165], v[178:181], v[54:57]
	v_mfma_f32_16x16x32_bf16 v[50:53], v[170:173], v[178:181], v[50:53]
	v_mfma_f32_16x16x32_bf16 v[38:41], v[162:165], v[194:197], v[38:41]
	v_mfma_f32_16x16x32_bf16 v[34:37], v[170:173], v[194:197], v[34:37]
	v_mfma_f32_16x16x32_bf16 v[22:25], v[162:165], v[218:221], v[22:25]
	v_mfma_f32_16x16x32_bf16 v[18:21], v[170:173], v[218:221], v[18:21]
	v_mfma_f32_16x16x32_bf16 v[6:9], v[162:165], v[226:229], v[6:9]
	v_mfma_f32_16x16x32_bf16 v[2:5], v[170:173], v[226:229], v[2:5]
	v_mfma_f32_16x16x32_bf16 v[54:57], v[166:169], v[190:193], v[54:57]
	v_mfma_f32_16x16x32_bf16 v[50:53], v[174:177], v[190:193], v[50:53]
	v_mfma_f32_16x16x32_bf16 v[38:41], v[166:169], v[214:217], v[38:41]
	v_mfma_f32_16x16x32_bf16 v[34:37], v[174:177], v[214:217], v[34:37]
	v_mfma_f32_16x16x32_bf16 v[22:25], v[166:169], v[222:225], v[22:25]
	v_mfma_f32_16x16x32_bf16 v[18:21], v[174:177], v[222:225], v[18:21]
	v_mfma_f32_16x16x32_bf16 v[6:9], v[166:169], v[230:233], v[6:9]
	v_mfma_f32_16x16x32_bf16 v[2:5], v[174:177], v[230:233], v[2:5]
	s_barrier
	s_add_i32 s59, s59, 2
	s_add_u32 s57, s57, 0x100
	s_addc_u32 s58, s58, 0
	s_cmp_gt_u32 s59, 41
	s_mov_b64 s[22:23], s[24:25]
	s_cbranch_scc0 .LBB11_2770
	s_and_b64 vcc, exec, s[14:15]
	s_cbranch_vccz .LBB11_2773
	s_barrier
